# v28 + fewer instructions beside the MFMA streams: GEMM MMA segments without s_setprio toggles and the repeated lgkmcnt(0), LDS-DMA addresses from the scalar base (8 fewer 64-bit VALU adds per loop bod
# speedup vs baseline: 1.0170x; 1.0170x over previous
.LBB0_121:
	ds_read_b128 v[154:157], v150
	ds_read_b128 v[158:161], v150 offset:1024
	ds_read_b128 v[162:165], v150 offset:2048
	ds_read_b128 v[166:169], v150 offset:3072
	ds_read_b128 v[170:173], v151
	ds_read_b128 v[174:177], v151 offset:1024
	ds_read_b128 v[178:181], v151 offset:2048
	ds_read_b128 v[182:185], v151 offset:3072
	s_add_u32 s52, s40, 0xfffc0080
	s_addc_u32 s53, s41, -1
	s_cmp_eq_u32 s57, 12
	s_cselect_b32 s55, s0, s53
	s_cselect_b32 s54, s1, s52
	s_cselect_b32 s53, s11, s56
	s_cselect_b32 s52, s13, s51
	s_add_i32 m0, s19, 0xc000
	ds_read_b128 v[186:189], v152
	ds_read_b128 v[190:193], v152 offset:1024
	ds_read_b128 v[194:197], v152 offset:2048
	ds_read_b128 v[198:201], v152 offset:3072
	ds_read_b128 v[202:205], v152 offset:4096
	ds_read_b128 v[206:209], v152 offset:5120
	ds_read_b128 v[210:213], v152 offset:6144
	ds_read_b128 v[214:217], v152 offset:7168
	global_load_lds_dwordx4 v136, s[40:41]
	s_add_i32 m0, s19, 0xe000
	s_nop 0
	global_load_lds_dwordx4 v138, s[40:41]
	s_waitcnt vmcnt(8)
	s_waitcnt lgkmcnt(0)
	s_barrier
	v_mfma_f32_16x16x32_bf16 v[124:127], v[154:157], v[186:189], v[124:127]
	v_mfma_f32_16x16x32_bf16 v[120:123], v[162:165], v[186:189], v[120:123]
	v_mfma_f32_16x16x32_bf16 v[108:111], v[154:157], v[194:197], v[108:111]
	v_mfma_f32_16x16x32_bf16 v[104:107], v[162:165], v[194:197], v[104:107]
	v_mfma_f32_16x16x32_bf16 v[92:95], v[154:157], v[202:205], v[92:95]
	v_mfma_f32_16x16x32_bf16 v[88:91], v[162:165], v[202:205], v[88:91]
	v_mfma_f32_16x16x32_bf16 v[76:79], v[154:157], v[210:213], v[76:79]
	v_mfma_f32_16x16x32_bf16 v[72:75], v[162:165], v[210:213], v[72:75]
	v_mfma_f32_16x16x32_bf16 v[124:127], v[158:161], v[190:193], v[124:127]
	v_mfma_f32_16x16x32_bf16 v[120:123], v[166:169], v[190:193], v[120:123]
	v_mfma_f32_16x16x32_bf16 v[108:111], v[158:161], v[198:201], v[108:111]
	v_mfma_f32_16x16x32_bf16 v[104:107], v[166:169], v[198:201], v[104:107]
	v_mfma_f32_16x16x32_bf16 v[92:95], v[158:161], v[206:209], v[92:95]
	v_mfma_f32_16x16x32_bf16 v[88:91], v[166:169], v[206:209], v[88:91]
	v_mfma_f32_16x16x32_bf16 v[76:79], v[158:161], v[214:217], v[76:79]
	v_mfma_f32_16x16x32_bf16 v[72:75], v[166:169], v[214:217], v[72:75]
	v_mfma_f32_16x16x32_bf16 v[116:119], v[170:173], v[186:189], v[116:119]
	v_mfma_f32_16x16x32_bf16 v[112:115], v[178:181], v[186:189], v[112:115]
	v_mfma_f32_16x16x32_bf16 v[100:103], v[170:173], v[194:197], v[100:103]
	v_mfma_f32_16x16x32_bf16 v[96:99], v[178:181], v[194:197], v[96:99]
	v_mfma_f32_16x16x32_bf16 v[84:87], v[170:173], v[202:205], v[84:87]
	v_mfma_f32_16x16x32_bf16 v[80:83], v[178:181], v[202:205], v[80:83]
	v_mfma_f32_16x16x32_bf16 v[68:71], v[170:173], v[210:213], v[68:71]
	v_mfma_f32_16x16x32_bf16 v[64:67], v[178:181], v[210:213], v[64:67]
	v_mfma_f32_16x16x32_bf16 v[116:119], v[174:177], v[190:193], v[116:119]
	v_mfma_f32_16x16x32_bf16 v[112:115], v[182:185], v[190:193], v[112:115]
	v_mfma_f32_16x16x32_bf16 v[100:103], v[174:177], v[198:201], v[100:103]
	v_mfma_f32_16x16x32_bf16 v[96:99], v[182:185], v[198:201], v[96:99]
	v_mfma_f32_16x16x32_bf16 v[84:87], v[174:177], v[206:209], v[84:87]
	v_mfma_f32_16x16x32_bf16 v[80:83], v[182:185], v[206:209], v[80:83]
	v_mfma_f32_16x16x32_bf16 v[68:71], v[174:177], v[214:217], v[68:71]
	v_mfma_f32_16x16x32_bf16 v[64:67], v[182:185], v[214:217], v[64:67]
	s_barrier
	s_add_i32 s58, s47, s21
	v_lshl_add_u64 v[144:145], s[52:53], 0, v[128:129]
	s_mov_b32 m0, s58
	ds_read_b128 v[186:189], v152 offset:16384
	ds_read_b128 v[190:193], v152 offset:17408
	ds_read_b128 v[194:197], v152 offset:18432
	ds_read_b128 v[198:201], v152 offset:19456
	ds_read_b128 v[202:205], v152 offset:20480
	ds_read_b128 v[206:209], v152 offset:21504
	ds_read_b128 v[210:213], v152 offset:22528
	ds_read_b128 v[214:217], v152 offset:23552
	global_load_lds_dwordx4 v[144:145], off
	s_add_i32 m0, s58, 0x2000
	s_add_u32 s58, s52, 0x40000
	v_lshl_add_u64 v[218:219], s[52:53], 0, v[130:131]
	s_addc_u32 s59, s53, 0
	s_add_i32 s60, s48, s21
	global_load_lds_dwordx4 v[218:219], off
	s_mov_b32 m0, s60
	v_lshl_add_u64 v[222:223], s[54:55], 0, v[132:133]
	global_load_lds_dwordx4 v128, s[58:59]
	s_add_i32 m0, s60, 0x2000
	s_nop 0
	global_load_lds_dwordx4 v130, s[58:59]
	v_lshl_add_u64 v[220:221], s[54:55], 0, v[134:135]
	s_mov_b32 m0, s19
	s_nop 0
	global_load_lds_dwordx4 v[220:221], off
	s_mov_b32 m0, s35
	s_nop 0
	global_load_lds_dwordx4 v[222:223], off
	s_waitcnt vmcnt(8)
	s_waitcnt lgkmcnt(0)
	s_barrier
	v_mfma_f32_16x16x32_bf16 v[60:63], v[154:157], v[186:189], v[60:63]
	v_mfma_f32_16x16x32_bf16 v[56:59], v[162:165], v[186:189], v[56:59]
	v_mfma_f32_16x16x32_bf16 v[44:47], v[154:157], v[194:197], v[44:47]
	v_mfma_f32_16x16x32_bf16 v[40:43], v[162:165], v[194:197], v[40:43]
	v_mfma_f32_16x16x32_bf16 v[28:31], v[154:157], v[202:205], v[28:31]
	v_mfma_f32_16x16x32_bf16 v[24:27], v[162:165], v[202:205], v[24:27]
	v_mfma_f32_16x16x32_bf16 v[12:15], v[154:157], v[210:213], v[12:15]
	v_mfma_f32_16x16x32_bf16 v[8:11], v[162:165], v[210:213], v[8:11]
	v_mfma_f32_16x16x32_bf16 v[60:63], v[158:161], v[190:193], v[60:63]
	v_mfma_f32_16x16x32_bf16 v[56:59], v[166:169], v[190:193], v[56:59]
	v_mfma_f32_16x16x32_bf16 v[44:47], v[158:161], v[198:201], v[44:47]
	v_mfma_f32_16x16x32_bf16 v[40:43], v[166:169], v[198:201], v[40:43]
	v_mfma_f32_16x16x32_bf16 v[28:31], v[158:161], v[206:209], v[28:31]
	v_mfma_f32_16x16x32_bf16 v[24:27], v[166:169], v[206:209], v[24:27]
	v_mfma_f32_16x16x32_bf16 v[12:15], v[158:161], v[214:217], v[12:15]
	v_mfma_f32_16x16x32_bf16 v[8:11], v[166:169], v[214:217], v[8:11]
	v_mfma_f32_16x16x32_bf16 v[52:55], v[170:173], v[186:189], v[52:55]
	v_mfma_f32_16x16x32_bf16 v[48:51], v[178:181], v[186:189], v[48:51]
	v_mfma_f32_16x16x32_bf16 v[36:39], v[170:173], v[194:197], v[36:39]
	v_mfma_f32_16x16x32_bf16 v[32:35], v[178:181], v[194:197], v[32:35]
	v_mfma_f32_16x16x32_bf16 v[20:23], v[170:173], v[202:205], v[20:23]
	v_mfma_f32_16x16x32_bf16 v[16:19], v[178:181], v[202:205], v[16:19]
	v_mfma_f32_16x16x32_bf16 v[4:7], v[170:173], v[210:213], v[4:7]
	v_mfma_f32_16x16x32_bf16 v[0:3], v[178:181], v[210:213], v[0:3]
	v_mfma_f32_16x16x32_bf16 v[52:55], v[174:177], v[190:193], v[52:55]
	v_mfma_f32_16x16x32_bf16 v[48:51], v[182:185], v[190:193], v[48:51]
	v_mfma_f32_16x16x32_bf16 v[36:39], v[174:177], v[198:201], v[36:39]
	v_mfma_f32_16x16x32_bf16 v[32:35], v[182:185], v[198:201], v[32:35]
	v_mfma_f32_16x16x32_bf16 v[20:23], v[174:177], v[206:209], v[20:23]
	v_mfma_f32_16x16x32_bf16 v[16:19], v[182:185], v[206:209], v[16:19]
	v_mfma_f32_16x16x32_bf16 v[4:7], v[174:177], v[214:217], v[4:7]
	v_mfma_f32_16x16x32_bf16 v[0:3], v[182:185], v[214:217], v[0:3]
	s_barrier
	s_add_i32 s58, 0, 0x18000
	v_add_u32_e32 v153, s58, v148
	s_add_i32 s59, 0, 0x1c000
	ds_read_b128 v[154:157], v153
	ds_read_b128 v[158:161], v153 offset:1024
	ds_read_b128 v[162:165], v153 offset:2048
	ds_read_b128 v[166:169], v153 offset:3072
	v_add_u32_e32 v153, s59, v148
	ds_read_b128 v[170:173], v153
	ds_read_b128 v[174:177], v153 offset:1024
	ds_read_b128 v[178:181], v153 offset:2048
	ds_read_b128 v[182:185], v153 offset:3072
	s_add_u32 s54, s54, 0x40000
	s_addc_u32 s55, s55, 0
	s_mov_b32 m0, s38
	ds_read_b128 v[186:189], v152 offset:32768
	ds_read_b128 v[190:193], v152 offset:33792
	ds_read_b128 v[194:197], v152 offset:34816
	ds_read_b128 v[198:201], v152 offset:35840
	ds_read_b128 v[202:205], v152 offset:36864
	ds_read_b128 v[206:209], v152 offset:37888
	ds_read_b128 v[210:213], v152 offset:38912
	ds_read_b128 v[214:217], v152 offset:39936
	global_load_lds_dwordx4 v134, s[54:55]
	s_mov_b32 m0, s39
	s_nop 0
	global_load_lds_dwordx4 v132, s[54:55]
	s_waitcnt vmcnt(8)
	s_waitcnt lgkmcnt(0)
	s_barrier
	v_mfma_f32_16x16x32_bf16 v[124:127], v[154:157], v[186:189], v[124:127]
	v_mfma_f32_16x16x32_bf16 v[120:123], v[162:165], v[186:189], v[120:123]
	v_mfma_f32_16x16x32_bf16 v[108:111], v[154:157], v[194:197], v[108:111]
	v_mfma_f32_16x16x32_bf16 v[104:107], v[162:165], v[194:197], v[104:107]
	v_mfma_f32_16x16x32_bf16 v[92:95], v[154:157], v[202:205], v[92:95]
	v_mfma_f32_16x16x32_bf16 v[88:91], v[162:165], v[202:205], v[88:91]
	v_mfma_f32_16x16x32_bf16 v[76:79], v[154:157], v[210:213], v[76:79]
	v_mfma_f32_16x16x32_bf16 v[72:75], v[162:165], v[210:213], v[72:75]
	v_mfma_f32_16x16x32_bf16 v[124:127], v[158:161], v[190:193], v[124:127]
	v_mfma_f32_16x16x32_bf16 v[120:123], v[166:169], v[190:193], v[120:123]
	v_mfma_f32_16x16x32_bf16 v[108:111], v[158:161], v[198:201], v[108:111]
	v_mfma_f32_16x16x32_bf16 v[104:107], v[166:169], v[198:201], v[104:107]
	v_mfma_f32_16x16x32_bf16 v[92:95], v[158:161], v[206:209], v[92:95]
	v_mfma_f32_16x16x32_bf16 v[88:91], v[166:169], v[206:209], v[88:91]
	v_mfma_f32_16x16x32_bf16 v[76:79], v[158:161], v[214:217], v[76:79]
	v_mfma_f32_16x16x32_bf16 v[72:75], v[166:169], v[214:217], v[72:75]
	v_mfma_f32_16x16x32_bf16 v[116:119], v[170:173], v[186:189], v[116:119]
	v_mfma_f32_16x16x32_bf16 v[112:115], v[178:181], v[186:189], v[112:115]
	v_mfma_f32_16x16x32_bf16 v[100:103], v[170:173], v[194:197], v[100:103]
	v_mfma_f32_16x16x32_bf16 v[96:99], v[178:181], v[194:197], v[96:99]
	v_mfma_f32_16x16x32_bf16 v[84:87], v[170:173], v[202:205], v[84:87]
	v_mfma_f32_16x16x32_bf16 v[80:83], v[178:181], v[202:205], v[80:83]
	v_mfma_f32_16x16x32_bf16 v[68:71], v[170:173], v[210:213], v[68:71]
	v_mfma_f32_16x16x32_bf16 v[64:67], v[178:181], v[210:213], v[64:67]
	v_mfma_f32_16x16x32_bf16 v[116:119], v[174:177], v[190:193], v[116:119]
	v_mfma_f32_16x16x32_bf16 v[112:115], v[182:185], v[190:193], v[112:115]
	v_mfma_f32_16x16x32_bf16 v[100:103], v[174:177], v[198:201], v[100:103]
	v_mfma_f32_16x16x32_bf16 v[96:99], v[182:185], v[198:201], v[96:99]
	v_mfma_f32_16x16x32_bf16 v[84:87], v[174:177], v[206:209], v[84:87]
	v_mfma_f32_16x16x32_bf16 v[80:83], v[182:185], v[206:209], v[80:83]
	v_mfma_f32_16x16x32_bf16 v[68:71], v[174:177], v[214:217], v[68:71]
	v_mfma_f32_16x16x32_bf16 v[64:67], v[182:185], v[214:217], v[64:67]
	s_barrier
	s_add_i32 s54, s58, s21
	v_lshl_add_u64 v[144:145], v[144:145], 0, s[6:7]
	s_mov_b32 m0, s54
	ds_read_b128 v[186:189], v152 offset:49152
	ds_read_b128 v[190:193], v152 offset:50176
	ds_read_b128 v[194:197], v152 offset:51200
	ds_read_b128 v[198:201], v152 offset:52224
	ds_read_b128 v[202:205], v152 offset:53248
	ds_read_b128 v[206:209], v152 offset:54272
	ds_read_b128 v[210:213], v152 offset:55296
	ds_read_b128 v[214:217], v152 offset:56320
	global_load_lds_dwordx4 v[144:145], off
	s_add_i32 m0, s54, 0x2000
	s_add_u32 s52, s52, 0x40080
	v_lshl_add_u64 v[144:145], v[218:219], 0, s[6:7]
	s_addc_u32 s53, s53, 0
	s_add_i32 s54, s59, s21
	global_load_lds_dwordx4 v[144:145], off
	s_mov_b32 m0, s54
	s_nop 0
	global_load_lds_dwordx4 v128, s[52:53]
	s_add_i32 m0, s54, 0x2000
	s_nop 0
	global_load_lds_dwordx4 v130, s[52:53]
	v_lshl_add_u64 v[144:145], v[220:221], 0, s[6:7]
	s_mov_b32 m0, s43
	s_nop 0
	global_load_lds_dwordx4 v[144:145], off
	v_lshl_add_u64 v[144:145], v[222:223], 0, s[6:7]
	s_mov_b32 m0, s44
	s_nop 0
	global_load_lds_dwordx4 v[144:145], off
	s_waitcnt vmcnt(8)
	s_waitcnt lgkmcnt(0)
	s_barrier
	v_mfma_f32_16x16x32_bf16 v[60:63], v[154:157], v[186:189], v[60:63]
	v_mfma_f32_16x16x32_bf16 v[56:59], v[162:165], v[186:189], v[56:59]
	v_mfma_f32_16x16x32_bf16 v[44:47], v[154:157], v[194:197], v[44:47]
	v_mfma_f32_16x16x32_bf16 v[40:43], v[162:165], v[194:197], v[40:43]
	v_mfma_f32_16x16x32_bf16 v[28:31], v[154:157], v[202:205], v[28:31]
	v_mfma_f32_16x16x32_bf16 v[24:27], v[162:165], v[202:205], v[24:27]
	v_mfma_f32_16x16x32_bf16 v[12:15], v[154:157], v[210:213], v[12:15]
	v_mfma_f32_16x16x32_bf16 v[8:11], v[162:165], v[210:213], v[8:11]
	v_mfma_f32_16x16x32_bf16 v[60:63], v[158:161], v[190:193], v[60:63]
	v_mfma_f32_16x16x32_bf16 v[56:59], v[166:169], v[190:193], v[56:59]
	v_mfma_f32_16x16x32_bf16 v[44:47], v[158:161], v[198:201], v[44:47]
	v_mfma_f32_16x16x32_bf16 v[40:43], v[166:169], v[198:201], v[40:43]
	v_mfma_f32_16x16x32_bf16 v[28:31], v[158:161], v[206:209], v[28:31]
	v_mfma_f32_16x16x32_bf16 v[24:27], v[166:169], v[206:209], v[24:27]
	v_mfma_f32_16x16x32_bf16 v[12:15], v[158:161], v[214:217], v[12:15]
	v_mfma_f32_16x16x32_bf16 v[8:11], v[166:169], v[214:217], v[8:11]
	v_mfma_f32_16x16x32_bf16 v[52:55], v[170:173], v[186:189], v[52:55]
	v_mfma_f32_16x16x32_bf16 v[48:51], v[178:181], v[186:189], v[48:51]
	v_mfma_f32_16x16x32_bf16 v[36:39], v[170:173], v[194:197], v[36:39]
	v_mfma_f32_16x16x32_bf16 v[32:35], v[178:181], v[194:197], v[32:35]
	v_mfma_f32_16x16x32_bf16 v[20:23], v[170:173], v[202:205], v[20:23]
	v_mfma_f32_16x16x32_bf16 v[16:19], v[178:181], v[202:205], v[16:19]
	v_mfma_f32_16x16x32_bf16 v[4:7], v[170:173], v[210:213], v[4:7]
	v_mfma_f32_16x16x32_bf16 v[0:3], v[178:181], v[210:213], v[0:3]
	v_mfma_f32_16x16x32_bf16 v[52:55], v[174:177], v[190:193], v[52:55]
	v_mfma_f32_16x16x32_bf16 v[48:51], v[182:185], v[190:193], v[48:51]
	v_mfma_f32_16x16x32_bf16 v[36:39], v[174:177], v[198:201], v[36:39]
	v_mfma_f32_16x16x32_bf16 v[32:35], v[182:185], v[198:201], v[32:35]
	v_mfma_f32_16x16x32_bf16 v[20:23], v[174:177], v[206:209], v[20:23]
	v_mfma_f32_16x16x32_bf16 v[16:19], v[182:185], v[206:209], v[16:19]
	v_mfma_f32_16x16x32_bf16 v[4:7], v[174:177], v[214:217], v[4:7]
	v_mfma_f32_16x16x32_bf16 v[0:3], v[182:185], v[214:217], v[0:3]
	s_barrier
	s_add_i32 s57, s57, 2
	s_add_u32 s40, s40, 0x100
	s_addc_u32 s41, s41, 0
	s_add_u32 s51, s51, 0x100
	s_addc_u32 s56, s56, 0
	s_cmp_gt_u32 s57, 13
	s_cbranch_scc0 .LBB0_121
	s_and_b64 vcc, exec, s[8:9]
	s_cbranch_vccz .LBB0_124
	s_barrier

.LBB0_201:
	ds_read_b128 v[154:157], v150
	ds_read_b128 v[158:161], v150 offset:1024
	ds_read_b128 v[162:165], v150 offset:2048
	ds_read_b128 v[166:169], v150 offset:3072
	ds_read_b128 v[170:173], v151
	ds_read_b128 v[174:177], v151 offset:1024
	ds_read_b128 v[178:181], v151 offset:2048
	ds_read_b128 v[182:185], v151 offset:3072
	s_add_u32 s16, s14, 0x100
	s_addc_u32 s17, s15, 0
	s_cmp_eq_u32 s55, 40
	s_cselect_b32 s53, s5, s17
	s_cselect_b32 s52, s4, s16
	s_cselect_b32 s19, s13, s1
	s_cselect_b32 s18, s12, s0
	s_add_i32 m0, s34, 0xc000
	ds_read_b128 v[186:189], v152
	ds_read_b128 v[190:193], v152 offset:1024
	ds_read_b128 v[194:197], v152 offset:2048
	ds_read_b128 v[198:201], v152 offset:3072
	ds_read_b128 v[202:205], v152 offset:4096
	ds_read_b128 v[206:209], v152 offset:5120
	ds_read_b128 v[210:213], v152 offset:6144
	ds_read_b128 v[214:217], v152 offset:7168
	global_load_lds_dwordx4 v136, s[14:15]
	s_add_i32 m0, s34, 0xe000
	s_nop 0
	global_load_lds_dwordx4 v138, s[14:15]
	s_waitcnt vmcnt(8)
	s_waitcnt lgkmcnt(0)
	s_barrier
	v_mfma_f32_16x16x32_bf16 v[124:127], v[154:157], v[186:189], v[124:127]
	v_mfma_f32_16x16x32_bf16 v[120:123], v[162:165], v[186:189], v[120:123]
	v_mfma_f32_16x16x32_bf16 v[112:115], v[154:157], v[194:197], v[112:115]
	v_mfma_f32_16x16x32_bf16 v[104:107], v[162:165], v[194:197], v[104:107]
	v_mfma_f32_16x16x32_bf16 v[96:99], v[154:157], v[202:205], v[96:99]
	v_mfma_f32_16x16x32_bf16 v[88:91], v[162:165], v[202:205], v[88:91]
	v_mfma_f32_16x16x32_bf16 v[80:83], v[154:157], v[210:213], v[80:83]
	v_mfma_f32_16x16x32_bf16 v[72:75], v[162:165], v[210:213], v[72:75]
	v_mfma_f32_16x16x32_bf16 v[124:127], v[158:161], v[190:193], v[124:127]
	v_mfma_f32_16x16x32_bf16 v[120:123], v[166:169], v[190:193], v[120:123]
	v_mfma_f32_16x16x32_bf16 v[112:115], v[158:161], v[198:201], v[112:115]
	v_mfma_f32_16x16x32_bf16 v[104:107], v[166:169], v[198:201], v[104:107]
	v_mfma_f32_16x16x32_bf16 v[96:99], v[158:161], v[206:209], v[96:99]
	v_mfma_f32_16x16x32_bf16 v[88:91], v[166:169], v[206:209], v[88:91]
	v_mfma_f32_16x16x32_bf16 v[80:83], v[158:161], v[214:217], v[80:83]
	v_mfma_f32_16x16x32_bf16 v[72:75], v[166:169], v[214:217], v[72:75]
	v_mfma_f32_16x16x32_bf16 v[116:119], v[170:173], v[186:189], v[116:119]
	v_mfma_f32_16x16x32_bf16 v[108:111], v[178:181], v[186:189], v[108:111]
	v_mfma_f32_16x16x32_bf16 v[100:103], v[170:173], v[194:197], v[100:103]
	v_mfma_f32_16x16x32_bf16 v[92:95], v[178:181], v[194:197], v[92:95]
	v_mfma_f32_16x16x32_bf16 v[84:87], v[170:173], v[202:205], v[84:87]
	v_mfma_f32_16x16x32_bf16 v[76:79], v[178:181], v[202:205], v[76:79]
	v_mfma_f32_16x16x32_bf16 v[68:71], v[170:173], v[210:213], v[68:71]
	v_mfma_f32_16x16x32_bf16 v[64:67], v[178:181], v[210:213], v[64:67]
	v_mfma_f32_16x16x32_bf16 v[116:119], v[174:177], v[190:193], v[116:119]
	v_mfma_f32_16x16x32_bf16 v[108:111], v[182:185], v[190:193], v[108:111]
	v_mfma_f32_16x16x32_bf16 v[100:103], v[174:177], v[198:201], v[100:103]
	v_mfma_f32_16x16x32_bf16 v[92:95], v[182:185], v[198:201], v[92:95]
	v_mfma_f32_16x16x32_bf16 v[84:87], v[174:177], v[206:209], v[84:87]
	v_mfma_f32_16x16x32_bf16 v[76:79], v[182:185], v[206:209], v[76:79]
	v_mfma_f32_16x16x32_bf16 v[68:71], v[174:177], v[214:217], v[68:71]
	v_mfma_f32_16x16x32_bf16 v[64:67], v[182:185], v[214:217], v[64:67]
	s_barrier
	s_add_i32 s14, s47, s23
	v_lshl_add_u64 v[144:145], s[18:19], 0, v[130:131]
	s_mov_b32 m0, s14
	ds_read_b128 v[186:189], v152 offset:16384
	ds_read_b128 v[190:193], v152 offset:17408
	ds_read_b128 v[194:197], v152 offset:18432
	ds_read_b128 v[198:201], v152 offset:19456
	ds_read_b128 v[202:205], v152 offset:20480
	ds_read_b128 v[206:209], v152 offset:21504
	ds_read_b128 v[210:213], v152 offset:22528
	ds_read_b128 v[214:217], v152 offset:23552
	global_load_lds_dwordx4 v[144:145], off
	s_add_i32 m0, s14, 0x2000
	s_add_u32 s14, s18, 0xb0000
	v_lshl_add_u64 v[218:219], s[18:19], 0, v[134:135]
	s_addc_u32 s15, s19, 0
	s_add_i32 s56, s48, s23
	global_load_lds_dwordx4 v[218:219], off
	s_mov_b32 m0, s56
	v_lshl_add_u64 v[222:223], s[52:53], 0, v[132:133]
	global_load_lds_dwordx4 v130, s[14:15]
	s_add_i32 m0, s56, 0x2000
	s_nop 0
	global_load_lds_dwordx4 v134, s[14:15]
	v_lshl_add_u64 v[220:221], s[52:53], 0, v[128:129]
	s_mov_b32 m0, s34
	s_nop 0
	global_load_lds_dwordx4 v[220:221], off
	s_mov_b32 m0, s35
	s_nop 0
	global_load_lds_dwordx4 v[222:223], off
	s_waitcnt vmcnt(8)
	s_waitcnt lgkmcnt(0)
	s_barrier
	v_mfma_f32_16x16x32_bf16 v[60:63], v[154:157], v[186:189], v[60:63]
	v_mfma_f32_16x16x32_bf16 v[56:59], v[162:165], v[186:189], v[56:59]
	v_mfma_f32_16x16x32_bf16 v[48:51], v[154:157], v[194:197], v[48:51]
	v_mfma_f32_16x16x32_bf16 v[40:43], v[162:165], v[194:197], v[40:43]
	v_mfma_f32_16x16x32_bf16 v[32:35], v[154:157], v[202:205], v[32:35]
	v_mfma_f32_16x16x32_bf16 v[24:27], v[162:165], v[202:205], v[24:27]
	v_mfma_f32_16x16x32_bf16 v[16:19], v[154:157], v[210:213], v[16:19]
	v_mfma_f32_16x16x32_bf16 v[8:11], v[162:165], v[210:213], v[8:11]
	v_mfma_f32_16x16x32_bf16 v[60:63], v[158:161], v[190:193], v[60:63]
	v_mfma_f32_16x16x32_bf16 v[56:59], v[166:169], v[190:193], v[56:59]
	v_mfma_f32_16x16x32_bf16 v[48:51], v[158:161], v[198:201], v[48:51]
	v_mfma_f32_16x16x32_bf16 v[40:43], v[166:169], v[198:201], v[40:43]
	v_mfma_f32_16x16x32_bf16 v[32:35], v[158:161], v[206:209], v[32:35]
	v_mfma_f32_16x16x32_bf16 v[24:27], v[166:169], v[206:209], v[24:27]
	v_mfma_f32_16x16x32_bf16 v[16:19], v[158:161], v[214:217], v[16:19]
	v_mfma_f32_16x16x32_bf16 v[8:11], v[166:169], v[214:217], v[8:11]
	v_mfma_f32_16x16x32_bf16 v[52:55], v[170:173], v[186:189], v[52:55]
	v_mfma_f32_16x16x32_bf16 v[44:47], v[178:181], v[186:189], v[44:47]
	v_mfma_f32_16x16x32_bf16 v[36:39], v[170:173], v[194:197], v[36:39]
	v_mfma_f32_16x16x32_bf16 v[28:31], v[178:181], v[194:197], v[28:31]
	v_mfma_f32_16x16x32_bf16 v[20:23], v[170:173], v[202:205], v[20:23]
	v_mfma_f32_16x16x32_bf16 v[12:15], v[178:181], v[202:205], v[12:15]
	v_mfma_f32_16x16x32_bf16 v[4:7], v[170:173], v[210:213], v[4:7]
	v_mfma_f32_16x16x32_bf16 v[0:3], v[178:181], v[210:213], v[0:3]
	v_mfma_f32_16x16x32_bf16 v[52:55], v[174:177], v[190:193], v[52:55]
	v_mfma_f32_16x16x32_bf16 v[44:47], v[182:185], v[190:193], v[44:47]
	v_mfma_f32_16x16x32_bf16 v[36:39], v[174:177], v[198:201], v[36:39]
	v_mfma_f32_16x16x32_bf16 v[28:31], v[182:185], v[198:201], v[28:31]
	v_mfma_f32_16x16x32_bf16 v[20:23], v[174:177], v[206:209], v[20:23]
	v_mfma_f32_16x16x32_bf16 v[12:15], v[182:185], v[206:209], v[12:15]
	v_mfma_f32_16x16x32_bf16 v[4:7], v[174:177], v[214:217], v[4:7]
	v_mfma_f32_16x16x32_bf16 v[0:3], v[182:185], v[214:217], v[0:3]
	s_barrier
	s_add_i32 s56, 0, 0x18000
	v_add_u32_e32 v153, s56, v148
	s_add_i32 s57, 0, 0x1c000
	ds_read_b128 v[154:157], v153
	ds_read_b128 v[158:161], v153 offset:1024
	ds_read_b128 v[162:165], v153 offset:2048
	ds_read_b128 v[166:169], v153 offset:3072
	v_add_u32_e32 v153, s57, v148
	ds_read_b128 v[170:173], v153
	ds_read_b128 v[174:177], v153 offset:1024
	ds_read_b128 v[178:181], v153 offset:2048
	ds_read_b128 v[182:185], v153 offset:3072
	s_add_u32 s14, s52, 0xb0000
	s_addc_u32 s15, s53, 0
	s_mov_b32 m0, s38
	ds_read_b128 v[186:189], v152 offset:32768
	ds_read_b128 v[190:193], v152 offset:33792
	ds_read_b128 v[194:197], v152 offset:34816
	ds_read_b128 v[198:201], v152 offset:35840
	ds_read_b128 v[202:205], v152 offset:36864
	ds_read_b128 v[206:209], v152 offset:37888
	ds_read_b128 v[210:213], v152 offset:38912
	ds_read_b128 v[214:217], v152 offset:39936
	global_load_lds_dwordx4 v128, s[14:15]
	s_mov_b32 m0, s39
	s_nop 0
	global_load_lds_dwordx4 v132, s[14:15]
	s_waitcnt vmcnt(8)
	s_waitcnt lgkmcnt(0)
	s_barrier
	v_mfma_f32_16x16x32_bf16 v[124:127], v[154:157], v[186:189], v[124:127]
	v_mfma_f32_16x16x32_bf16 v[120:123], v[162:165], v[186:189], v[120:123]
	v_mfma_f32_16x16x32_bf16 v[112:115], v[154:157], v[194:197], v[112:115]
	v_mfma_f32_16x16x32_bf16 v[104:107], v[162:165], v[194:197], v[104:107]
	v_mfma_f32_16x16x32_bf16 v[96:99], v[154:157], v[202:205], v[96:99]
	v_mfma_f32_16x16x32_bf16 v[88:91], v[162:165], v[202:205], v[88:91]
	v_mfma_f32_16x16x32_bf16 v[80:83], v[154:157], v[210:213], v[80:83]
	v_mfma_f32_16x16x32_bf16 v[72:75], v[162:165], v[210:213], v[72:75]
	v_mfma_f32_16x16x32_bf16 v[124:127], v[158:161], v[190:193], v[124:127]
	v_mfma_f32_16x16x32_bf16 v[120:123], v[166:169], v[190:193], v[120:123]
	v_mfma_f32_16x16x32_bf16 v[112:115], v[158:161], v[198:201], v[112:115]
	v_mfma_f32_16x16x32_bf16 v[104:107], v[166:169], v[198:201], v[104:107]
	v_mfma_f32_16x16x32_bf16 v[96:99], v[158:161], v[206:209], v[96:99]
	v_mfma_f32_16x16x32_bf16 v[88:91], v[166:169], v[206:209], v[88:91]
	v_mfma_f32_16x16x32_bf16 v[80:83], v[158:161], v[214:217], v[80:83]
	v_mfma_f32_16x16x32_bf16 v[72:75], v[166:169], v[214:217], v[72:75]
	v_mfma_f32_16x16x32_bf16 v[116:119], v[170:173], v[186:189], v[116:119]
	v_mfma_f32_16x16x32_bf16 v[108:111], v[178:181], v[186:189], v[108:111]
	v_mfma_f32_16x16x32_bf16 v[100:103], v[170:173], v[194:197], v[100:103]
	v_mfma_f32_16x16x32_bf16 v[92:95], v[178:181], v[194:197], v[92:95]
	v_mfma_f32_16x16x32_bf16 v[84:87], v[170:173], v[202:205], v[84:87]
	v_mfma_f32_16x16x32_bf16 v[76:79], v[178:181], v[202:205], v[76:79]
	v_mfma_f32_16x16x32_bf16 v[68:71], v[170:173], v[210:213], v[68:71]
	v_mfma_f32_16x16x32_bf16 v[64:67], v[178:181], v[210:213], v[64:67]
	v_mfma_f32_16x16x32_bf16 v[116:119], v[174:177], v[190:193], v[116:119]
	v_mfma_f32_16x16x32_bf16 v[108:111], v[182:185], v[190:193], v[108:111]
	v_mfma_f32_16x16x32_bf16 v[100:103], v[174:177], v[198:201], v[100:103]
	v_mfma_f32_16x16x32_bf16 v[92:95], v[182:185], v[198:201], v[92:95]
	v_mfma_f32_16x16x32_bf16 v[84:87], v[174:177], v[206:209], v[84:87]
	v_mfma_f32_16x16x32_bf16 v[76:79], v[182:185], v[206:209], v[76:79]
	v_mfma_f32_16x16x32_bf16 v[68:71], v[174:177], v[214:217], v[68:71]
	v_mfma_f32_16x16x32_bf16 v[64:67], v[182:185], v[214:217], v[64:67]
	s_barrier
	s_add_i32 s14, s56, s23
	v_lshl_add_u64 v[144:145], v[144:145], 0, s[8:9]
	s_mov_b32 m0, s14
	ds_read_b128 v[186:189], v152 offset:49152
	ds_read_b128 v[190:193], v152 offset:50176
	ds_read_b128 v[194:197], v152 offset:51200
	ds_read_b128 v[198:201], v152 offset:52224
	ds_read_b128 v[202:205], v152 offset:53248
	ds_read_b128 v[206:209], v152 offset:54272
	ds_read_b128 v[210:213], v152 offset:55296
	ds_read_b128 v[214:217], v152 offset:56320
	global_load_lds_dwordx4 v[144:145], off
	s_add_i32 m0, s14, 0x2000
	s_add_u32 s14, s18, 0xb0080
	v_lshl_add_u64 v[144:145], v[218:219], 0, s[8:9]
	s_addc_u32 s15, s19, 0
	s_add_i32 s18, s57, s23
	global_load_lds_dwordx4 v[144:145], off
	s_mov_b32 m0, s18
	s_nop 0
	global_load_lds_dwordx4 v130, s[14:15]
	s_add_i32 m0, s18, 0x2000
	s_nop 0
	global_load_lds_dwordx4 v134, s[14:15]
	v_lshl_add_u64 v[144:145], v[220:221], 0, s[8:9]
	s_mov_b32 m0, s43
	s_nop 0
	global_load_lds_dwordx4 v[144:145], off
	v_lshl_add_u64 v[144:145], v[222:223], 0, s[8:9]
	s_mov_b32 m0, s44
	s_nop 0
	global_load_lds_dwordx4 v[144:145], off
	s_waitcnt vmcnt(8)
	s_waitcnt lgkmcnt(0)
	s_barrier
	v_mfma_f32_16x16x32_bf16 v[60:63], v[154:157], v[186:189], v[60:63]
	v_mfma_f32_16x16x32_bf16 v[56:59], v[162:165], v[186:189], v[56:59]
	v_mfma_f32_16x16x32_bf16 v[48:51], v[154:157], v[194:197], v[48:51]
	v_mfma_f32_16x16x32_bf16 v[40:43], v[162:165], v[194:197], v[40:43]
	v_mfma_f32_16x16x32_bf16 v[32:35], v[154:157], v[202:205], v[32:35]
	v_mfma_f32_16x16x32_bf16 v[24:27], v[162:165], v[202:205], v[24:27]
	v_mfma_f32_16x16x32_bf16 v[16:19], v[154:157], v[210:213], v[16:19]
	v_mfma_f32_16x16x32_bf16 v[8:11], v[162:165], v[210:213], v[8:11]
	v_mfma_f32_16x16x32_bf16 v[60:63], v[158:161], v[190:193], v[60:63]
	v_mfma_f32_16x16x32_bf16 v[56:59], v[166:169], v[190:193], v[56:59]
	v_mfma_f32_16x16x32_bf16 v[48:51], v[158:161], v[198:201], v[48:51]
	v_mfma_f32_16x16x32_bf16 v[40:43], v[166:169], v[198:201], v[40:43]
	v_mfma_f32_16x16x32_bf16 v[32:35], v[158:161], v[206:209], v[32:35]
	v_mfma_f32_16x16x32_bf16 v[24:27], v[166:169], v[206:209], v[24:27]
	v_mfma_f32_16x16x32_bf16 v[16:19], v[158:161], v[214:217], v[16:19]
	v_mfma_f32_16x16x32_bf16 v[8:11], v[166:169], v[214:217], v[8:11]
	v_mfma_f32_16x16x32_bf16 v[52:55], v[170:173], v[186:189], v[52:55]
	v_mfma_f32_16x16x32_bf16 v[44:47], v[178:181], v[186:189], v[44:47]
	v_mfma_f32_16x16x32_bf16 v[36:39], v[170:173], v[194:197], v[36:39]
	v_mfma_f32_16x16x32_bf16 v[28:31], v[178:181], v[194:197], v[28:31]
	v_mfma_f32_16x16x32_bf16 v[20:23], v[170:173], v[202:205], v[20:23]
	v_mfma_f32_16x16x32_bf16 v[12:15], v[178:181], v[202:205], v[12:15]
	v_mfma_f32_16x16x32_bf16 v[4:7], v[170:173], v[210:213], v[4:7]
	v_mfma_f32_16x16x32_bf16 v[0:3], v[178:181], v[210:213], v[0:3]
	v_mfma_f32_16x16x32_bf16 v[52:55], v[174:177], v[190:193], v[52:55]
	v_mfma_f32_16x16x32_bf16 v[44:47], v[182:185], v[190:193], v[44:47]
	v_mfma_f32_16x16x32_bf16 v[36:39], v[174:177], v[198:201], v[36:39]
	v_mfma_f32_16x16x32_bf16 v[28:31], v[182:185], v[198:201], v[28:31]
	v_mfma_f32_16x16x32_bf16 v[20:23], v[174:177], v[206:209], v[20:23]
	v_mfma_f32_16x16x32_bf16 v[12:15], v[182:185], v[206:209], v[12:15]
	v_mfma_f32_16x16x32_bf16 v[4:7], v[174:177], v[214:217], v[4:7]
	v_mfma_f32_16x16x32_bf16 v[0:3], v[182:185], v[214:217], v[0:3]
	s_barrier
	s_add_i32 s55, s55, 2
	s_add_u32 s0, s0, 0x100
	s_addc_u32 s1, s1, 0
	s_cmp_gt_u32 s55, 41
	s_mov_b64 s[14:15], s[16:17]
	s_cbranch_scc0 .LBB0_201
	s_and_b64 vcc, exec, s[10:11]
	s_cbranch_vccz .LBB0_204
	s_barrier

.LBB0_336:
	ds_read_b128 v[154:157], v150
	ds_read_b128 v[158:161], v150 offset:1024
	ds_read_b128 v[162:165], v150 offset:2048
	ds_read_b128 v[166:169], v150 offset:3072
	ds_read_b128 v[170:173], v151
	ds_read_b128 v[174:177], v151 offset:1024
	ds_read_b128 v[178:181], v151 offset:2048
	ds_read_b128 v[182:185], v151 offset:3072
	s_add_u32 s54, s52, 0xfffc0080
	s_addc_u32 s55, s53, -1
	s_cmp_eq_u32 s51, 12
	s_cselect_b32 s57, s0, s55
	s_cselect_b32 s56, s1, s54
	s_cselect_b32 s55, s11, s50
	s_cselect_b32 s54, s13, s49
	s_add_i32 m0, s19, 0xc000
	ds_read_b128 v[186:189], v152
	ds_read_b128 v[190:193], v152 offset:1024
	ds_read_b128 v[194:197], v152 offset:2048
	ds_read_b128 v[198:201], v152 offset:3072
	ds_read_b128 v[202:205], v152 offset:4096
	ds_read_b128 v[206:209], v152 offset:5120
	ds_read_b128 v[210:213], v152 offset:6144
	ds_read_b128 v[214:217], v152 offset:7168
	global_load_lds_dwordx4 v136, s[52:53]
	s_add_i32 m0, s19, 0xe000
	s_nop 0
	global_load_lds_dwordx4 v138, s[52:53]
	s_waitcnt vmcnt(8)
	s_waitcnt lgkmcnt(0)
	s_barrier
	v_mfma_f32_16x16x32_bf16 v[124:127], v[154:157], v[186:189], v[124:127]
	v_mfma_f32_16x16x32_bf16 v[120:123], v[162:165], v[186:189], v[120:123]
	v_mfma_f32_16x16x32_bf16 v[112:115], v[154:157], v[194:197], v[112:115]
	v_mfma_f32_16x16x32_bf16 v[104:107], v[162:165], v[194:197], v[104:107]
	v_mfma_f32_16x16x32_bf16 v[96:99], v[154:157], v[202:205], v[96:99]
	v_mfma_f32_16x16x32_bf16 v[88:91], v[162:165], v[202:205], v[88:91]
	v_mfma_f32_16x16x32_bf16 v[80:83], v[154:157], v[210:213], v[80:83]
	v_mfma_f32_16x16x32_bf16 v[72:75], v[162:165], v[210:213], v[72:75]
	v_mfma_f32_16x16x32_bf16 v[124:127], v[158:161], v[190:193], v[124:127]
	v_mfma_f32_16x16x32_bf16 v[120:123], v[166:169], v[190:193], v[120:123]
	v_mfma_f32_16x16x32_bf16 v[112:115], v[158:161], v[198:201], v[112:115]
	v_mfma_f32_16x16x32_bf16 v[104:107], v[166:169], v[198:201], v[104:107]
	v_mfma_f32_16x16x32_bf16 v[96:99], v[158:161], v[206:209], v[96:99]
	v_mfma_f32_16x16x32_bf16 v[88:91], v[166:169], v[206:209], v[88:91]
	v_mfma_f32_16x16x32_bf16 v[80:83], v[158:161], v[214:217], v[80:83]
	v_mfma_f32_16x16x32_bf16 v[72:75], v[166:169], v[214:217], v[72:75]
	v_mfma_f32_16x16x32_bf16 v[116:119], v[170:173], v[186:189], v[116:119]
	v_mfma_f32_16x16x32_bf16 v[108:111], v[178:181], v[186:189], v[108:111]
	v_mfma_f32_16x16x32_bf16 v[100:103], v[170:173], v[194:197], v[100:103]
	v_mfma_f32_16x16x32_bf16 v[92:95], v[178:181], v[194:197], v[92:95]
	v_mfma_f32_16x16x32_bf16 v[84:87], v[170:173], v[202:205], v[84:87]
	v_mfma_f32_16x16x32_bf16 v[76:79], v[178:181], v[202:205], v[76:79]
	v_mfma_f32_16x16x32_bf16 v[68:71], v[170:173], v[210:213], v[68:71]
	v_mfma_f32_16x16x32_bf16 v[64:67], v[178:181], v[210:213], v[64:67]
	v_mfma_f32_16x16x32_bf16 v[116:119], v[174:177], v[190:193], v[116:119]
	v_mfma_f32_16x16x32_bf16 v[108:111], v[182:185], v[190:193], v[108:111]
	v_mfma_f32_16x16x32_bf16 v[100:103], v[174:177], v[198:201], v[100:103]
	v_mfma_f32_16x16x32_bf16 v[92:95], v[182:185], v[198:201], v[92:95]
	v_mfma_f32_16x16x32_bf16 v[84:87], v[174:177], v[206:209], v[84:87]
	v_mfma_f32_16x16x32_bf16 v[76:79], v[182:185], v[206:209], v[76:79]
	v_mfma_f32_16x16x32_bf16 v[68:71], v[174:177], v[214:217], v[68:71]
	v_mfma_f32_16x16x32_bf16 v[64:67], v[182:185], v[214:217], v[64:67]
	s_barrier
	s_add_i32 s58, s46, s23
	v_lshl_add_u64 v[144:145], s[54:55], 0, v[130:131]
	s_mov_b32 m0, s58
	ds_read_b128 v[186:189], v152 offset:16384
	ds_read_b128 v[190:193], v152 offset:17408
	ds_read_b128 v[194:197], v152 offset:18432
	ds_read_b128 v[198:201], v152 offset:19456
	ds_read_b128 v[202:205], v152 offset:20480
	ds_read_b128 v[206:209], v152 offset:21504
	ds_read_b128 v[210:213], v152 offset:22528
	ds_read_b128 v[214:217], v152 offset:23552
	global_load_lds_dwordx4 v[144:145], off
	s_add_i32 m0, s58, 0x2000
	s_add_u32 s58, s54, 0x40000
	v_lshl_add_u64 v[218:219], s[54:55], 0, v[134:135]
	s_addc_u32 s59, s55, 0
	s_add_i32 s60, s47, s23
	global_load_lds_dwordx4 v[218:219], off
	s_mov_b32 m0, s60
	v_lshl_add_u64 v[222:223], s[56:57], 0, v[132:133]
	global_load_lds_dwordx4 v130, s[58:59]
	s_add_i32 m0, s60, 0x2000
	s_nop 0
	global_load_lds_dwordx4 v134, s[58:59]
	v_lshl_add_u64 v[220:221], s[56:57], 0, v[128:129]
	s_mov_b32 m0, s19
	s_nop 0
	global_load_lds_dwordx4 v[220:221], off
	s_mov_b32 m0, s34
	s_nop 0
	global_load_lds_dwordx4 v[222:223], off
	s_waitcnt vmcnt(8)
	s_waitcnt lgkmcnt(0)
	s_barrier
	v_mfma_f32_16x16x32_bf16 v[60:63], v[154:157], v[186:189], v[60:63]
	v_mfma_f32_16x16x32_bf16 v[56:59], v[162:165], v[186:189], v[56:59]
	v_mfma_f32_16x16x32_bf16 v[48:51], v[154:157], v[194:197], v[48:51]
	v_mfma_f32_16x16x32_bf16 v[40:43], v[162:165], v[194:197], v[40:43]
	v_mfma_f32_16x16x32_bf16 v[32:35], v[154:157], v[202:205], v[32:35]
	v_mfma_f32_16x16x32_bf16 v[24:27], v[162:165], v[202:205], v[24:27]
	v_mfma_f32_16x16x32_bf16 v[16:19], v[154:157], v[210:213], v[16:19]
	v_mfma_f32_16x16x32_bf16 v[8:11], v[162:165], v[210:213], v[8:11]
	v_mfma_f32_16x16x32_bf16 v[60:63], v[158:161], v[190:193], v[60:63]
	v_mfma_f32_16x16x32_bf16 v[56:59], v[166:169], v[190:193], v[56:59]
	v_mfma_f32_16x16x32_bf16 v[48:51], v[158:161], v[198:201], v[48:51]
	v_mfma_f32_16x16x32_bf16 v[40:43], v[166:169], v[198:201], v[40:43]
	v_mfma_f32_16x16x32_bf16 v[32:35], v[158:161], v[206:209], v[32:35]
	v_mfma_f32_16x16x32_bf16 v[24:27], v[166:169], v[206:209], v[24:27]
	v_mfma_f32_16x16x32_bf16 v[16:19], v[158:161], v[214:217], v[16:19]
	v_mfma_f32_16x16x32_bf16 v[8:11], v[166:169], v[214:217], v[8:11]
	v_mfma_f32_16x16x32_bf16 v[52:55], v[170:173], v[186:189], v[52:55]
	v_mfma_f32_16x16x32_bf16 v[44:47], v[178:181], v[186:189], v[44:47]
	v_mfma_f32_16x16x32_bf16 v[36:39], v[170:173], v[194:197], v[36:39]
	v_mfma_f32_16x16x32_bf16 v[28:31], v[178:181], v[194:197], v[28:31]
	v_mfma_f32_16x16x32_bf16 v[20:23], v[170:173], v[202:205], v[20:23]
	v_mfma_f32_16x16x32_bf16 v[12:15], v[178:181], v[202:205], v[12:15]
	v_mfma_f32_16x16x32_bf16 v[4:7], v[170:173], v[210:213], v[4:7]
	v_mfma_f32_16x16x32_bf16 v[0:3], v[178:181], v[210:213], v[0:3]
	v_mfma_f32_16x16x32_bf16 v[52:55], v[174:177], v[190:193], v[52:55]
	v_mfma_f32_16x16x32_bf16 v[44:47], v[182:185], v[190:193], v[44:47]
	v_mfma_f32_16x16x32_bf16 v[36:39], v[174:177], v[198:201], v[36:39]
	v_mfma_f32_16x16x32_bf16 v[28:31], v[182:185], v[198:201], v[28:31]
	v_mfma_f32_16x16x32_bf16 v[20:23], v[174:177], v[206:209], v[20:23]
	v_mfma_f32_16x16x32_bf16 v[12:15], v[182:185], v[206:209], v[12:15]
	v_mfma_f32_16x16x32_bf16 v[4:7], v[174:177], v[214:217], v[4:7]
	v_mfma_f32_16x16x32_bf16 v[0:3], v[182:185], v[214:217], v[0:3]
	s_barrier
	s_add_i32 s58, 0, 0x18000
	v_add_u32_e32 v153, s58, v148
	s_add_i32 s59, 0, 0x1c000
	ds_read_b128 v[154:157], v153
	ds_read_b128 v[158:161], v153 offset:1024
	ds_read_b128 v[162:165], v153 offset:2048
	ds_read_b128 v[166:169], v153 offset:3072
	v_add_u32_e32 v153, s59, v148
	ds_read_b128 v[170:173], v153
	ds_read_b128 v[174:177], v153 offset:1024
	ds_read_b128 v[178:181], v153 offset:2048
	ds_read_b128 v[182:185], v153 offset:3072
	s_add_u32 s56, s56, 0x40000
	s_addc_u32 s57, s57, 0
	s_mov_b32 m0, s35
	ds_read_b128 v[186:189], v152 offset:32768
	ds_read_b128 v[190:193], v152 offset:33792
	ds_read_b128 v[194:197], v152 offset:34816
	ds_read_b128 v[198:201], v152 offset:35840
	ds_read_b128 v[202:205], v152 offset:36864
	ds_read_b128 v[206:209], v152 offset:37888
	ds_read_b128 v[210:213], v152 offset:38912
	ds_read_b128 v[214:217], v152 offset:39936
	global_load_lds_dwordx4 v128, s[56:57]
	s_mov_b32 m0, s38
	s_nop 0
	global_load_lds_dwordx4 v132, s[56:57]
	s_waitcnt vmcnt(8)
	s_waitcnt lgkmcnt(0)
	s_barrier
	v_mfma_f32_16x16x32_bf16 v[124:127], v[154:157], v[186:189], v[124:127]
	v_mfma_f32_16x16x32_bf16 v[120:123], v[162:165], v[186:189], v[120:123]
	v_mfma_f32_16x16x32_bf16 v[112:115], v[154:157], v[194:197], v[112:115]
	v_mfma_f32_16x16x32_bf16 v[104:107], v[162:165], v[194:197], v[104:107]
	v_mfma_f32_16x16x32_bf16 v[96:99], v[154:157], v[202:205], v[96:99]
	v_mfma_f32_16x16x32_bf16 v[88:91], v[162:165], v[202:205], v[88:91]
	v_mfma_f32_16x16x32_bf16 v[80:83], v[154:157], v[210:213], v[80:83]
	v_mfma_f32_16x16x32_bf16 v[72:75], v[162:165], v[210:213], v[72:75]
	v_mfma_f32_16x16x32_bf16 v[124:127], v[158:161], v[190:193], v[124:127]
	v_mfma_f32_16x16x32_bf16 v[120:123], v[166:169], v[190:193], v[120:123]
	v_mfma_f32_16x16x32_bf16 v[112:115], v[158:161], v[198:201], v[112:115]
	v_mfma_f32_16x16x32_bf16 v[104:107], v[166:169], v[198:201], v[104:107]
	v_mfma_f32_16x16x32_bf16 v[96:99], v[158:161], v[206:209], v[96:99]
	v_mfma_f32_16x16x32_bf16 v[88:91], v[166:169], v[206:209], v[88:91]
	v_mfma_f32_16x16x32_bf16 v[80:83], v[158:161], v[214:217], v[80:83]
	v_mfma_f32_16x16x32_bf16 v[72:75], v[166:169], v[214:217], v[72:75]
	v_mfma_f32_16x16x32_bf16 v[116:119], v[170:173], v[186:189], v[116:119]
	v_mfma_f32_16x16x32_bf16 v[108:111], v[178:181], v[186:189], v[108:111]
	v_mfma_f32_16x16x32_bf16 v[100:103], v[170:173], v[194:197], v[100:103]
	v_mfma_f32_16x16x32_bf16 v[92:95], v[178:181], v[194:197], v[92:95]
	v_mfma_f32_16x16x32_bf16 v[84:87], v[170:173], v[202:205], v[84:87]
	v_mfma_f32_16x16x32_bf16 v[76:79], v[178:181], v[202:205], v[76:79]
	v_mfma_f32_16x16x32_bf16 v[68:71], v[170:173], v[210:213], v[68:71]
	v_mfma_f32_16x16x32_bf16 v[64:67], v[178:181], v[210:213], v[64:67]
	v_mfma_f32_16x16x32_bf16 v[116:119], v[174:177], v[190:193], v[116:119]
	v_mfma_f32_16x16x32_bf16 v[108:111], v[182:185], v[190:193], v[108:111]
	v_mfma_f32_16x16x32_bf16 v[100:103], v[174:177], v[198:201], v[100:103]
	v_mfma_f32_16x16x32_bf16 v[92:95], v[182:185], v[198:201], v[92:95]
	v_mfma_f32_16x16x32_bf16 v[84:87], v[174:177], v[206:209], v[84:87]
	v_mfma_f32_16x16x32_bf16 v[76:79], v[182:185], v[206:209], v[76:79]
	v_mfma_f32_16x16x32_bf16 v[68:71], v[174:177], v[214:217], v[68:71]
	v_mfma_f32_16x16x32_bf16 v[64:67], v[182:185], v[214:217], v[64:67]
	s_barrier
	s_add_i32 s56, s58, s23
	v_lshl_add_u64 v[144:145], v[144:145], 0, s[6:7]
	s_mov_b32 m0, s56
	ds_read_b128 v[186:189], v152 offset:49152
	ds_read_b128 v[190:193], v152 offset:50176
	ds_read_b128 v[194:197], v152 offset:51200
	ds_read_b128 v[198:201], v152 offset:52224
	ds_read_b128 v[202:205], v152 offset:53248
	ds_read_b128 v[206:209], v152 offset:54272
	ds_read_b128 v[210:213], v152 offset:55296
	ds_read_b128 v[214:217], v152 offset:56320
	global_load_lds_dwordx4 v[144:145], off
	s_add_i32 m0, s56, 0x2000
	s_add_u32 s54, s54, 0x40080
	v_lshl_add_u64 v[144:145], v[218:219], 0, s[6:7]
	s_addc_u32 s55, s55, 0
	s_add_i32 s56, s59, s23
	global_load_lds_dwordx4 v[144:145], off
	s_mov_b32 m0, s56
	s_nop 0
	global_load_lds_dwordx4 v130, s[54:55]
	s_add_i32 m0, s56, 0x2000
	s_nop 0
	global_load_lds_dwordx4 v134, s[54:55]
	v_lshl_add_u64 v[144:145], v[220:221], 0, s[6:7]
	s_mov_b32 m0, s42
	s_nop 0
	global_load_lds_dwordx4 v[144:145], off
	v_lshl_add_u64 v[144:145], v[222:223], 0, s[6:7]
	s_mov_b32 m0, s43
	s_nop 0
	global_load_lds_dwordx4 v[144:145], off
	s_waitcnt vmcnt(8)
	s_waitcnt lgkmcnt(0)
	s_barrier
	v_mfma_f32_16x16x32_bf16 v[60:63], v[154:157], v[186:189], v[60:63]
	v_mfma_f32_16x16x32_bf16 v[56:59], v[162:165], v[186:189], v[56:59]
	v_mfma_f32_16x16x32_bf16 v[48:51], v[154:157], v[194:197], v[48:51]
	v_mfma_f32_16x16x32_bf16 v[40:43], v[162:165], v[194:197], v[40:43]
	v_mfma_f32_16x16x32_bf16 v[32:35], v[154:157], v[202:205], v[32:35]
	v_mfma_f32_16x16x32_bf16 v[24:27], v[162:165], v[202:205], v[24:27]
	v_mfma_f32_16x16x32_bf16 v[16:19], v[154:157], v[210:213], v[16:19]
	v_mfma_f32_16x16x32_bf16 v[8:11], v[162:165], v[210:213], v[8:11]
	v_mfma_f32_16x16x32_bf16 v[60:63], v[158:161], v[190:193], v[60:63]
	v_mfma_f32_16x16x32_bf16 v[56:59], v[166:169], v[190:193], v[56:59]
	v_mfma_f32_16x16x32_bf16 v[48:51], v[158:161], v[198:201], v[48:51]
	v_mfma_f32_16x16x32_bf16 v[40:43], v[166:169], v[198:201], v[40:43]
	v_mfma_f32_16x16x32_bf16 v[32:35], v[158:161], v[206:209], v[32:35]
	v_mfma_f32_16x16x32_bf16 v[24:27], v[166:169], v[206:209], v[24:27]
	v_mfma_f32_16x16x32_bf16 v[16:19], v[158:161], v[214:217], v[16:19]
	v_mfma_f32_16x16x32_bf16 v[8:11], v[166:169], v[214:217], v[8:11]
	v_mfma_f32_16x16x32_bf16 v[52:55], v[170:173], v[186:189], v[52:55]
	v_mfma_f32_16x16x32_bf16 v[44:47], v[178:181], v[186:189], v[44:47]
	v_mfma_f32_16x16x32_bf16 v[36:39], v[170:173], v[194:197], v[36:39]
	v_mfma_f32_16x16x32_bf16 v[28:31], v[178:181], v[194:197], v[28:31]
	v_mfma_f32_16x16x32_bf16 v[20:23], v[170:173], v[202:205], v[20:23]
	v_mfma_f32_16x16x32_bf16 v[12:15], v[178:181], v[202:205], v[12:15]
	v_mfma_f32_16x16x32_bf16 v[4:7], v[170:173], v[210:213], v[4:7]
	v_mfma_f32_16x16x32_bf16 v[0:3], v[178:181], v[210:213], v[0:3]
	v_mfma_f32_16x16x32_bf16 v[52:55], v[174:177], v[190:193], v[52:55]
	v_mfma_f32_16x16x32_bf16 v[44:47], v[182:185], v[190:193], v[44:47]
	v_mfma_f32_16x16x32_bf16 v[36:39], v[174:177], v[198:201], v[36:39]
	v_mfma_f32_16x16x32_bf16 v[28:31], v[182:185], v[198:201], v[28:31]
	v_mfma_f32_16x16x32_bf16 v[20:23], v[174:177], v[206:209], v[20:23]
	v_mfma_f32_16x16x32_bf16 v[12:15], v[182:185], v[206:209], v[12:15]
	v_mfma_f32_16x16x32_bf16 v[4:7], v[174:177], v[214:217], v[4:7]
	v_mfma_f32_16x16x32_bf16 v[0:3], v[182:185], v[214:217], v[0:3]
	s_barrier
	s_add_i32 s51, s51, 2
	s_add_u32 s52, s52, 0x100
	s_addc_u32 s53, s53, 0
	s_add_u32 s49, s49, 0x100
	s_addc_u32 s50, s50, 0
	s_cmp_gt_u32 s51, 13
	s_cbranch_scc0 .LBB0_336
	s_and_b64 vcc, exec, s[8:9]
	s_cbranch_vccz .LBB0_339
	s_barrier

.LBB0_470:
	ds_read_b128 v[130:133], v242
	ds_read_b128 v[134:137], v242 offset:1024
	ds_read_b128 v[138:141], v242 offset:2048
	ds_read_b128 v[142:145], v242 offset:3072
	ds_read_b128 v[146:149], v243
	ds_read_b128 v[150:153], v243 offset:1024
	ds_read_b128 v[154:157], v243 offset:2048
	ds_read_b128 v[158:161], v243 offset:3072
	s_add_i32 s60, s10, 2
	s_add_u32 s20, s56, 0x80
	s_addc_u32 s35, s57, 0
	s_cmp_eq_u32 s63, s10
	s_cselect_b32 s59, s5, s35
	s_cselect_b32 s58, s4, s20
	s_cselect_b32 s39, s55, s1
	s_cselect_b32 s38, s54, s0
	v_lshl_add_u64 v[194:195], s[56:57], 0, v[230:231]
	s_add_i32 m0, s45, 0xc000
	ds_read_b128 v[162:165], v244
	ds_read_b128 v[166:169], v244 offset:1024
	ds_read_b128 v[170:173], v244 offset:2048
	ds_read_b128 v[174:177], v244 offset:3072
	ds_read_b128 v[178:181], v244 offset:4096
	ds_read_b128 v[182:185], v244 offset:5120
	ds_read_b128 v[186:189], v244 offset:6144
	ds_read_b128 v[190:193], v244 offset:7168
	global_load_lds_dwordx4 v[194:195], off
	v_lshl_add_u64 v[194:195], s[56:57], 0, v[232:233]
	s_add_i32 m0, s45, 0xe000
	s_nop 0
	global_load_lds_dwordx4 v[194:195], off
	s_waitcnt vmcnt(8)
	s_waitcnt lgkmcnt(0)
	s_barrier
	v_mfma_f32_16x16x32_bf16 v[126:129], v[130:133], v[162:165], v[126:129]
	v_mfma_f32_16x16x32_bf16 v[122:125], v[138:141], v[162:165], v[122:125]
	v_mfma_f32_16x16x32_bf16 v[118:121], v[130:133], v[170:173], v[118:121]
	v_mfma_f32_16x16x32_bf16 v[114:117], v[138:141], v[170:173], v[114:117]
	v_mfma_f32_16x16x32_bf16 v[110:113], v[130:133], v[178:181], v[110:113]
	v_mfma_f32_16x16x32_bf16 v[106:109], v[138:141], v[178:181], v[106:109]
	v_mfma_f32_16x16x32_bf16 v[102:105], v[130:133], v[186:189], v[102:105]
	v_mfma_f32_16x16x32_bf16 v[98:101], v[138:141], v[186:189], v[98:101]
	v_mfma_f32_16x16x32_bf16 v[126:129], v[134:137], v[166:169], v[126:129]
	v_mfma_f32_16x16x32_bf16 v[122:125], v[142:145], v[166:169], v[122:125]
	v_mfma_f32_16x16x32_bf16 v[118:121], v[134:137], v[174:177], v[118:121]
	v_mfma_f32_16x16x32_bf16 v[114:117], v[142:145], v[174:177], v[114:117]
	v_mfma_f32_16x16x32_bf16 v[110:113], v[134:137], v[182:185], v[110:113]
	v_mfma_f32_16x16x32_bf16 v[106:109], v[142:145], v[182:185], v[106:109]
	v_mfma_f32_16x16x32_bf16 v[102:105], v[134:137], v[190:193], v[102:105]
	v_mfma_f32_16x16x32_bf16 v[98:101], v[142:145], v[190:193], v[98:101]
	v_mfma_f32_16x16x32_bf16 v[62:65], v[146:149], v[162:165], v[62:65]
	v_mfma_f32_16x16x32_bf16 v[58:61], v[154:157], v[162:165], v[58:61]
	v_mfma_f32_16x16x32_bf16 v[54:57], v[146:149], v[170:173], v[54:57]
	v_mfma_f32_16x16x32_bf16 v[50:53], v[154:157], v[170:173], v[50:53]
	v_mfma_f32_16x16x32_bf16 v[46:49], v[146:149], v[178:181], v[46:49]
	v_mfma_f32_16x16x32_bf16 v[42:45], v[154:157], v[178:181], v[42:45]
	v_mfma_f32_16x16x32_bf16 v[38:41], v[146:149], v[186:189], v[38:41]
	v_mfma_f32_16x16x32_bf16 v[34:37], v[154:157], v[186:189], v[34:37]
	v_mfma_f32_16x16x32_bf16 v[62:65], v[150:153], v[166:169], v[62:65]
	v_mfma_f32_16x16x32_bf16 v[58:61], v[158:161], v[166:169], v[58:61]
	v_mfma_f32_16x16x32_bf16 v[54:57], v[150:153], v[174:177], v[54:57]
	v_mfma_f32_16x16x32_bf16 v[50:53], v[158:161], v[174:177], v[50:53]
	v_mfma_f32_16x16x32_bf16 v[46:49], v[150:153], v[182:185], v[46:49]
	v_mfma_f32_16x16x32_bf16 v[42:45], v[158:161], v[182:185], v[42:45]
	v_mfma_f32_16x16x32_bf16 v[38:41], v[150:153], v[190:193], v[38:41]
	v_mfma_f32_16x16x32_bf16 v[34:37], v[158:161], v[190:193], v[34:37]
	s_barrier
	s_add_i32 s10, s81, s44
	v_lshl_add_u64 v[194:195], s[38:39], 0, v[222:223]
	s_mov_b32 m0, s10
	ds_read_b128 v[162:165], v244 offset:16384
	ds_read_b128 v[166:169], v244 offset:17408
	ds_read_b128 v[170:173], v244 offset:18432
	ds_read_b128 v[174:177], v244 offset:19456
	ds_read_b128 v[178:181], v244 offset:20480
	ds_read_b128 v[182:185], v244 offset:21504
	ds_read_b128 v[186:189], v244 offset:22528
	ds_read_b128 v[190:193], v244 offset:23552
	global_load_lds_dwordx4 v[194:195], off
	s_add_i32 m0, s10, 0x2000
	v_lshl_add_u64 v[196:197], s[38:39], 0, v[226:227]
	s_add_u32 s38, s38, s6
	s_addc_u32 s39, s39, s7
	s_add_i32 s10, s86, s44
	global_load_lds_dwordx4 v[196:197], off
	v_lshl_add_u64 v[198:199], s[38:39], 0, v[222:223]
	s_mov_b32 m0, s10
	v_lshl_add_u64 v[200:201], s[38:39], 0, v[226:227]
	global_load_lds_dwordx4 v[198:199], off
	s_add_i32 m0, s10, 0x2000
	v_lshl_add_u64 v[202:203], s[58:59], 0, v[220:221]
	global_load_lds_dwordx4 v[200:201], off
	s_mov_b32 m0, s45
	v_lshl_add_u64 v[204:205], s[58:59], 0, v[224:225]
	global_load_lds_dwordx4 v[202:203], off
	s_mov_b32 m0, s46
	s_nop 0
	global_load_lds_dwordx4 v[204:205], off
	s_waitcnt vmcnt(8)
	s_waitcnt lgkmcnt(0)
	s_barrier
	v_mfma_f32_16x16x32_bf16 v[94:97], v[130:133], v[162:165], v[94:97]
	v_mfma_f32_16x16x32_bf16 v[90:93], v[138:141], v[162:165], v[90:93]
	v_mfma_f32_16x16x32_bf16 v[86:89], v[130:133], v[170:173], v[86:89]
	v_mfma_f32_16x16x32_bf16 v[82:85], v[138:141], v[170:173], v[82:85]
	v_mfma_f32_16x16x32_bf16 v[78:81], v[130:133], v[178:181], v[78:81]
	v_mfma_f32_16x16x32_bf16 v[74:77], v[138:141], v[178:181], v[74:77]
	v_mfma_f32_16x16x32_bf16 v[70:73], v[130:133], v[186:189], v[70:73]
	v_mfma_f32_16x16x32_bf16 v[66:69], v[138:141], v[186:189], v[66:69]
	v_mfma_f32_16x16x32_bf16 v[94:97], v[134:137], v[166:169], v[94:97]
	v_mfma_f32_16x16x32_bf16 v[90:93], v[142:145], v[166:169], v[90:93]
	v_mfma_f32_16x16x32_bf16 v[86:89], v[134:137], v[174:177], v[86:89]
	v_mfma_f32_16x16x32_bf16 v[82:85], v[142:145], v[174:177], v[82:85]
	v_mfma_f32_16x16x32_bf16 v[78:81], v[134:137], v[182:185], v[78:81]
	v_mfma_f32_16x16x32_bf16 v[74:77], v[142:145], v[182:185], v[74:77]
	v_mfma_f32_16x16x32_bf16 v[70:73], v[134:137], v[190:193], v[70:73]
	v_mfma_f32_16x16x32_bf16 v[66:69], v[142:145], v[190:193], v[66:69]
	v_mfma_f32_16x16x32_bf16 v[30:33], v[146:149], v[162:165], v[30:33]
	v_mfma_f32_16x16x32_bf16 v[26:29], v[154:157], v[162:165], v[26:29]
	v_mfma_f32_16x16x32_bf16 v[22:25], v[146:149], v[170:173], v[22:25]
	v_mfma_f32_16x16x32_bf16 v[18:21], v[154:157], v[170:173], v[18:21]
	v_mfma_f32_16x16x32_bf16 v[14:17], v[146:149], v[178:181], v[14:17]
	v_mfma_f32_16x16x32_bf16 v[10:13], v[154:157], v[178:181], v[10:13]
	v_mfma_f32_16x16x32_bf16 v[6:9], v[146:149], v[186:189], v[6:9]
	v_mfma_f32_16x16x32_bf16 v[2:5], v[154:157], v[186:189], v[2:5]
	v_mfma_f32_16x16x32_bf16 v[30:33], v[150:153], v[166:169], v[30:33]
	v_mfma_f32_16x16x32_bf16 v[26:29], v[158:161], v[166:169], v[26:29]
	v_mfma_f32_16x16x32_bf16 v[22:25], v[150:153], v[174:177], v[22:25]
	v_mfma_f32_16x16x32_bf16 v[18:21], v[158:161], v[174:177], v[18:21]
	v_mfma_f32_16x16x32_bf16 v[14:17], v[150:153], v[182:185], v[14:17]
	v_mfma_f32_16x16x32_bf16 v[10:13], v[158:161], v[182:185], v[10:13]
	v_mfma_f32_16x16x32_bf16 v[6:9], v[150:153], v[190:193], v[6:9]
	v_mfma_f32_16x16x32_bf16 v[2:5], v[158:161], v[190:193], v[2:5]
	s_barrier
	s_add_i32 s10, 0, 0x18000
	s_add_i32 s20, 0, 0x1c000
	v_add_u32_e32 v142, s10, v241
	v_add_u32_e32 v158, s20, v241
	ds_read_b128 v[130:133], v142
	ds_read_b128 v[134:137], v142 offset:1024
	ds_read_b128 v[138:141], v142 offset:2048
	ds_read_b128 v[142:145], v142 offset:3072
	ds_read_b128 v[146:149], v158
	ds_read_b128 v[150:153], v158 offset:1024
	ds_read_b128 v[154:157], v158 offset:2048
	ds_read_b128 v[158:161], v158 offset:3072
	s_add_u32 s38, s58, s6
	s_addc_u32 s39, s59, s7
	s_mov_b32 m0, s47
	ds_read_b128 v[162:165], v244 offset:32768
	ds_read_b128 v[166:169], v244 offset:33792
	ds_read_b128 v[170:173], v244 offset:34816
	ds_read_b128 v[174:177], v244 offset:35840
	ds_read_b128 v[178:181], v244 offset:36864
	ds_read_b128 v[182:185], v244 offset:37888
	ds_read_b128 v[186:189], v244 offset:38912
	ds_read_b128 v[190:193], v244 offset:39936
	global_load_lds_dwordx4 v220, s[38:39]
	s_mov_b32 m0, s48
	s_nop 0
	global_load_lds_dwordx4 v224, s[38:39]
	s_waitcnt vmcnt(8)
	s_waitcnt lgkmcnt(0)
	s_barrier
	v_mfma_f32_16x16x32_bf16 v[126:129], v[130:133], v[162:165], v[126:129]
	v_mfma_f32_16x16x32_bf16 v[122:125], v[138:141], v[162:165], v[122:125]
	v_mfma_f32_16x16x32_bf16 v[118:121], v[130:133], v[170:173], v[118:121]
	v_mfma_f32_16x16x32_bf16 v[114:117], v[138:141], v[170:173], v[114:117]
	v_mfma_f32_16x16x32_bf16 v[110:113], v[130:133], v[178:181], v[110:113]
	v_mfma_f32_16x16x32_bf16 v[106:109], v[138:141], v[178:181], v[106:109]
	v_mfma_f32_16x16x32_bf16 v[102:105], v[130:133], v[186:189], v[102:105]
	v_mfma_f32_16x16x32_bf16 v[98:101], v[138:141], v[186:189], v[98:101]
	v_mfma_f32_16x16x32_bf16 v[126:129], v[134:137], v[166:169], v[126:129]
	v_mfma_f32_16x16x32_bf16 v[122:125], v[142:145], v[166:169], v[122:125]
	v_mfma_f32_16x16x32_bf16 v[118:121], v[134:137], v[174:177], v[118:121]
	v_mfma_f32_16x16x32_bf16 v[114:117], v[142:145], v[174:177], v[114:117]
	v_mfma_f32_16x16x32_bf16 v[110:113], v[134:137], v[182:185], v[110:113]
	v_mfma_f32_16x16x32_bf16 v[106:109], v[142:145], v[182:185], v[106:109]
	v_mfma_f32_16x16x32_bf16 v[102:105], v[134:137], v[190:193], v[102:105]
	v_mfma_f32_16x16x32_bf16 v[98:101], v[142:145], v[190:193], v[98:101]
	v_mfma_f32_16x16x32_bf16 v[62:65], v[146:149], v[162:165], v[62:65]
	v_mfma_f32_16x16x32_bf16 v[58:61], v[154:157], v[162:165], v[58:61]
	v_mfma_f32_16x16x32_bf16 v[54:57], v[146:149], v[170:173], v[54:57]
	v_mfma_f32_16x16x32_bf16 v[50:53], v[154:157], v[170:173], v[50:53]
	v_mfma_f32_16x16x32_bf16 v[46:49], v[146:149], v[178:181], v[46:49]
	v_mfma_f32_16x16x32_bf16 v[42:45], v[154:157], v[178:181], v[42:45]
	v_mfma_f32_16x16x32_bf16 v[38:41], v[146:149], v[186:189], v[38:41]
	v_mfma_f32_16x16x32_bf16 v[34:37], v[154:157], v[186:189], v[34:37]
	v_mfma_f32_16x16x32_bf16 v[62:65], v[150:153], v[166:169], v[62:65]
	v_mfma_f32_16x16x32_bf16 v[58:61], v[158:161], v[166:169], v[58:61]
	v_mfma_f32_16x16x32_bf16 v[54:57], v[150:153], v[174:177], v[54:57]
	v_mfma_f32_16x16x32_bf16 v[50:53], v[158:161], v[174:177], v[50:53]
	v_mfma_f32_16x16x32_bf16 v[46:49], v[150:153], v[182:185], v[46:49]
	v_mfma_f32_16x16x32_bf16 v[42:45], v[158:161], v[182:185], v[42:45]
	v_mfma_f32_16x16x32_bf16 v[38:41], v[150:153], v[190:193], v[38:41]
	v_mfma_f32_16x16x32_bf16 v[34:37], v[158:161], v[190:193], v[34:37]
	s_barrier
	s_add_i32 s10, s10, s44
	v_lshl_add_u64 v[194:195], v[194:195], 0, s[14:15]
	s_mov_b32 m0, s10
	ds_read_b128 v[162:165], v244 offset:49152
	ds_read_b128 v[166:169], v244 offset:50176
	ds_read_b128 v[170:173], v244 offset:51200
	ds_read_b128 v[174:177], v244 offset:52224
	ds_read_b128 v[178:181], v244 offset:53248
	ds_read_b128 v[182:185], v244 offset:54272
	ds_read_b128 v[186:189], v244 offset:55296
	ds_read_b128 v[190:193], v244 offset:56320
	global_load_lds_dwordx4 v[194:195], off
	v_lshl_add_u64 v[194:195], v[196:197], 0, s[14:15]
	s_add_i32 m0, s10, 0x2000
	s_add_i32 s10, s20, s44
	global_load_lds_dwordx4 v[194:195], off
	v_lshl_add_u64 v[194:195], v[198:199], 0, s[14:15]
	s_mov_b32 m0, s10
	s_nop 0
	global_load_lds_dwordx4 v[194:195], off
	v_lshl_add_u64 v[194:195], v[200:201], 0, s[14:15]
	s_add_i32 m0, s10, 0x2000
	s_nop 0
	global_load_lds_dwordx4 v[194:195], off
	v_lshl_add_u64 v[194:195], v[202:203], 0, s[14:15]
	s_mov_b32 m0, s50
	s_nop 0
	global_load_lds_dwordx4 v[194:195], off
	v_lshl_add_u64 v[194:195], v[204:205], 0, s[14:15]
	s_mov_b32 m0, s51
	s_nop 0
	global_load_lds_dwordx4 v[194:195], off
	s_waitcnt vmcnt(8)
	s_waitcnt lgkmcnt(0)
	s_barrier
	v_mfma_f32_16x16x32_bf16 v[94:97], v[130:133], v[162:165], v[94:97]
	v_mfma_f32_16x16x32_bf16 v[90:93], v[138:141], v[162:165], v[90:93]
	v_mfma_f32_16x16x32_bf16 v[86:89], v[130:133], v[170:173], v[86:89]
	v_mfma_f32_16x16x32_bf16 v[82:85], v[138:141], v[170:173], v[82:85]
	v_mfma_f32_16x16x32_bf16 v[78:81], v[130:133], v[178:181], v[78:81]
	v_mfma_f32_16x16x32_bf16 v[74:77], v[138:141], v[178:181], v[74:77]
	v_mfma_f32_16x16x32_bf16 v[70:73], v[130:133], v[186:189], v[70:73]
	v_mfma_f32_16x16x32_bf16 v[66:69], v[138:141], v[186:189], v[66:69]
	v_mfma_f32_16x16x32_bf16 v[94:97], v[134:137], v[166:169], v[94:97]
	v_mfma_f32_16x16x32_bf16 v[90:93], v[142:145], v[166:169], v[90:93]
	v_mfma_f32_16x16x32_bf16 v[86:89], v[134:137], v[174:177], v[86:89]
	v_mfma_f32_16x16x32_bf16 v[82:85], v[142:145], v[174:177], v[82:85]
	v_mfma_f32_16x16x32_bf16 v[78:81], v[134:137], v[182:185], v[78:81]
	v_mfma_f32_16x16x32_bf16 v[74:77], v[142:145], v[182:185], v[74:77]
	v_mfma_f32_16x16x32_bf16 v[70:73], v[134:137], v[190:193], v[70:73]
	v_mfma_f32_16x16x32_bf16 v[66:69], v[142:145], v[190:193], v[66:69]
	v_mfma_f32_16x16x32_bf16 v[30:33], v[146:149], v[162:165], v[30:33]
	v_mfma_f32_16x16x32_bf16 v[26:29], v[154:157], v[162:165], v[26:29]
	v_mfma_f32_16x16x32_bf16 v[22:25], v[146:149], v[170:173], v[22:25]
	v_mfma_f32_16x16x32_bf16 v[18:21], v[154:157], v[170:173], v[18:21]
	v_mfma_f32_16x16x32_bf16 v[14:17], v[146:149], v[178:181], v[14:17]
	v_mfma_f32_16x16x32_bf16 v[10:13], v[154:157], v[178:181], v[10:13]
	v_mfma_f32_16x16x32_bf16 v[6:9], v[146:149], v[186:189], v[6:9]
	v_mfma_f32_16x16x32_bf16 v[2:5], v[154:157], v[186:189], v[2:5]
	v_mfma_f32_16x16x32_bf16 v[30:33], v[150:153], v[166:169], v[30:33]
	v_mfma_f32_16x16x32_bf16 v[26:29], v[158:161], v[166:169], v[26:29]
	v_mfma_f32_16x16x32_bf16 v[22:25], v[150:153], v[174:177], v[22:25]
	v_mfma_f32_16x16x32_bf16 v[18:21], v[158:161], v[174:177], v[18:21]
	v_mfma_f32_16x16x32_bf16 v[14:17], v[150:153], v[182:185], v[14:17]
	v_mfma_f32_16x16x32_bf16 v[10:13], v[158:161], v[182:185], v[10:13]
	v_mfma_f32_16x16x32_bf16 v[6:9], v[150:153], v[190:193], v[6:9]
	v_mfma_f32_16x16x32_bf16 v[2:5], v[158:161], v[190:193], v[2:5]
	s_barrier
	s_add_u32 s56, s56, 0x100
	s_addc_u32 s57, s57, 0
	s_add_u32 s0, s0, 0x100
	s_addc_u32 s1, s1, 0
	s_cmp_ge_i32 s60, s49
	s_mov_b32 s10, s60
	s_cbranch_scc0 .LBB0_470
	v_mov_b64_e32 v[194:195], v[104:105]
	v_mov_b64_e32 v[172:173], v[64:65]
	v_mov_b64_e32 v[150:151], v[40:41]
	v_mov_b64_e32 v[196:197], v[100:101]
	v_mov_b64_e32 v[174:175], v[60:61]
	v_mov_b64_e32 v[152:153], v[36:37]
	v_mov_b64_e32 v[216:217], v[128:129]
	v_mov_b64_e32 v[210:211], v[120:121]
	v_mov_b64_e32 v[204:205], v[112:113]
	v_mov_b64_e32 v[166:167], v[56:57]
	v_mov_b64_e32 v[160:161], v[48:49]
	v_mov_b64_e32 v[198:199], v[96:97]
	v_mov_b64_e32 v[188:189], v[88:89]
	v_mov_b64_e32 v[182:183], v[80:81]
	v_mov_b64_e32 v[176:177], v[72:73]
	v_mov_b64_e32 v[154:155], v[32:33]
	v_mov_b64_e32 v[144:145], v[24:25]
	v_mov_b64_e32 v[138:139], v[16:17]
	v_mov_b64_e32 v[132:133], v[8:9]
	v_mov_b64_e32 v[218:219], v[124:125]
	v_mov_b64_e32 v[212:213], v[116:117]
	v_mov_b64_e32 v[206:207], v[108:109]
	v_mov_b64_e32 v[168:169], v[52:53]
	v_mov_b64_e32 v[162:163], v[44:45]
	v_mov_b64_e32 v[200:201], v[92:93]
	v_mov_b64_e32 v[190:191], v[84:85]
	v_mov_b64_e32 v[184:185], v[76:77]
	v_mov_b64_e32 v[178:179], v[68:69]
	v_mov_b64_e32 v[156:157], v[28:29]
	v_mov_b64_e32 v[146:147], v[20:21]
	v_mov_b64_e32 v[140:141], v[12:13]
	v_mov_b64_e32 v[134:135], v[4:5]
	v_mov_b64_e32 v[214:215], v[126:127]
	v_mov_b64_e32 v[216:217], v[122:123]
	v_mov_b64_e32 v[208:209], v[118:119]
	v_mov_b64_e32 v[210:211], v[114:115]
	v_mov_b64_e32 v[202:203], v[110:111]
	v_mov_b64_e32 v[204:205], v[106:107]
	v_mov_b64_e32 v[192:193], v[102:103]
	v_mov_b64_e32 v[194:195], v[98:99]
	v_mov_b64_e32 v[170:171], v[62:63]
	v_mov_b64_e32 v[172:173], v[58:59]
	v_mov_b64_e32 v[164:165], v[54:55]
	v_mov_b64_e32 v[166:167], v[50:51]
	v_mov_b64_e32 v[158:159], v[46:47]
	v_mov_b64_e32 v[160:161], v[42:43]
	v_mov_b64_e32 v[148:149], v[38:39]
	v_mov_b64_e32 v[150:151], v[34:35]
	v_mov_b64_e32 v[196:197], v[94:95]
	v_mov_b64_e32 v[198:199], v[90:91]
	v_mov_b64_e32 v[186:187], v[86:87]
	v_mov_b64_e32 v[188:189], v[82:83]
	v_mov_b64_e32 v[180:181], v[78:79]
	v_mov_b64_e32 v[182:183], v[74:75]
	v_mov_b64_e32 v[174:175], v[70:71]
	v_mov_b64_e32 v[176:177], v[66:67]
	v_mov_b64_e32 v[152:153], v[30:31]
	v_mov_b64_e32 v[154:155], v[26:27]
	v_mov_b64_e32 v[142:143], v[22:23]
	v_mov_b64_e32 v[144:145], v[18:19]
	v_mov_b64_e32 v[136:137], v[14:15]
	v_mov_b64_e32 v[138:139], v[10:11]
	v_mov_b64_e32 v[130:131], v[6:7]
	v_mov_b64_e32 v[132:133], v[2:3]

.LBB0_838:
	ds_read_b128 v[154:157], v150
	ds_read_b128 v[158:161], v150 offset:1024
	ds_read_b128 v[162:165], v150 offset:2048
	ds_read_b128 v[166:169], v150 offset:3072
	ds_read_b128 v[170:173], v151
	ds_read_b128 v[174:177], v151 offset:1024
	ds_read_b128 v[178:181], v151 offset:2048
	ds_read_b128 v[182:185], v151 offset:3072
	s_add_u32 s20, s52, 0xfffc0080
	s_addc_u32 s35, s53, -1
	s_cmp_eq_u32 s65, 12
	s_cselect_b32 s57, s0, s35
	s_cselect_b32 s56, s1, s20
	s_cselect_b32 s55, s11, s64
	s_cselect_b32 s54, s13, s63
	s_add_i32 m0, s19, 0xc000
	ds_read_b128 v[186:189], v152
	ds_read_b128 v[190:193], v152 offset:1024
	ds_read_b128 v[194:197], v152 offset:2048
	ds_read_b128 v[198:201], v152 offset:3072
	ds_read_b128 v[202:205], v152 offset:4096
	ds_read_b128 v[206:209], v152 offset:5120
	ds_read_b128 v[210:213], v152 offset:6144
	ds_read_b128 v[214:217], v152 offset:7168
	global_load_lds_dwordx4 v136, s[52:53]
	s_add_i32 m0, s19, 0xe000
	s_nop 0
	global_load_lds_dwordx4 v138, s[52:53]
	s_waitcnt vmcnt(8)
	s_waitcnt lgkmcnt(0)
	s_barrier
	v_mfma_f32_16x16x32_bf16 v[124:127], v[154:157], v[186:189], v[124:127]
	v_mfma_f32_16x16x32_bf16 v[120:123], v[162:165], v[186:189], v[120:123]
	v_mfma_f32_16x16x32_bf16 v[112:115], v[154:157], v[194:197], v[112:115]
	v_mfma_f32_16x16x32_bf16 v[104:107], v[162:165], v[194:197], v[104:107]
	v_mfma_f32_16x16x32_bf16 v[96:99], v[154:157], v[202:205], v[96:99]
	v_mfma_f32_16x16x32_bf16 v[88:91], v[162:165], v[202:205], v[88:91]
	v_mfma_f32_16x16x32_bf16 v[80:83], v[154:157], v[210:213], v[80:83]
	v_mfma_f32_16x16x32_bf16 v[72:75], v[162:165], v[210:213], v[72:75]
	v_mfma_f32_16x16x32_bf16 v[124:127], v[158:161], v[190:193], v[124:127]
	v_mfma_f32_16x16x32_bf16 v[120:123], v[166:169], v[190:193], v[120:123]
	v_mfma_f32_16x16x32_bf16 v[112:115], v[158:161], v[198:201], v[112:115]
	v_mfma_f32_16x16x32_bf16 v[104:107], v[166:169], v[198:201], v[104:107]
	v_mfma_f32_16x16x32_bf16 v[96:99], v[158:161], v[206:209], v[96:99]
	v_mfma_f32_16x16x32_bf16 v[88:91], v[166:169], v[206:209], v[88:91]
	v_mfma_f32_16x16x32_bf16 v[80:83], v[158:161], v[214:217], v[80:83]
	v_mfma_f32_16x16x32_bf16 v[72:75], v[166:169], v[214:217], v[72:75]
	v_mfma_f32_16x16x32_bf16 v[116:119], v[170:173], v[186:189], v[116:119]
	v_mfma_f32_16x16x32_bf16 v[108:111], v[178:181], v[186:189], v[108:111]
	v_mfma_f32_16x16x32_bf16 v[100:103], v[170:173], v[194:197], v[100:103]
	v_mfma_f32_16x16x32_bf16 v[92:95], v[178:181], v[194:197], v[92:95]
	v_mfma_f32_16x16x32_bf16 v[84:87], v[170:173], v[202:205], v[84:87]
	v_mfma_f32_16x16x32_bf16 v[76:79], v[178:181], v[202:205], v[76:79]
	v_mfma_f32_16x16x32_bf16 v[68:71], v[170:173], v[210:213], v[68:71]
	v_mfma_f32_16x16x32_bf16 v[64:67], v[178:181], v[210:213], v[64:67]
	v_mfma_f32_16x16x32_bf16 v[116:119], v[174:177], v[190:193], v[116:119]
	v_mfma_f32_16x16x32_bf16 v[108:111], v[182:185], v[190:193], v[108:111]
	v_mfma_f32_16x16x32_bf16 v[100:103], v[174:177], v[198:201], v[100:103]
	v_mfma_f32_16x16x32_bf16 v[92:95], v[182:185], v[198:201], v[92:95]
	v_mfma_f32_16x16x32_bf16 v[84:87], v[174:177], v[206:209], v[84:87]
	v_mfma_f32_16x16x32_bf16 v[76:79], v[182:185], v[206:209], v[76:79]
	v_mfma_f32_16x16x32_bf16 v[68:71], v[174:177], v[214:217], v[68:71]
	v_mfma_f32_16x16x32_bf16 v[64:67], v[182:185], v[214:217], v[64:67]
	s_barrier
	s_add_i32 s20, s60, s45
	v_lshl_add_u64 v[144:145], s[54:55], 0, v[130:131]
	s_mov_b32 m0, s20
	ds_read_b128 v[186:189], v152 offset:16384
	ds_read_b128 v[190:193], v152 offset:17408
	ds_read_b128 v[194:197], v152 offset:18432
	ds_read_b128 v[198:201], v152 offset:19456
	ds_read_b128 v[202:205], v152 offset:20480
	ds_read_b128 v[206:209], v152 offset:21504
	ds_read_b128 v[210:213], v152 offset:22528
	ds_read_b128 v[214:217], v152 offset:23552
	global_load_lds_dwordx4 v[144:145], off
	s_add_i32 m0, s20, 0x2000
	s_add_u32 s38, s54, 0x40000
	v_lshl_add_u64 v[218:219], s[54:55], 0, v[134:135]
	s_addc_u32 s39, s55, 0
	s_add_i32 s20, s61, s45
	global_load_lds_dwordx4 v[218:219], off
	s_mov_b32 m0, s20
	v_lshl_add_u64 v[222:223], s[56:57], 0, v[132:133]
	global_load_lds_dwordx4 v130, s[38:39]
	s_add_i32 m0, s20, 0x2000
	s_nop 0
	global_load_lds_dwordx4 v134, s[38:39]
	v_lshl_add_u64 v[220:221], s[56:57], 0, v[128:129]
	s_mov_b32 m0, s19
	s_nop 0
	global_load_lds_dwordx4 v[220:221], off
	s_mov_b32 m0, s46
	s_nop 0
	global_load_lds_dwordx4 v[222:223], off
	s_waitcnt vmcnt(8)
	s_waitcnt lgkmcnt(0)
	s_barrier
	v_mfma_f32_16x16x32_bf16 v[60:63], v[154:157], v[186:189], v[60:63]
	v_mfma_f32_16x16x32_bf16 v[56:59], v[162:165], v[186:189], v[56:59]
	v_mfma_f32_16x16x32_bf16 v[48:51], v[154:157], v[194:197], v[48:51]
	v_mfma_f32_16x16x32_bf16 v[40:43], v[162:165], v[194:197], v[40:43]
	v_mfma_f32_16x16x32_bf16 v[32:35], v[154:157], v[202:205], v[32:35]
	v_mfma_f32_16x16x32_bf16 v[24:27], v[162:165], v[202:205], v[24:27]
	v_mfma_f32_16x16x32_bf16 v[16:19], v[154:157], v[210:213], v[16:19]
	v_mfma_f32_16x16x32_bf16 v[8:11], v[162:165], v[210:213], v[8:11]
	v_mfma_f32_16x16x32_bf16 v[60:63], v[158:161], v[190:193], v[60:63]
	v_mfma_f32_16x16x32_bf16 v[56:59], v[166:169], v[190:193], v[56:59]
	v_mfma_f32_16x16x32_bf16 v[48:51], v[158:161], v[198:201], v[48:51]
	v_mfma_f32_16x16x32_bf16 v[40:43], v[166:169], v[198:201], v[40:43]
	v_mfma_f32_16x16x32_bf16 v[32:35], v[158:161], v[206:209], v[32:35]
	v_mfma_f32_16x16x32_bf16 v[24:27], v[166:169], v[206:209], v[24:27]
	v_mfma_f32_16x16x32_bf16 v[16:19], v[158:161], v[214:217], v[16:19]
	v_mfma_f32_16x16x32_bf16 v[8:11], v[166:169], v[214:217], v[8:11]
	v_mfma_f32_16x16x32_bf16 v[52:55], v[170:173], v[186:189], v[52:55]
	v_mfma_f32_16x16x32_bf16 v[44:47], v[178:181], v[186:189], v[44:47]
	v_mfma_f32_16x16x32_bf16 v[36:39], v[170:173], v[194:197], v[36:39]
	v_mfma_f32_16x16x32_bf16 v[28:31], v[178:181], v[194:197], v[28:31]
	v_mfma_f32_16x16x32_bf16 v[20:23], v[170:173], v[202:205], v[20:23]
	v_mfma_f32_16x16x32_bf16 v[12:15], v[178:181], v[202:205], v[12:15]
	v_mfma_f32_16x16x32_bf16 v[4:7], v[170:173], v[210:213], v[4:7]
	v_mfma_f32_16x16x32_bf16 v[0:3], v[178:181], v[210:213], v[0:3]
	v_mfma_f32_16x16x32_bf16 v[52:55], v[174:177], v[190:193], v[52:55]
	v_mfma_f32_16x16x32_bf16 v[44:47], v[182:185], v[190:193], v[44:47]
	v_mfma_f32_16x16x32_bf16 v[36:39], v[174:177], v[198:201], v[36:39]
	v_mfma_f32_16x16x32_bf16 v[28:31], v[182:185], v[198:201], v[28:31]
	v_mfma_f32_16x16x32_bf16 v[20:23], v[174:177], v[206:209], v[20:23]
	v_mfma_f32_16x16x32_bf16 v[12:15], v[182:185], v[206:209], v[12:15]
	v_mfma_f32_16x16x32_bf16 v[4:7], v[174:177], v[214:217], v[4:7]
	v_mfma_f32_16x16x32_bf16 v[0:3], v[182:185], v[214:217], v[0:3]
	s_barrier
	s_add_i32 s20, 0, 0x18000
	v_add_u32_e32 v153, s20, v148
	s_add_i32 s35, 0, 0x1c000
	ds_read_b128 v[154:157], v153
	ds_read_b128 v[158:161], v153 offset:1024
	ds_read_b128 v[162:165], v153 offset:2048
	ds_read_b128 v[166:169], v153 offset:3072
	v_add_u32_e32 v153, s35, v148
	ds_read_b128 v[170:173], v153
	ds_read_b128 v[174:177], v153 offset:1024
	ds_read_b128 v[178:181], v153 offset:2048
	ds_read_b128 v[182:185], v153 offset:3072
	s_add_u32 s38, s56, 0x40000
	s_addc_u32 s39, s57, 0
	s_mov_b32 m0, s47
	ds_read_b128 v[186:189], v152 offset:32768
	ds_read_b128 v[190:193], v152 offset:33792
	ds_read_b128 v[194:197], v152 offset:34816
	ds_read_b128 v[198:201], v152 offset:35840
	ds_read_b128 v[202:205], v152 offset:36864
	ds_read_b128 v[206:209], v152 offset:37888
	ds_read_b128 v[210:213], v152 offset:38912
	ds_read_b128 v[214:217], v152 offset:39936
	global_load_lds_dwordx4 v128, s[38:39]
	s_mov_b32 m0, s48
	s_nop 0
	global_load_lds_dwordx4 v132, s[38:39]
	s_waitcnt vmcnt(8)
	s_waitcnt lgkmcnt(0)
	s_barrier
	v_mfma_f32_16x16x32_bf16 v[124:127], v[154:157], v[186:189], v[124:127]
	v_mfma_f32_16x16x32_bf16 v[120:123], v[162:165], v[186:189], v[120:123]
	v_mfma_f32_16x16x32_bf16 v[112:115], v[154:157], v[194:197], v[112:115]
	v_mfma_f32_16x16x32_bf16 v[104:107], v[162:165], v[194:197], v[104:107]
	v_mfma_f32_16x16x32_bf16 v[96:99], v[154:157], v[202:205], v[96:99]
	v_mfma_f32_16x16x32_bf16 v[88:91], v[162:165], v[202:205], v[88:91]
	v_mfma_f32_16x16x32_bf16 v[80:83], v[154:157], v[210:213], v[80:83]
	v_mfma_f32_16x16x32_bf16 v[72:75], v[162:165], v[210:213], v[72:75]
	v_mfma_f32_16x16x32_bf16 v[124:127], v[158:161], v[190:193], v[124:127]
	v_mfma_f32_16x16x32_bf16 v[120:123], v[166:169], v[190:193], v[120:123]
	v_mfma_f32_16x16x32_bf16 v[112:115], v[158:161], v[198:201], v[112:115]
	v_mfma_f32_16x16x32_bf16 v[104:107], v[166:169], v[198:201], v[104:107]
	v_mfma_f32_16x16x32_bf16 v[96:99], v[158:161], v[206:209], v[96:99]
	v_mfma_f32_16x16x32_bf16 v[88:91], v[166:169], v[206:209], v[88:91]
	v_mfma_f32_16x16x32_bf16 v[80:83], v[158:161], v[214:217], v[80:83]
	v_mfma_f32_16x16x32_bf16 v[72:75], v[166:169], v[214:217], v[72:75]
	v_mfma_f32_16x16x32_bf16 v[116:119], v[170:173], v[186:189], v[116:119]
	v_mfma_f32_16x16x32_bf16 v[108:111], v[178:181], v[186:189], v[108:111]
	v_mfma_f32_16x16x32_bf16 v[100:103], v[170:173], v[194:197], v[100:103]
	v_mfma_f32_16x16x32_bf16 v[92:95], v[178:181], v[194:197], v[92:95]
	v_mfma_f32_16x16x32_bf16 v[84:87], v[170:173], v[202:205], v[84:87]
	v_mfma_f32_16x16x32_bf16 v[76:79], v[178:181], v[202:205], v[76:79]
	v_mfma_f32_16x16x32_bf16 v[68:71], v[170:173], v[210:213], v[68:71]
	v_mfma_f32_16x16x32_bf16 v[64:67], v[178:181], v[210:213], v[64:67]
	v_mfma_f32_16x16x32_bf16 v[116:119], v[174:177], v[190:193], v[116:119]
	v_mfma_f32_16x16x32_bf16 v[108:111], v[182:185], v[190:193], v[108:111]
	v_mfma_f32_16x16x32_bf16 v[100:103], v[174:177], v[198:201], v[100:103]
	v_mfma_f32_16x16x32_bf16 v[92:95], v[182:185], v[198:201], v[92:95]
	v_mfma_f32_16x16x32_bf16 v[84:87], v[174:177], v[206:209], v[84:87]
	v_mfma_f32_16x16x32_bf16 v[76:79], v[182:185], v[206:209], v[76:79]
	v_mfma_f32_16x16x32_bf16 v[68:71], v[174:177], v[214:217], v[68:71]
	v_mfma_f32_16x16x32_bf16 v[64:67], v[182:185], v[214:217], v[64:67]
	s_barrier
	s_add_i32 s20, s20, s45
	v_lshl_add_u64 v[144:145], v[144:145], 0, s[6:7]
	s_mov_b32 m0, s20
	ds_read_b128 v[186:189], v152 offset:49152
	ds_read_b128 v[190:193], v152 offset:50176
	ds_read_b128 v[194:197], v152 offset:51200
	ds_read_b128 v[198:201], v152 offset:52224
	ds_read_b128 v[202:205], v152 offset:53248
	ds_read_b128 v[206:209], v152 offset:54272
	ds_read_b128 v[210:213], v152 offset:55296
	ds_read_b128 v[214:217], v152 offset:56320
	global_load_lds_dwordx4 v[144:145], off
	s_add_i32 m0, s20, 0x2000
	s_add_u32 s38, s54, 0x40080
	v_lshl_add_u64 v[144:145], v[218:219], 0, s[6:7]
	s_addc_u32 s39, s55, 0
	s_add_i32 s20, s35, s45
	global_load_lds_dwordx4 v[144:145], off
	s_mov_b32 m0, s20
	s_nop 0
	global_load_lds_dwordx4 v130, s[38:39]
	s_add_i32 m0, s20, 0x2000
	s_nop 0
	global_load_lds_dwordx4 v134, s[38:39]
	v_lshl_add_u64 v[144:145], v[220:221], 0, s[6:7]
	s_mov_b32 m0, s50
	s_nop 0
	global_load_lds_dwordx4 v[144:145], off
	v_lshl_add_u64 v[144:145], v[222:223], 0, s[6:7]
	s_mov_b32 m0, s51
	s_nop 0
	global_load_lds_dwordx4 v[144:145], off
	s_waitcnt vmcnt(8)
	s_waitcnt lgkmcnt(0)
	s_barrier
	v_mfma_f32_16x16x32_bf16 v[60:63], v[154:157], v[186:189], v[60:63]
	v_mfma_f32_16x16x32_bf16 v[56:59], v[162:165], v[186:189], v[56:59]
	v_mfma_f32_16x16x32_bf16 v[48:51], v[154:157], v[194:197], v[48:51]
	v_mfma_f32_16x16x32_bf16 v[40:43], v[162:165], v[194:197], v[40:43]
	v_mfma_f32_16x16x32_bf16 v[32:35], v[154:157], v[202:205], v[32:35]
	v_mfma_f32_16x16x32_bf16 v[24:27], v[162:165], v[202:205], v[24:27]
	v_mfma_f32_16x16x32_bf16 v[16:19], v[154:157], v[210:213], v[16:19]
	v_mfma_f32_16x16x32_bf16 v[8:11], v[162:165], v[210:213], v[8:11]
	v_mfma_f32_16x16x32_bf16 v[60:63], v[158:161], v[190:193], v[60:63]
	v_mfma_f32_16x16x32_bf16 v[56:59], v[166:169], v[190:193], v[56:59]
	v_mfma_f32_16x16x32_bf16 v[48:51], v[158:161], v[198:201], v[48:51]
	v_mfma_f32_16x16x32_bf16 v[40:43], v[166:169], v[198:201], v[40:43]
	v_mfma_f32_16x16x32_bf16 v[32:35], v[158:161], v[206:209], v[32:35]
	v_mfma_f32_16x16x32_bf16 v[24:27], v[166:169], v[206:209], v[24:27]
	v_mfma_f32_16x16x32_bf16 v[16:19], v[158:161], v[214:217], v[16:19]
	v_mfma_f32_16x16x32_bf16 v[8:11], v[166:169], v[214:217], v[8:11]
	v_mfma_f32_16x16x32_bf16 v[52:55], v[170:173], v[186:189], v[52:55]
	v_mfma_f32_16x16x32_bf16 v[44:47], v[178:181], v[186:189], v[44:47]
	v_mfma_f32_16x16x32_bf16 v[36:39], v[170:173], v[194:197], v[36:39]
	v_mfma_f32_16x16x32_bf16 v[28:31], v[178:181], v[194:197], v[28:31]
	v_mfma_f32_16x16x32_bf16 v[20:23], v[170:173], v[202:205], v[20:23]
	v_mfma_f32_16x16x32_bf16 v[12:15], v[178:181], v[202:205], v[12:15]
	v_mfma_f32_16x16x32_bf16 v[4:7], v[170:173], v[210:213], v[4:7]
	v_mfma_f32_16x16x32_bf16 v[0:3], v[178:181], v[210:213], v[0:3]
	v_mfma_f32_16x16x32_bf16 v[52:55], v[174:177], v[190:193], v[52:55]
	v_mfma_f32_16x16x32_bf16 v[44:47], v[182:185], v[190:193], v[44:47]
	v_mfma_f32_16x16x32_bf16 v[36:39], v[174:177], v[198:201], v[36:39]
	v_mfma_f32_16x16x32_bf16 v[28:31], v[182:185], v[198:201], v[28:31]
	v_mfma_f32_16x16x32_bf16 v[20:23], v[174:177], v[206:209], v[20:23]
	v_mfma_f32_16x16x32_bf16 v[12:15], v[182:185], v[206:209], v[12:15]
	v_mfma_f32_16x16x32_bf16 v[4:7], v[174:177], v[214:217], v[4:7]
	v_mfma_f32_16x16x32_bf16 v[0:3], v[182:185], v[214:217], v[0:3]
	s_barrier
	s_add_i32 s65, s65, 2
	s_add_u32 s52, s52, 0x100
	s_addc_u32 s53, s53, 0
	s_add_u32 s63, s63, 0x100
	s_addc_u32 s64, s64, 0
	s_cmp_gt_u32 s65, 13
	s_cbranch_scc0 .LBB0_838
	s_and_b64 vcc, exec, s[8:9]
	s_cbranch_vccz .LBB0_841
	s_barrier

.LBB0_968:
	ds_read_b128 v[154:157], v150
	ds_read_b128 v[158:161], v150 offset:1024
	ds_read_b128 v[162:165], v150 offset:2048
	ds_read_b128 v[166:169], v150 offset:3072
	ds_read_b128 v[170:173], v151
	ds_read_b128 v[174:177], v151 offset:1024
	ds_read_b128 v[178:181], v151 offset:2048
	ds_read_b128 v[182:185], v151 offset:3072
	s_add_u32 s20, s52, 0xfffc0080
	s_addc_u32 s35, s53, -1
	s_cmp_eq_u32 s67, 12
	s_cselect_b32 s57, s0, s35
	s_cselect_b32 s56, s1, s20
	s_cselect_b32 s55, s11, s66
	s_cselect_b32 s54, s13, s65
	s_add_i32 m0, s19, 0xc000
	ds_read_b128 v[186:189], v152
	ds_read_b128 v[190:193], v152 offset:1024
	ds_read_b128 v[194:197], v152 offset:2048
	ds_read_b128 v[198:201], v152 offset:3072
	ds_read_b128 v[202:205], v152 offset:4096
	ds_read_b128 v[206:209], v152 offset:5120
	ds_read_b128 v[210:213], v152 offset:6144
	ds_read_b128 v[214:217], v152 offset:7168
	global_load_lds_dwordx4 v136, s[52:53]
	s_add_i32 m0, s19, 0xe000
	s_nop 0
	global_load_lds_dwordx4 v138, s[52:53]
	s_waitcnt vmcnt(8)
	s_waitcnt lgkmcnt(0)
	s_barrier
	v_mfma_f32_16x16x32_bf16 v[124:127], v[154:157], v[186:189], v[124:127]
	v_mfma_f32_16x16x32_bf16 v[120:123], v[162:165], v[186:189], v[120:123]
	v_mfma_f32_16x16x32_bf16 v[108:111], v[154:157], v[194:197], v[108:111]
	v_mfma_f32_16x16x32_bf16 v[104:107], v[162:165], v[194:197], v[104:107]
	v_mfma_f32_16x16x32_bf16 v[92:95], v[154:157], v[202:205], v[92:95]
	v_mfma_f32_16x16x32_bf16 v[88:91], v[162:165], v[202:205], v[88:91]
	v_mfma_f32_16x16x32_bf16 v[76:79], v[154:157], v[210:213], v[76:79]
	v_mfma_f32_16x16x32_bf16 v[72:75], v[162:165], v[210:213], v[72:75]
	v_mfma_f32_16x16x32_bf16 v[124:127], v[158:161], v[190:193], v[124:127]
	v_mfma_f32_16x16x32_bf16 v[120:123], v[166:169], v[190:193], v[120:123]
	v_mfma_f32_16x16x32_bf16 v[108:111], v[158:161], v[198:201], v[108:111]
	v_mfma_f32_16x16x32_bf16 v[104:107], v[166:169], v[198:201], v[104:107]
	v_mfma_f32_16x16x32_bf16 v[92:95], v[158:161], v[206:209], v[92:95]
	v_mfma_f32_16x16x32_bf16 v[88:91], v[166:169], v[206:209], v[88:91]
	v_mfma_f32_16x16x32_bf16 v[76:79], v[158:161], v[214:217], v[76:79]
	v_mfma_f32_16x16x32_bf16 v[72:75], v[166:169], v[214:217], v[72:75]
	v_mfma_f32_16x16x32_bf16 v[116:119], v[170:173], v[186:189], v[116:119]
	v_mfma_f32_16x16x32_bf16 v[112:115], v[178:181], v[186:189], v[112:115]
	v_mfma_f32_16x16x32_bf16 v[100:103], v[170:173], v[194:197], v[100:103]
	v_mfma_f32_16x16x32_bf16 v[96:99], v[178:181], v[194:197], v[96:99]
	v_mfma_f32_16x16x32_bf16 v[84:87], v[170:173], v[202:205], v[84:87]
	v_mfma_f32_16x16x32_bf16 v[80:83], v[178:181], v[202:205], v[80:83]
	v_mfma_f32_16x16x32_bf16 v[68:71], v[170:173], v[210:213], v[68:71]
	v_mfma_f32_16x16x32_bf16 v[64:67], v[178:181], v[210:213], v[64:67]
	v_mfma_f32_16x16x32_bf16 v[116:119], v[174:177], v[190:193], v[116:119]
	v_mfma_f32_16x16x32_bf16 v[112:115], v[182:185], v[190:193], v[112:115]
	v_mfma_f32_16x16x32_bf16 v[100:103], v[174:177], v[198:201], v[100:103]
	v_mfma_f32_16x16x32_bf16 v[96:99], v[182:185], v[198:201], v[96:99]
	v_mfma_f32_16x16x32_bf16 v[84:87], v[174:177], v[206:209], v[84:87]
	v_mfma_f32_16x16x32_bf16 v[80:83], v[182:185], v[206:209], v[80:83]
	v_mfma_f32_16x16x32_bf16 v[68:71], v[174:177], v[214:217], v[68:71]
	v_mfma_f32_16x16x32_bf16 v[64:67], v[182:185], v[214:217], v[64:67]
	s_barrier
	s_add_i32 s20, s61, s44
	v_lshl_add_u64 v[144:145], s[54:55], 0, v[128:129]
	s_mov_b32 m0, s20
	ds_read_b128 v[186:189], v152 offset:16384
	ds_read_b128 v[190:193], v152 offset:17408
	ds_read_b128 v[194:197], v152 offset:18432
	ds_read_b128 v[198:201], v152 offset:19456
	ds_read_b128 v[202:205], v152 offset:20480
	ds_read_b128 v[206:209], v152 offset:21504
	ds_read_b128 v[210:213], v152 offset:22528
	ds_read_b128 v[214:217], v152 offset:23552
	global_load_lds_dwordx4 v[144:145], off
	s_add_i32 m0, s20, 0x2000
	s_add_u32 s38, s54, 0x40000
	v_lshl_add_u64 v[218:219], s[54:55], 0, v[130:131]
	s_addc_u32 s39, s55, 0
	s_add_i32 s20, s62, s44
	global_load_lds_dwordx4 v[218:219], off
	s_mov_b32 m0, s20
	v_lshl_add_u64 v[222:223], s[56:57], 0, v[132:133]
	global_load_lds_dwordx4 v128, s[38:39]
	s_add_i32 m0, s20, 0x2000
	s_nop 0
	global_load_lds_dwordx4 v130, s[38:39]
	v_lshl_add_u64 v[220:221], s[56:57], 0, v[134:135]
	s_mov_b32 m0, s19
	s_nop 0
	global_load_lds_dwordx4 v[220:221], off
	s_mov_b32 m0, s47
	s_nop 0
	global_load_lds_dwordx4 v[222:223], off
	s_waitcnt vmcnt(8)
	s_waitcnt lgkmcnt(0)
	s_barrier
	v_mfma_f32_16x16x32_bf16 v[60:63], v[154:157], v[186:189], v[60:63]
	v_mfma_f32_16x16x32_bf16 v[56:59], v[162:165], v[186:189], v[56:59]
	v_mfma_f32_16x16x32_bf16 v[44:47], v[154:157], v[194:197], v[44:47]
	v_mfma_f32_16x16x32_bf16 v[40:43], v[162:165], v[194:197], v[40:43]
	v_mfma_f32_16x16x32_bf16 v[28:31], v[154:157], v[202:205], v[28:31]
	v_mfma_f32_16x16x32_bf16 v[24:27], v[162:165], v[202:205], v[24:27]
	v_mfma_f32_16x16x32_bf16 v[12:15], v[154:157], v[210:213], v[12:15]
	v_mfma_f32_16x16x32_bf16 v[8:11], v[162:165], v[210:213], v[8:11]
	v_mfma_f32_16x16x32_bf16 v[60:63], v[158:161], v[190:193], v[60:63]
	v_mfma_f32_16x16x32_bf16 v[56:59], v[166:169], v[190:193], v[56:59]
	v_mfma_f32_16x16x32_bf16 v[44:47], v[158:161], v[198:201], v[44:47]
	v_mfma_f32_16x16x32_bf16 v[40:43], v[166:169], v[198:201], v[40:43]
	v_mfma_f32_16x16x32_bf16 v[28:31], v[158:161], v[206:209], v[28:31]
	v_mfma_f32_16x16x32_bf16 v[24:27], v[166:169], v[206:209], v[24:27]
	v_mfma_f32_16x16x32_bf16 v[12:15], v[158:161], v[214:217], v[12:15]
	v_mfma_f32_16x16x32_bf16 v[8:11], v[166:169], v[214:217], v[8:11]
	v_mfma_f32_16x16x32_bf16 v[52:55], v[170:173], v[186:189], v[52:55]
	v_mfma_f32_16x16x32_bf16 v[48:51], v[178:181], v[186:189], v[48:51]
	v_mfma_f32_16x16x32_bf16 v[36:39], v[170:173], v[194:197], v[36:39]
	v_mfma_f32_16x16x32_bf16 v[32:35], v[178:181], v[194:197], v[32:35]
	v_mfma_f32_16x16x32_bf16 v[20:23], v[170:173], v[202:205], v[20:23]
	v_mfma_f32_16x16x32_bf16 v[16:19], v[178:181], v[202:205], v[16:19]
	v_mfma_f32_16x16x32_bf16 v[4:7], v[170:173], v[210:213], v[4:7]
	v_mfma_f32_16x16x32_bf16 v[0:3], v[178:181], v[210:213], v[0:3]
	v_mfma_f32_16x16x32_bf16 v[52:55], v[174:177], v[190:193], v[52:55]
	v_mfma_f32_16x16x32_bf16 v[48:51], v[182:185], v[190:193], v[48:51]
	v_mfma_f32_16x16x32_bf16 v[36:39], v[174:177], v[198:201], v[36:39]
	v_mfma_f32_16x16x32_bf16 v[32:35], v[182:185], v[198:201], v[32:35]
	v_mfma_f32_16x16x32_bf16 v[20:23], v[174:177], v[206:209], v[20:23]
	v_mfma_f32_16x16x32_bf16 v[16:19], v[182:185], v[206:209], v[16:19]
	v_mfma_f32_16x16x32_bf16 v[4:7], v[174:177], v[214:217], v[4:7]
	v_mfma_f32_16x16x32_bf16 v[0:3], v[182:185], v[214:217], v[0:3]
	s_barrier
	s_add_i32 s20, 0, 0x18000
	v_add_u32_e32 v153, s20, v148
	s_add_i32 s35, 0, 0x1c000
	ds_read_b128 v[154:157], v153
	ds_read_b128 v[158:161], v153 offset:1024
	ds_read_b128 v[162:165], v153 offset:2048
	ds_read_b128 v[166:169], v153 offset:3072
	v_add_u32_e32 v153, s35, v148
	ds_read_b128 v[170:173], v153
	ds_read_b128 v[174:177], v153 offset:1024
	ds_read_b128 v[178:181], v153 offset:2048
	ds_read_b128 v[182:185], v153 offset:3072
	s_add_u32 s38, s56, 0x40000
	s_addc_u32 s39, s57, 0
	s_mov_b32 m0, s48
	ds_read_b128 v[186:189], v152 offset:32768
	ds_read_b128 v[190:193], v152 offset:33792
	ds_read_b128 v[194:197], v152 offset:34816
	ds_read_b128 v[198:201], v152 offset:35840
	ds_read_b128 v[202:205], v152 offset:36864
	ds_read_b128 v[206:209], v152 offset:37888
	ds_read_b128 v[210:213], v152 offset:38912
	ds_read_b128 v[214:217], v152 offset:39936
	global_load_lds_dwordx4 v134, s[38:39]
	s_mov_b32 m0, s49
	s_nop 0
	global_load_lds_dwordx4 v132, s[38:39]
	s_waitcnt vmcnt(8)
	s_waitcnt lgkmcnt(0)
	s_barrier
	v_mfma_f32_16x16x32_bf16 v[124:127], v[154:157], v[186:189], v[124:127]
	v_mfma_f32_16x16x32_bf16 v[120:123], v[162:165], v[186:189], v[120:123]
	v_mfma_f32_16x16x32_bf16 v[108:111], v[154:157], v[194:197], v[108:111]
	v_mfma_f32_16x16x32_bf16 v[104:107], v[162:165], v[194:197], v[104:107]
	v_mfma_f32_16x16x32_bf16 v[92:95], v[154:157], v[202:205], v[92:95]
	v_mfma_f32_16x16x32_bf16 v[88:91], v[162:165], v[202:205], v[88:91]
	v_mfma_f32_16x16x32_bf16 v[76:79], v[154:157], v[210:213], v[76:79]
	v_mfma_f32_16x16x32_bf16 v[72:75], v[162:165], v[210:213], v[72:75]
	v_mfma_f32_16x16x32_bf16 v[124:127], v[158:161], v[190:193], v[124:127]
	v_mfma_f32_16x16x32_bf16 v[120:123], v[166:169], v[190:193], v[120:123]
	v_mfma_f32_16x16x32_bf16 v[108:111], v[158:161], v[198:201], v[108:111]
	v_mfma_f32_16x16x32_bf16 v[104:107], v[166:169], v[198:201], v[104:107]
	v_mfma_f32_16x16x32_bf16 v[92:95], v[158:161], v[206:209], v[92:95]
	v_mfma_f32_16x16x32_bf16 v[88:91], v[166:169], v[206:209], v[88:91]
	v_mfma_f32_16x16x32_bf16 v[76:79], v[158:161], v[214:217], v[76:79]
	v_mfma_f32_16x16x32_bf16 v[72:75], v[166:169], v[214:217], v[72:75]
	v_mfma_f32_16x16x32_bf16 v[116:119], v[170:173], v[186:189], v[116:119]
	v_mfma_f32_16x16x32_bf16 v[112:115], v[178:181], v[186:189], v[112:115]
	v_mfma_f32_16x16x32_bf16 v[100:103], v[170:173], v[194:197], v[100:103]
	v_mfma_f32_16x16x32_bf16 v[96:99], v[178:181], v[194:197], v[96:99]
	v_mfma_f32_16x16x32_bf16 v[84:87], v[170:173], v[202:205], v[84:87]
	v_mfma_f32_16x16x32_bf16 v[80:83], v[178:181], v[202:205], v[80:83]
	v_mfma_f32_16x16x32_bf16 v[68:71], v[170:173], v[210:213], v[68:71]
	v_mfma_f32_16x16x32_bf16 v[64:67], v[178:181], v[210:213], v[64:67]
	v_mfma_f32_16x16x32_bf16 v[116:119], v[174:177], v[190:193], v[116:119]
	v_mfma_f32_16x16x32_bf16 v[112:115], v[182:185], v[190:193], v[112:115]
	v_mfma_f32_16x16x32_bf16 v[100:103], v[174:177], v[198:201], v[100:103]
	v_mfma_f32_16x16x32_bf16 v[96:99], v[182:185], v[198:201], v[96:99]
	v_mfma_f32_16x16x32_bf16 v[84:87], v[174:177], v[206:209], v[84:87]
	v_mfma_f32_16x16x32_bf16 v[80:83], v[182:185], v[206:209], v[80:83]
	v_mfma_f32_16x16x32_bf16 v[68:71], v[174:177], v[214:217], v[68:71]
	v_mfma_f32_16x16x32_bf16 v[64:67], v[182:185], v[214:217], v[64:67]
	s_barrier
	s_add_i32 s20, s20, s44
	v_lshl_add_u64 v[144:145], v[144:145], 0, s[6:7]
	s_mov_b32 m0, s20
	ds_read_b128 v[186:189], v152 offset:49152
	ds_read_b128 v[190:193], v152 offset:50176
	ds_read_b128 v[194:197], v152 offset:51200
	ds_read_b128 v[198:201], v152 offset:52224
	ds_read_b128 v[202:205], v152 offset:53248
	ds_read_b128 v[206:209], v152 offset:54272
	ds_read_b128 v[210:213], v152 offset:55296
	ds_read_b128 v[214:217], v152 offset:56320
	global_load_lds_dwordx4 v[144:145], off
	s_add_i32 m0, s20, 0x2000
	s_add_u32 s38, s54, 0x40080
	v_lshl_add_u64 v[144:145], v[218:219], 0, s[6:7]
	s_addc_u32 s39, s55, 0
	s_add_i32 s20, s35, s44
	global_load_lds_dwordx4 v[144:145], off
	s_mov_b32 m0, s20
	s_nop 0
	global_load_lds_dwordx4 v128, s[38:39]
	s_add_i32 m0, s20, 0x2000
	s_nop 0
	global_load_lds_dwordx4 v130, s[38:39]
	v_lshl_add_u64 v[144:145], v[220:221], 0, s[6:7]
	s_mov_b32 m0, s51
	s_nop 0
	global_load_lds_dwordx4 v[144:145], off
	v_lshl_add_u64 v[144:145], v[222:223], 0, s[6:7]
	s_mov_b32 m0, s58
	s_nop 0
	global_load_lds_dwordx4 v[144:145], off
	s_waitcnt vmcnt(8)
	s_waitcnt lgkmcnt(0)
	s_barrier
	v_mfma_f32_16x16x32_bf16 v[60:63], v[154:157], v[186:189], v[60:63]
	v_mfma_f32_16x16x32_bf16 v[56:59], v[162:165], v[186:189], v[56:59]
	v_mfma_f32_16x16x32_bf16 v[44:47], v[154:157], v[194:197], v[44:47]
	v_mfma_f32_16x16x32_bf16 v[40:43], v[162:165], v[194:197], v[40:43]
	v_mfma_f32_16x16x32_bf16 v[28:31], v[154:157], v[202:205], v[28:31]
	v_mfma_f32_16x16x32_bf16 v[24:27], v[162:165], v[202:205], v[24:27]
	v_mfma_f32_16x16x32_bf16 v[12:15], v[154:157], v[210:213], v[12:15]
	v_mfma_f32_16x16x32_bf16 v[8:11], v[162:165], v[210:213], v[8:11]
	v_mfma_f32_16x16x32_bf16 v[60:63], v[158:161], v[190:193], v[60:63]
	v_mfma_f32_16x16x32_bf16 v[56:59], v[166:169], v[190:193], v[56:59]
	v_mfma_f32_16x16x32_bf16 v[44:47], v[158:161], v[198:201], v[44:47]
	v_mfma_f32_16x16x32_bf16 v[40:43], v[166:169], v[198:201], v[40:43]
	v_mfma_f32_16x16x32_bf16 v[28:31], v[158:161], v[206:209], v[28:31]
	v_mfma_f32_16x16x32_bf16 v[24:27], v[166:169], v[206:209], v[24:27]
	v_mfma_f32_16x16x32_bf16 v[12:15], v[158:161], v[214:217], v[12:15]
	v_mfma_f32_16x16x32_bf16 v[8:11], v[166:169], v[214:217], v[8:11]
	v_mfma_f32_16x16x32_bf16 v[52:55], v[170:173], v[186:189], v[52:55]
	v_mfma_f32_16x16x32_bf16 v[48:51], v[178:181], v[186:189], v[48:51]
	v_mfma_f32_16x16x32_bf16 v[36:39], v[170:173], v[194:197], v[36:39]
	v_mfma_f32_16x16x32_bf16 v[32:35], v[178:181], v[194:197], v[32:35]
	v_mfma_f32_16x16x32_bf16 v[20:23], v[170:173], v[202:205], v[20:23]
	v_mfma_f32_16x16x32_bf16 v[16:19], v[178:181], v[202:205], v[16:19]
	v_mfma_f32_16x16x32_bf16 v[4:7], v[170:173], v[210:213], v[4:7]
	v_mfma_f32_16x16x32_bf16 v[0:3], v[178:181], v[210:213], v[0:3]
	v_mfma_f32_16x16x32_bf16 v[52:55], v[174:177], v[190:193], v[52:55]
	v_mfma_f32_16x16x32_bf16 v[48:51], v[182:185], v[190:193], v[48:51]
	v_mfma_f32_16x16x32_bf16 v[36:39], v[174:177], v[198:201], v[36:39]
	v_mfma_f32_16x16x32_bf16 v[32:35], v[182:185], v[198:201], v[32:35]
	v_mfma_f32_16x16x32_bf16 v[20:23], v[174:177], v[206:209], v[20:23]
	v_mfma_f32_16x16x32_bf16 v[16:19], v[182:185], v[206:209], v[16:19]
	v_mfma_f32_16x16x32_bf16 v[4:7], v[174:177], v[214:217], v[4:7]
	v_mfma_f32_16x16x32_bf16 v[0:3], v[182:185], v[214:217], v[0:3]
	s_barrier
	s_add_i32 s67, s67, 2
	s_add_u32 s52, s52, 0x100
	s_addc_u32 s53, s53, 0
	s_add_u32 s65, s65, 0x100
	s_addc_u32 s66, s66, 0
	s_cmp_gt_u32 s67, 13
	s_cbranch_scc0 .LBB0_968
	s_and_b64 vcc, exec, s[8:9]
	s_cbranch_vccz .LBB0_971
	s_barrier

.LBB0_1048:
	ds_read_b128 v[154:157], v150
	ds_read_b128 v[158:161], v150 offset:1024
	ds_read_b128 v[162:165], v150 offset:2048
	ds_read_b128 v[166:169], v150 offset:3072
	ds_read_b128 v[170:173], v151
	ds_read_b128 v[174:177], v151 offset:1024
	ds_read_b128 v[178:181], v151 offset:2048
	ds_read_b128 v[182:185], v151 offset:3072
	s_add_u32 s16, s14, 0x100
	s_addc_u32 s17, s15, 0
	s_cmp_eq_u32 s63, 40
	s_cselect_b32 s53, s5, s17
	s_cselect_b32 s52, s4, s16
	s_cselect_b32 s19, s13, s1
	s_cselect_b32 s18, s12, s0
	s_add_i32 m0, s46, 0xc000
	ds_read_b128 v[186:189], v152
	ds_read_b128 v[190:193], v152 offset:1024
	ds_read_b128 v[194:197], v152 offset:2048
	ds_read_b128 v[198:201], v152 offset:3072
	ds_read_b128 v[202:205], v152 offset:4096
	ds_read_b128 v[206:209], v152 offset:5120
	ds_read_b128 v[210:213], v152 offset:6144
	ds_read_b128 v[214:217], v152 offset:7168
	global_load_lds_dwordx4 v136, s[14:15]
	s_add_i32 m0, s46, 0xe000
	s_nop 0
	global_load_lds_dwordx4 v138, s[14:15]
	s_waitcnt vmcnt(8)
	s_waitcnt lgkmcnt(0)
	s_barrier
	v_mfma_f32_16x16x32_bf16 v[124:127], v[154:157], v[186:189], v[124:127]
	v_mfma_f32_16x16x32_bf16 v[120:123], v[162:165], v[186:189], v[120:123]
	v_mfma_f32_16x16x32_bf16 v[112:115], v[154:157], v[194:197], v[112:115]
	v_mfma_f32_16x16x32_bf16 v[104:107], v[162:165], v[194:197], v[104:107]
	v_mfma_f32_16x16x32_bf16 v[96:99], v[154:157], v[202:205], v[96:99]
	v_mfma_f32_16x16x32_bf16 v[88:91], v[162:165], v[202:205], v[88:91]
	v_mfma_f32_16x16x32_bf16 v[80:83], v[154:157], v[210:213], v[80:83]
	v_mfma_f32_16x16x32_bf16 v[72:75], v[162:165], v[210:213], v[72:75]
	v_mfma_f32_16x16x32_bf16 v[124:127], v[158:161], v[190:193], v[124:127]
	v_mfma_f32_16x16x32_bf16 v[120:123], v[166:169], v[190:193], v[120:123]
	v_mfma_f32_16x16x32_bf16 v[112:115], v[158:161], v[198:201], v[112:115]
	v_mfma_f32_16x16x32_bf16 v[104:107], v[166:169], v[198:201], v[104:107]
	v_mfma_f32_16x16x32_bf16 v[96:99], v[158:161], v[206:209], v[96:99]
	v_mfma_f32_16x16x32_bf16 v[88:91], v[166:169], v[206:209], v[88:91]
	v_mfma_f32_16x16x32_bf16 v[80:83], v[158:161], v[214:217], v[80:83]
	v_mfma_f32_16x16x32_bf16 v[72:75], v[166:169], v[214:217], v[72:75]
	v_mfma_f32_16x16x32_bf16 v[116:119], v[170:173], v[186:189], v[116:119]
	v_mfma_f32_16x16x32_bf16 v[108:111], v[178:181], v[186:189], v[108:111]
	v_mfma_f32_16x16x32_bf16 v[100:103], v[170:173], v[194:197], v[100:103]
	v_mfma_f32_16x16x32_bf16 v[92:95], v[178:181], v[194:197], v[92:95]
	v_mfma_f32_16x16x32_bf16 v[84:87], v[170:173], v[202:205], v[84:87]
	v_mfma_f32_16x16x32_bf16 v[76:79], v[178:181], v[202:205], v[76:79]
	v_mfma_f32_16x16x32_bf16 v[68:71], v[170:173], v[210:213], v[68:71]
	v_mfma_f32_16x16x32_bf16 v[64:67], v[178:181], v[210:213], v[64:67]
	v_mfma_f32_16x16x32_bf16 v[116:119], v[174:177], v[190:193], v[116:119]
	v_mfma_f32_16x16x32_bf16 v[108:111], v[182:185], v[190:193], v[108:111]
	v_mfma_f32_16x16x32_bf16 v[100:103], v[174:177], v[198:201], v[100:103]
	v_mfma_f32_16x16x32_bf16 v[92:95], v[182:185], v[198:201], v[92:95]
	v_mfma_f32_16x16x32_bf16 v[84:87], v[174:177], v[206:209], v[84:87]
	v_mfma_f32_16x16x32_bf16 v[76:79], v[182:185], v[206:209], v[76:79]
	v_mfma_f32_16x16x32_bf16 v[68:71], v[174:177], v[214:217], v[68:71]
	v_mfma_f32_16x16x32_bf16 v[64:67], v[182:185], v[214:217], v[64:67]
	s_barrier
	s_add_i32 s14, s57, s45
	v_lshl_add_u64 v[144:145], s[18:19], 0, v[130:131]
	s_mov_b32 m0, s14
	ds_read_b128 v[186:189], v152 offset:16384
	ds_read_b128 v[190:193], v152 offset:17408
	ds_read_b128 v[194:197], v152 offset:18432
	ds_read_b128 v[198:201], v152 offset:19456
	ds_read_b128 v[202:205], v152 offset:20480
	ds_read_b128 v[206:209], v152 offset:21504
	ds_read_b128 v[210:213], v152 offset:22528
	ds_read_b128 v[214:217], v152 offset:23552
	global_load_lds_dwordx4 v[144:145], off
	s_add_i32 m0, s14, 0x2000
	s_add_u32 s14, s18, 0xb0000
	v_lshl_add_u64 v[218:219], s[18:19], 0, v[134:135]
	s_addc_u32 s15, s19, 0
	s_add_i32 s20, s58, s45
	global_load_lds_dwordx4 v[218:219], off
	s_mov_b32 m0, s20
	v_lshl_add_u64 v[222:223], s[52:53], 0, v[132:133]
	global_load_lds_dwordx4 v130, s[14:15]
	s_add_i32 m0, s20, 0x2000
	s_nop 0
	global_load_lds_dwordx4 v134, s[14:15]
	v_lshl_add_u64 v[220:221], s[52:53], 0, v[128:129]
	s_mov_b32 m0, s46
	s_nop 0
	global_load_lds_dwordx4 v[220:221], off
	s_mov_b32 m0, s47
	s_nop 0
	global_load_lds_dwordx4 v[222:223], off
	s_waitcnt vmcnt(8)
	s_waitcnt lgkmcnt(0)
	s_barrier
	v_mfma_f32_16x16x32_bf16 v[60:63], v[154:157], v[186:189], v[60:63]
	v_mfma_f32_16x16x32_bf16 v[56:59], v[162:165], v[186:189], v[56:59]
	v_mfma_f32_16x16x32_bf16 v[48:51], v[154:157], v[194:197], v[48:51]
	v_mfma_f32_16x16x32_bf16 v[40:43], v[162:165], v[194:197], v[40:43]
	v_mfma_f32_16x16x32_bf16 v[32:35], v[154:157], v[202:205], v[32:35]
	v_mfma_f32_16x16x32_bf16 v[24:27], v[162:165], v[202:205], v[24:27]
	v_mfma_f32_16x16x32_bf16 v[16:19], v[154:157], v[210:213], v[16:19]
	v_mfma_f32_16x16x32_bf16 v[8:11], v[162:165], v[210:213], v[8:11]
	v_mfma_f32_16x16x32_bf16 v[60:63], v[158:161], v[190:193], v[60:63]
	v_mfma_f32_16x16x32_bf16 v[56:59], v[166:169], v[190:193], v[56:59]
	v_mfma_f32_16x16x32_bf16 v[48:51], v[158:161], v[198:201], v[48:51]
	v_mfma_f32_16x16x32_bf16 v[40:43], v[166:169], v[198:201], v[40:43]
	v_mfma_f32_16x16x32_bf16 v[32:35], v[158:161], v[206:209], v[32:35]
	v_mfma_f32_16x16x32_bf16 v[24:27], v[166:169], v[206:209], v[24:27]
	v_mfma_f32_16x16x32_bf16 v[16:19], v[158:161], v[214:217], v[16:19]
	v_mfma_f32_16x16x32_bf16 v[8:11], v[166:169], v[214:217], v[8:11]
	v_mfma_f32_16x16x32_bf16 v[52:55], v[170:173], v[186:189], v[52:55]
	v_mfma_f32_16x16x32_bf16 v[44:47], v[178:181], v[186:189], v[44:47]
	v_mfma_f32_16x16x32_bf16 v[36:39], v[170:173], v[194:197], v[36:39]
	v_mfma_f32_16x16x32_bf16 v[28:31], v[178:181], v[194:197], v[28:31]
	v_mfma_f32_16x16x32_bf16 v[20:23], v[170:173], v[202:205], v[20:23]
	v_mfma_f32_16x16x32_bf16 v[12:15], v[178:181], v[202:205], v[12:15]
	v_mfma_f32_16x16x32_bf16 v[4:7], v[170:173], v[210:213], v[4:7]
	v_mfma_f32_16x16x32_bf16 v[0:3], v[178:181], v[210:213], v[0:3]
	v_mfma_f32_16x16x32_bf16 v[52:55], v[174:177], v[190:193], v[52:55]
	v_mfma_f32_16x16x32_bf16 v[44:47], v[182:185], v[190:193], v[44:47]
	v_mfma_f32_16x16x32_bf16 v[36:39], v[174:177], v[198:201], v[36:39]
	v_mfma_f32_16x16x32_bf16 v[28:31], v[182:185], v[198:201], v[28:31]
	v_mfma_f32_16x16x32_bf16 v[20:23], v[174:177], v[206:209], v[20:23]
	v_mfma_f32_16x16x32_bf16 v[12:15], v[182:185], v[206:209], v[12:15]
	v_mfma_f32_16x16x32_bf16 v[4:7], v[174:177], v[214:217], v[4:7]
	v_mfma_f32_16x16x32_bf16 v[0:3], v[182:185], v[214:217], v[0:3]
	s_barrier
	s_add_i32 s20, 0, 0x18000
	v_add_u32_e32 v153, s20, v148
	s_add_i32 s35, 0, 0x1c000
	ds_read_b128 v[154:157], v153
	ds_read_b128 v[158:161], v153 offset:1024
	ds_read_b128 v[162:165], v153 offset:2048
	ds_read_b128 v[166:169], v153 offset:3072
	v_add_u32_e32 v153, s35, v148
	ds_read_b128 v[170:173], v153
	ds_read_b128 v[174:177], v153 offset:1024
	ds_read_b128 v[178:181], v153 offset:2048
	ds_read_b128 v[182:185], v153 offset:3072
	s_add_u32 s14, s52, 0xb0000
	s_addc_u32 s15, s53, 0
	s_mov_b32 m0, s48
	ds_read_b128 v[186:189], v152 offset:32768
	ds_read_b128 v[190:193], v152 offset:33792
	ds_read_b128 v[194:197], v152 offset:34816
	ds_read_b128 v[198:201], v152 offset:35840
	ds_read_b128 v[202:205], v152 offset:36864
	ds_read_b128 v[206:209], v152 offset:37888
	ds_read_b128 v[210:213], v152 offset:38912
	ds_read_b128 v[214:217], v152 offset:39936
	global_load_lds_dwordx4 v128, s[14:15]
	s_mov_b32 m0, s49
	s_nop 0
	global_load_lds_dwordx4 v132, s[14:15]
	s_waitcnt vmcnt(8)
	s_waitcnt lgkmcnt(0)
	s_barrier
	v_mfma_f32_16x16x32_bf16 v[124:127], v[154:157], v[186:189], v[124:127]
	v_mfma_f32_16x16x32_bf16 v[120:123], v[162:165], v[186:189], v[120:123]
	v_mfma_f32_16x16x32_bf16 v[112:115], v[154:157], v[194:197], v[112:115]
	v_mfma_f32_16x16x32_bf16 v[104:107], v[162:165], v[194:197], v[104:107]
	v_mfma_f32_16x16x32_bf16 v[96:99], v[154:157], v[202:205], v[96:99]
	v_mfma_f32_16x16x32_bf16 v[88:91], v[162:165], v[202:205], v[88:91]
	v_mfma_f32_16x16x32_bf16 v[80:83], v[154:157], v[210:213], v[80:83]
	v_mfma_f32_16x16x32_bf16 v[72:75], v[162:165], v[210:213], v[72:75]
	v_mfma_f32_16x16x32_bf16 v[124:127], v[158:161], v[190:193], v[124:127]
	v_mfma_f32_16x16x32_bf16 v[120:123], v[166:169], v[190:193], v[120:123]
	v_mfma_f32_16x16x32_bf16 v[112:115], v[158:161], v[198:201], v[112:115]
	v_mfma_f32_16x16x32_bf16 v[104:107], v[166:169], v[198:201], v[104:107]
	v_mfma_f32_16x16x32_bf16 v[96:99], v[158:161], v[206:209], v[96:99]
	v_mfma_f32_16x16x32_bf16 v[88:91], v[166:169], v[206:209], v[88:91]
	v_mfma_f32_16x16x32_bf16 v[80:83], v[158:161], v[214:217], v[80:83]
	v_mfma_f32_16x16x32_bf16 v[72:75], v[166:169], v[214:217], v[72:75]
	v_mfma_f32_16x16x32_bf16 v[116:119], v[170:173], v[186:189], v[116:119]
	v_mfma_f32_16x16x32_bf16 v[108:111], v[178:181], v[186:189], v[108:111]
	v_mfma_f32_16x16x32_bf16 v[100:103], v[170:173], v[194:197], v[100:103]
	v_mfma_f32_16x16x32_bf16 v[92:95], v[178:181], v[194:197], v[92:95]
	v_mfma_f32_16x16x32_bf16 v[84:87], v[170:173], v[202:205], v[84:87]
	v_mfma_f32_16x16x32_bf16 v[76:79], v[178:181], v[202:205], v[76:79]
	v_mfma_f32_16x16x32_bf16 v[68:71], v[170:173], v[210:213], v[68:71]
	v_mfma_f32_16x16x32_bf16 v[64:67], v[178:181], v[210:213], v[64:67]
	v_mfma_f32_16x16x32_bf16 v[116:119], v[174:177], v[190:193], v[116:119]
	v_mfma_f32_16x16x32_bf16 v[108:111], v[182:185], v[190:193], v[108:111]
	v_mfma_f32_16x16x32_bf16 v[100:103], v[174:177], v[198:201], v[100:103]
	v_mfma_f32_16x16x32_bf16 v[92:95], v[182:185], v[198:201], v[92:95]
	v_mfma_f32_16x16x32_bf16 v[84:87], v[174:177], v[206:209], v[84:87]
	v_mfma_f32_16x16x32_bf16 v[76:79], v[182:185], v[206:209], v[76:79]
	v_mfma_f32_16x16x32_bf16 v[68:71], v[174:177], v[214:217], v[68:71]
	v_mfma_f32_16x16x32_bf16 v[64:67], v[182:185], v[214:217], v[64:67]
	s_barrier
	s_add_i32 s14, s20, s45
	v_lshl_add_u64 v[144:145], v[144:145], 0, s[8:9]
	s_mov_b32 m0, s14
	ds_read_b128 v[186:189], v152 offset:49152
	ds_read_b128 v[190:193], v152 offset:50176
	ds_read_b128 v[194:197], v152 offset:51200
	ds_read_b128 v[198:201], v152 offset:52224
	ds_read_b128 v[202:205], v152 offset:53248
	ds_read_b128 v[206:209], v152 offset:54272
	ds_read_b128 v[210:213], v152 offset:55296
	ds_read_b128 v[214:217], v152 offset:56320
	global_load_lds_dwordx4 v[144:145], off
	s_add_i32 m0, s14, 0x2000
	s_add_u32 s14, s18, 0xb0080
	v_lshl_add_u64 v[144:145], v[218:219], 0, s[8:9]
	s_addc_u32 s15, s19, 0
	s_add_i32 s18, s35, s45
	global_load_lds_dwordx4 v[144:145], off
	s_mov_b32 m0, s18
	s_nop 0
	global_load_lds_dwordx4 v130, s[14:15]
	s_add_i32 m0, s18, 0x2000
	s_nop 0
	global_load_lds_dwordx4 v134, s[14:15]
	v_lshl_add_u64 v[144:145], v[220:221], 0, s[8:9]
	s_mov_b32 m0, s51
	s_nop 0
	global_load_lds_dwordx4 v[144:145], off
	v_lshl_add_u64 v[144:145], v[222:223], 0, s[8:9]
	s_mov_b32 m0, s54
	s_nop 0
	global_load_lds_dwordx4 v[144:145], off
	s_waitcnt vmcnt(8)
	s_waitcnt lgkmcnt(0)
	s_barrier
	v_mfma_f32_16x16x32_bf16 v[60:63], v[154:157], v[186:189], v[60:63]
	v_mfma_f32_16x16x32_bf16 v[56:59], v[162:165], v[186:189], v[56:59]
	v_mfma_f32_16x16x32_bf16 v[48:51], v[154:157], v[194:197], v[48:51]
	v_mfma_f32_16x16x32_bf16 v[40:43], v[162:165], v[194:197], v[40:43]
	v_mfma_f32_16x16x32_bf16 v[32:35], v[154:157], v[202:205], v[32:35]
	v_mfma_f32_16x16x32_bf16 v[24:27], v[162:165], v[202:205], v[24:27]
	v_mfma_f32_16x16x32_bf16 v[16:19], v[154:157], v[210:213], v[16:19]
	v_mfma_f32_16x16x32_bf16 v[8:11], v[162:165], v[210:213], v[8:11]
	v_mfma_f32_16x16x32_bf16 v[60:63], v[158:161], v[190:193], v[60:63]
	v_mfma_f32_16x16x32_bf16 v[56:59], v[166:169], v[190:193], v[56:59]
	v_mfma_f32_16x16x32_bf16 v[48:51], v[158:161], v[198:201], v[48:51]
	v_mfma_f32_16x16x32_bf16 v[40:43], v[166:169], v[198:201], v[40:43]
	v_mfma_f32_16x16x32_bf16 v[32:35], v[158:161], v[206:209], v[32:35]
	v_mfma_f32_16x16x32_bf16 v[24:27], v[166:169], v[206:209], v[24:27]
	v_mfma_f32_16x16x32_bf16 v[16:19], v[158:161], v[214:217], v[16:19]
	v_mfma_f32_16x16x32_bf16 v[8:11], v[166:169], v[214:217], v[8:11]
	v_mfma_f32_16x16x32_bf16 v[52:55], v[170:173], v[186:189], v[52:55]
	v_mfma_f32_16x16x32_bf16 v[44:47], v[178:181], v[186:189], v[44:47]
	v_mfma_f32_16x16x32_bf16 v[36:39], v[170:173], v[194:197], v[36:39]
	v_mfma_f32_16x16x32_bf16 v[28:31], v[178:181], v[194:197], v[28:31]
	v_mfma_f32_16x16x32_bf16 v[20:23], v[170:173], v[202:205], v[20:23]
	v_mfma_f32_16x16x32_bf16 v[12:15], v[178:181], v[202:205], v[12:15]
	v_mfma_f32_16x16x32_bf16 v[4:7], v[170:173], v[210:213], v[4:7]
	v_mfma_f32_16x16x32_bf16 v[0:3], v[178:181], v[210:213], v[0:3]
	v_mfma_f32_16x16x32_bf16 v[52:55], v[174:177], v[190:193], v[52:55]
	v_mfma_f32_16x16x32_bf16 v[44:47], v[182:185], v[190:193], v[44:47]
	v_mfma_f32_16x16x32_bf16 v[36:39], v[174:177], v[198:201], v[36:39]
	v_mfma_f32_16x16x32_bf16 v[28:31], v[182:185], v[198:201], v[28:31]
	v_mfma_f32_16x16x32_bf16 v[20:23], v[174:177], v[206:209], v[20:23]
	v_mfma_f32_16x16x32_bf16 v[12:15], v[182:185], v[206:209], v[12:15]
	v_mfma_f32_16x16x32_bf16 v[4:7], v[174:177], v[214:217], v[4:7]
	v_mfma_f32_16x16x32_bf16 v[0:3], v[182:185], v[214:217], v[0:3]
	s_barrier
	s_add_i32 s63, s63, 2
	s_add_u32 s0, s0, 0x100
	s_addc_u32 s1, s1, 0
	s_cmp_gt_u32 s63, 41
	s_mov_b64 s[14:15], s[16:17]
	s_cbranch_scc0 .LBB0_1048
	s_and_b64 vcc, exec, s[10:11]
	s_cbranch_vccz .LBB0_1051
	s_barrier

.LBB0_1131:
	s_add_u32 s19, s54, s60
	s_addc_u32 s20, s55, 0
	s_add_u32 s35, s19, 0x100
	s_addc_u32 s42, s20, 0
	s_and_b64 s[38:39], s[58:59], exec
	s_cselect_b32 s63, s0, s42
	s_cselect_b32 s62, s1, s35
	s_add_u32 s35, s52, s60
	s_addc_u32 s38, s53, 0
	s_add_u32 s35, s35, 0x100
	s_addc_u32 s42, s38, 0
	s_and_b64 s[38:39], s[58:59], exec
	s_cselect_b32 s65, s11, s42
	s_cselect_b32 s64, s13, s35
	s_add_u32 s80, s19, 0x10080
	ds_read_b128 v[150:153], v146
	ds_read_b128 v[154:157], v146 offset:1024
	ds_read_b128 v[158:161], v146 offset:2048
	ds_read_b128 v[162:165], v146 offset:3072
	ds_read_b128 v[166:169], v147
	ds_read_b128 v[170:173], v147 offset:1024
	ds_read_b128 v[174:177], v147 offset:2048
	ds_read_b128 v[178:181], v147 offset:3072
	s_addc_u32 s81, s20, 0
	s_add_i32 s75, s77, s45
	s_add_i32 m0, s94, 0xc000
	s_add_i32 s19, s94, 0xe000
	s_add_i32 s42, s75, 0x2000
	s_add_u32 s66, s64, 0x10000
	s_addc_u32 s67, s65, 0
	s_add_i32 s43, s78, s45
	s_add_i32 s74, s43, 0x2000
	s_add_i32 vcc_hi, 0, 0x18000
	s_add_i32 vcc_lo, 0, 0x1c000
	s_add_u32 s60, s62, 0x10000
	s_addc_u32 s61, s63, 0
	s_add_i32 s20, vcc_hi, s45
	s_add_i32 s39, s20, 0x2000
	s_add_u32 s58, s64, 0x10080
	s_addc_u32 s59, s65, 0
	s_add_i32 s35, vcc_lo, s45
	s_add_i32 s38, s35, 0x2000
	ds_read_b128 v[182:185], v148
	ds_read_b128 v[186:189], v148 offset:1024
	ds_read_b128 v[190:193], v148 offset:2048
	ds_read_b128 v[194:197], v148 offset:3072
	ds_read_b128 v[198:201], v148 offset:4096
	ds_read_b128 v[202:205], v148 offset:5120
	ds_read_b128 v[206:209], v148 offset:6144
	ds_read_b128 v[210:213], v148 offset:7168
	global_load_lds_dwordx4 v128, s[80:81]
	s_mov_b32 m0, s19
	s_nop 0
	global_load_lds_dwordx4 v132, s[80:81]
	s_waitcnt vmcnt(8)
	s_waitcnt lgkmcnt(0)
	s_barrier
	v_mfma_f32_16x16x32_bf16 v[124:127], v[150:153], v[182:185], v[124:127]
	v_mfma_f32_16x16x32_bf16 v[120:123], v[158:161], v[182:185], v[120:123]
	v_mfma_f32_16x16x32_bf16 v[112:115], v[150:153], v[190:193], v[112:115]
	v_mfma_f32_16x16x32_bf16 v[104:107], v[158:161], v[190:193], v[104:107]
	v_mfma_f32_16x16x32_bf16 v[96:99], v[150:153], v[198:201], v[96:99]
	v_mfma_f32_16x16x32_bf16 v[88:91], v[158:161], v[198:201], v[88:91]
	v_mfma_f32_16x16x32_bf16 v[80:83], v[150:153], v[206:209], v[80:83]
	v_mfma_f32_16x16x32_bf16 v[72:75], v[158:161], v[206:209], v[72:75]
	v_mfma_f32_16x16x32_bf16 v[124:127], v[154:157], v[186:189], v[124:127]
	v_mfma_f32_16x16x32_bf16 v[120:123], v[162:165], v[186:189], v[120:123]
	v_mfma_f32_16x16x32_bf16 v[112:115], v[154:157], v[194:197], v[112:115]
	v_mfma_f32_16x16x32_bf16 v[104:107], v[162:165], v[194:197], v[104:107]
	v_mfma_f32_16x16x32_bf16 v[96:99], v[154:157], v[202:205], v[96:99]
	v_mfma_f32_16x16x32_bf16 v[88:91], v[162:165], v[202:205], v[88:91]
	v_mfma_f32_16x16x32_bf16 v[80:83], v[154:157], v[210:213], v[80:83]
	v_mfma_f32_16x16x32_bf16 v[72:75], v[162:165], v[210:213], v[72:75]
	v_mfma_f32_16x16x32_bf16 v[116:119], v[166:169], v[182:185], v[116:119]
	v_mfma_f32_16x16x32_bf16 v[108:111], v[174:177], v[182:185], v[108:111]
	v_mfma_f32_16x16x32_bf16 v[100:103], v[166:169], v[190:193], v[100:103]
	v_mfma_f32_16x16x32_bf16 v[92:95], v[174:177], v[190:193], v[92:95]
	v_mfma_f32_16x16x32_bf16 v[84:87], v[166:169], v[198:201], v[84:87]
	v_mfma_f32_16x16x32_bf16 v[76:79], v[174:177], v[198:201], v[76:79]
	v_mfma_f32_16x16x32_bf16 v[68:71], v[166:169], v[206:209], v[68:71]
	v_mfma_f32_16x16x32_bf16 v[64:67], v[174:177], v[206:209], v[64:67]
	v_mfma_f32_16x16x32_bf16 v[116:119], v[170:173], v[186:189], v[116:119]
	v_mfma_f32_16x16x32_bf16 v[108:111], v[178:181], v[186:189], v[108:111]
	v_mfma_f32_16x16x32_bf16 v[100:103], v[170:173], v[194:197], v[100:103]
	v_mfma_f32_16x16x32_bf16 v[92:95], v[178:181], v[194:197], v[92:95]
	v_mfma_f32_16x16x32_bf16 v[84:87], v[170:173], v[202:205], v[84:87]
	v_mfma_f32_16x16x32_bf16 v[76:79], v[178:181], v[202:205], v[76:79]
	v_mfma_f32_16x16x32_bf16 v[68:71], v[170:173], v[210:213], v[68:71]
	v_mfma_f32_16x16x32_bf16 v[64:67], v[178:181], v[210:213], v[64:67]
	s_barrier
	s_mov_b32 m0, s75
	v_lshl_add_u64 v[140:141], s[64:65], 0, v[130:131]
	ds_read_b128 v[182:185], v148 offset:16384
	ds_read_b128 v[186:189], v148 offset:17408
	ds_read_b128 v[190:193], v148 offset:18432
	ds_read_b128 v[194:197], v148 offset:19456
	ds_read_b128 v[198:201], v148 offset:20480
	ds_read_b128 v[202:205], v148 offset:21504
	ds_read_b128 v[206:209], v148 offset:22528
	ds_read_b128 v[210:213], v148 offset:23552
	global_load_lds_dwordx4 v[140:141], off
	v_lshl_add_u64 v[214:215], s[64:65], 0, v[134:135]
	s_mov_b32 m0, s42
	s_nop 0
	global_load_lds_dwordx4 v[214:215], off
	s_mov_b32 m0, s43
	v_lshl_add_u64 v[218:219], s[62:63], 0, v[132:133]
	global_load_lds_dwordx4 v130, s[66:67]
	s_mov_b32 m0, s74
	s_nop 0
	global_load_lds_dwordx4 v134, s[66:67]
	v_lshl_add_u64 v[216:217], s[62:63], 0, v[128:129]
	s_mov_b32 m0, s94
	s_nop 0
	global_load_lds_dwordx4 v[216:217], off
	s_mov_b32 m0, s46
	s_nop 0
	global_load_lds_dwordx4 v[218:219], off
	s_waitcnt vmcnt(8)
	s_waitcnt lgkmcnt(0)
	s_barrier
	v_mfma_f32_16x16x32_bf16 v[60:63], v[150:153], v[182:185], v[60:63]
	v_mfma_f32_16x16x32_bf16 v[56:59], v[158:161], v[182:185], v[56:59]
	v_mfma_f32_16x16x32_bf16 v[48:51], v[150:153], v[190:193], v[48:51]
	v_mfma_f32_16x16x32_bf16 v[40:43], v[158:161], v[190:193], v[40:43]
	v_mfma_f32_16x16x32_bf16 v[32:35], v[150:153], v[198:201], v[32:35]
	v_mfma_f32_16x16x32_bf16 v[24:27], v[158:161], v[198:201], v[24:27]
	v_mfma_f32_16x16x32_bf16 v[16:19], v[150:153], v[206:209], v[16:19]
	v_mfma_f32_16x16x32_bf16 v[8:11], v[158:161], v[206:209], v[8:11]
	v_mfma_f32_16x16x32_bf16 v[60:63], v[154:157], v[186:189], v[60:63]
	v_mfma_f32_16x16x32_bf16 v[56:59], v[162:165], v[186:189], v[56:59]
	v_mfma_f32_16x16x32_bf16 v[48:51], v[154:157], v[194:197], v[48:51]
	v_mfma_f32_16x16x32_bf16 v[40:43], v[162:165], v[194:197], v[40:43]
	v_mfma_f32_16x16x32_bf16 v[32:35], v[154:157], v[202:205], v[32:35]
	v_mfma_f32_16x16x32_bf16 v[24:27], v[162:165], v[202:205], v[24:27]
	v_mfma_f32_16x16x32_bf16 v[16:19], v[154:157], v[210:213], v[16:19]
	v_mfma_f32_16x16x32_bf16 v[8:11], v[162:165], v[210:213], v[8:11]
	v_mfma_f32_16x16x32_bf16 v[52:55], v[166:169], v[182:185], v[52:55]
	v_mfma_f32_16x16x32_bf16 v[44:47], v[174:177], v[182:185], v[44:47]
	v_mfma_f32_16x16x32_bf16 v[36:39], v[166:169], v[190:193], v[36:39]
	v_mfma_f32_16x16x32_bf16 v[28:31], v[174:177], v[190:193], v[28:31]
	v_mfma_f32_16x16x32_bf16 v[20:23], v[166:169], v[198:201], v[20:23]
	v_mfma_f32_16x16x32_bf16 v[12:15], v[174:177], v[198:201], v[12:15]
	v_mfma_f32_16x16x32_bf16 v[4:7], v[166:169], v[206:209], v[4:7]
	v_mfma_f32_16x16x32_bf16 v[0:3], v[174:177], v[206:209], v[0:3]
	v_mfma_f32_16x16x32_bf16 v[52:55], v[170:173], v[186:189], v[52:55]
	v_mfma_f32_16x16x32_bf16 v[44:47], v[178:181], v[186:189], v[44:47]
	v_mfma_f32_16x16x32_bf16 v[36:39], v[170:173], v[194:197], v[36:39]
	v_mfma_f32_16x16x32_bf16 v[28:31], v[178:181], v[194:197], v[28:31]
	v_mfma_f32_16x16x32_bf16 v[20:23], v[170:173], v[202:205], v[20:23]
	v_mfma_f32_16x16x32_bf16 v[12:15], v[178:181], v[202:205], v[12:15]
	v_mfma_f32_16x16x32_bf16 v[4:7], v[170:173], v[210:213], v[4:7]
	v_mfma_f32_16x16x32_bf16 v[0:3], v[178:181], v[210:213], v[0:3]
	s_barrier
	v_add_u32_e32 v149, vcc_hi, v144
	ds_read_b128 v[150:153], v149
	ds_read_b128 v[154:157], v149 offset:1024
	ds_read_b128 v[158:161], v149 offset:2048
	ds_read_b128 v[162:165], v149 offset:3072
	v_add_u32_e32 v149, vcc_lo, v144
	ds_read_b128 v[166:169], v149
	ds_read_b128 v[170:173], v149 offset:1024
	ds_read_b128 v[174:177], v149 offset:2048
	ds_read_b128 v[178:181], v149 offset:3072
	s_mov_b32 m0, s47
	ds_read_b128 v[182:185], v148 offset:32768
	ds_read_b128 v[186:189], v148 offset:33792
	ds_read_b128 v[190:193], v148 offset:34816
	ds_read_b128 v[194:197], v148 offset:35840
	ds_read_b128 v[198:201], v148 offset:36864
	ds_read_b128 v[202:205], v148 offset:37888
	ds_read_b128 v[206:209], v148 offset:38912
	ds_read_b128 v[210:213], v148 offset:39936
	global_load_lds_dwordx4 v128, s[60:61]
	s_mov_b32 m0, s48
	s_nop 0
	global_load_lds_dwordx4 v132, s[60:61]
	s_waitcnt vmcnt(8)
	s_waitcnt lgkmcnt(0)
	s_barrier
	v_mfma_f32_16x16x32_bf16 v[124:127], v[150:153], v[182:185], v[124:127]
	v_mfma_f32_16x16x32_bf16 v[120:123], v[158:161], v[182:185], v[120:123]
	v_mfma_f32_16x16x32_bf16 v[112:115], v[150:153], v[190:193], v[112:115]
	v_mfma_f32_16x16x32_bf16 v[104:107], v[158:161], v[190:193], v[104:107]
	v_mfma_f32_16x16x32_bf16 v[96:99], v[150:153], v[198:201], v[96:99]
	v_mfma_f32_16x16x32_bf16 v[88:91], v[158:161], v[198:201], v[88:91]
	v_mfma_f32_16x16x32_bf16 v[80:83], v[150:153], v[206:209], v[80:83]
	v_mfma_f32_16x16x32_bf16 v[72:75], v[158:161], v[206:209], v[72:75]
	v_mfma_f32_16x16x32_bf16 v[124:127], v[154:157], v[186:189], v[124:127]
	v_mfma_f32_16x16x32_bf16 v[120:123], v[162:165], v[186:189], v[120:123]
	v_mfma_f32_16x16x32_bf16 v[112:115], v[154:157], v[194:197], v[112:115]
	v_mfma_f32_16x16x32_bf16 v[104:107], v[162:165], v[194:197], v[104:107]
	v_mfma_f32_16x16x32_bf16 v[96:99], v[154:157], v[202:205], v[96:99]
	v_mfma_f32_16x16x32_bf16 v[88:91], v[162:165], v[202:205], v[88:91]
	v_mfma_f32_16x16x32_bf16 v[80:83], v[154:157], v[210:213], v[80:83]
	v_mfma_f32_16x16x32_bf16 v[72:75], v[162:165], v[210:213], v[72:75]
	v_mfma_f32_16x16x32_bf16 v[116:119], v[166:169], v[182:185], v[116:119]
	v_mfma_f32_16x16x32_bf16 v[108:111], v[174:177], v[182:185], v[108:111]
	v_mfma_f32_16x16x32_bf16 v[100:103], v[166:169], v[190:193], v[100:103]
	v_mfma_f32_16x16x32_bf16 v[92:95], v[174:177], v[190:193], v[92:95]
	v_mfma_f32_16x16x32_bf16 v[84:87], v[166:169], v[198:201], v[84:87]
	v_mfma_f32_16x16x32_bf16 v[76:79], v[174:177], v[198:201], v[76:79]
	v_mfma_f32_16x16x32_bf16 v[68:71], v[166:169], v[206:209], v[68:71]
	v_mfma_f32_16x16x32_bf16 v[64:67], v[174:177], v[206:209], v[64:67]
	v_mfma_f32_16x16x32_bf16 v[116:119], v[170:173], v[186:189], v[116:119]
	v_mfma_f32_16x16x32_bf16 v[108:111], v[178:181], v[186:189], v[108:111]
	v_mfma_f32_16x16x32_bf16 v[100:103], v[170:173], v[194:197], v[100:103]
	v_mfma_f32_16x16x32_bf16 v[92:95], v[178:181], v[194:197], v[92:95]
	v_mfma_f32_16x16x32_bf16 v[84:87], v[170:173], v[202:205], v[84:87]
	v_mfma_f32_16x16x32_bf16 v[76:79], v[178:181], v[202:205], v[76:79]
	v_mfma_f32_16x16x32_bf16 v[68:71], v[170:173], v[210:213], v[68:71]
	v_mfma_f32_16x16x32_bf16 v[64:67], v[178:181], v[210:213], v[64:67]
	s_barrier
	s_mov_b32 m0, s20
	v_lshl_add_u64 v[140:141], v[140:141], 0, s[6:7]
	ds_read_b128 v[182:185], v148 offset:49152
	ds_read_b128 v[186:189], v148 offset:50176
	ds_read_b128 v[190:193], v148 offset:51200
	ds_read_b128 v[194:197], v148 offset:52224
	ds_read_b128 v[198:201], v148 offset:53248
	ds_read_b128 v[202:205], v148 offset:54272
	ds_read_b128 v[206:209], v148 offset:55296
	ds_read_b128 v[210:213], v148 offset:56320
	global_load_lds_dwordx4 v[140:141], off
	v_lshl_add_u64 v[140:141], v[214:215], 0, s[6:7]
	s_mov_b32 m0, s39
	s_nop 0
	global_load_lds_dwordx4 v[140:141], off
	s_mov_b32 m0, s35
	s_nop 0
	global_load_lds_dwordx4 v130, s[58:59]
	s_mov_b32 m0, s38
	s_nop 0
	global_load_lds_dwordx4 v134, s[58:59]
	v_lshl_add_u64 v[140:141], v[216:217], 0, s[6:7]
	s_mov_b32 m0, s50
	s_nop 0
	global_load_lds_dwordx4 v[140:141], off
	v_lshl_add_u64 v[140:141], v[218:219], 0, s[6:7]
	s_mov_b32 m0, s51
	s_nop 0
	global_load_lds_dwordx4 v[140:141], off
	s_waitcnt vmcnt(8)
	s_waitcnt lgkmcnt(0)
	s_barrier
	v_mfma_f32_16x16x32_bf16 v[60:63], v[150:153], v[182:185], v[60:63]
	v_mfma_f32_16x16x32_bf16 v[56:59], v[158:161], v[182:185], v[56:59]
	v_mfma_f32_16x16x32_bf16 v[48:51], v[150:153], v[190:193], v[48:51]
	v_mfma_f32_16x16x32_bf16 v[40:43], v[158:161], v[190:193], v[40:43]
	v_mfma_f32_16x16x32_bf16 v[32:35], v[150:153], v[198:201], v[32:35]
	v_mfma_f32_16x16x32_bf16 v[24:27], v[158:161], v[198:201], v[24:27]
	v_mfma_f32_16x16x32_bf16 v[16:19], v[150:153], v[206:209], v[16:19]
	v_mfma_f32_16x16x32_bf16 v[8:11], v[158:161], v[206:209], v[8:11]
	v_mfma_f32_16x16x32_bf16 v[60:63], v[154:157], v[186:189], v[60:63]
	v_mfma_f32_16x16x32_bf16 v[56:59], v[162:165], v[186:189], v[56:59]
	v_mfma_f32_16x16x32_bf16 v[48:51], v[154:157], v[194:197], v[48:51]
	v_mfma_f32_16x16x32_bf16 v[40:43], v[162:165], v[194:197], v[40:43]
	v_mfma_f32_16x16x32_bf16 v[32:35], v[154:157], v[202:205], v[32:35]
	v_mfma_f32_16x16x32_bf16 v[24:27], v[162:165], v[202:205], v[24:27]
	v_mfma_f32_16x16x32_bf16 v[16:19], v[154:157], v[210:213], v[16:19]
	v_mfma_f32_16x16x32_bf16 v[8:11], v[162:165], v[210:213], v[8:11]
	v_mfma_f32_16x16x32_bf16 v[52:55], v[166:169], v[182:185], v[52:55]
	v_mfma_f32_16x16x32_bf16 v[44:47], v[174:177], v[182:185], v[44:47]
	v_mfma_f32_16x16x32_bf16 v[36:39], v[166:169], v[190:193], v[36:39]
	v_mfma_f32_16x16x32_bf16 v[28:31], v[174:177], v[190:193], v[28:31]
	v_mfma_f32_16x16x32_bf16 v[20:23], v[166:169], v[198:201], v[20:23]
	v_mfma_f32_16x16x32_bf16 v[12:15], v[174:177], v[198:201], v[12:15]
	v_mfma_f32_16x16x32_bf16 v[4:7], v[166:169], v[206:209], v[4:7]
	v_mfma_f32_16x16x32_bf16 v[0:3], v[174:177], v[206:209], v[0:3]
	v_mfma_f32_16x16x32_bf16 v[52:55], v[170:173], v[186:189], v[52:55]
	v_mfma_f32_16x16x32_bf16 v[44:47], v[178:181], v[186:189], v[44:47]
	v_mfma_f32_16x16x32_bf16 v[36:39], v[170:173], v[194:197], v[36:39]
	v_mfma_f32_16x16x32_bf16 v[28:31], v[178:181], v[194:197], v[28:31]
	v_mfma_f32_16x16x32_bf16 v[20:23], v[170:173], v[202:205], v[20:23]
	v_mfma_f32_16x16x32_bf16 v[12:15], v[178:181], v[202:205], v[12:15]
	v_mfma_f32_16x16x32_bf16 v[4:7], v[170:173], v[210:213], v[4:7]
	v_mfma_f32_16x16x32_bf16 v[0:3], v[178:181], v[210:213], v[0:3]
	s_barrier
	s_movk_i32 s60, 0x100
	s_andn2_b64 vcc, exec, s[56:57]
	s_mov_b64 s[58:59], -1
	s_mov_b64 s[56:57], 0
	s_cbranch_vccz .LBB0_1131
	s_and_b64 vcc, exec, s[8:9]
	s_cbranch_vccz .LBB0_1134
	s_barrier

.LBB0_1207:
	ds_read_b128 v[144:147], v154
	ds_read_b128 v[158:161], v154 offset:1024
	ds_read_b128 v[162:165], v154 offset:2048
	ds_read_b128 v[166:169], v154 offset:3072
	ds_read_b128 v[170:173], v155
	ds_read_b128 v[174:177], v155 offset:1024
	ds_read_b128 v[178:181], v155 offset:2048
	ds_read_b128 v[182:185], v155 offset:3072
	s_add_u32 s20, s52, 0xfffc0080
	s_addc_u32 s35, s53, -1
	s_cmp_eq_u32 s65, 12
	s_cselect_b32 s57, s0, s35
	s_cselect_b32 s56, s1, s20
	s_cselect_b32 s55, s11, s64
	s_cselect_b32 s54, s13, s63
	s_add_i32 m0, s46, 0xc000
	ds_read_b128 v[186:189], v156
	ds_read_b128 v[190:193], v156 offset:1024
	ds_read_b128 v[194:197], v156 offset:2048
	ds_read_b128 v[198:201], v156 offset:3072
	ds_read_b128 v[202:205], v156 offset:4096
	ds_read_b128 v[206:209], v156 offset:5120
	ds_read_b128 v[210:213], v156 offset:6144
	ds_read_b128 v[214:217], v156 offset:7168
	global_load_lds_dwordx4 v136, s[52:53]
	s_add_i32 m0, s46, 0xe000
	s_nop 0
	global_load_lds_dwordx4 v138, s[52:53]
	s_waitcnt vmcnt(8)
	s_waitcnt lgkmcnt(0)
	s_barrier
	v_mfma_f32_16x16x32_bf16 v[124:127], v[144:147], v[186:189], v[124:127]
	v_mfma_f32_16x16x32_bf16 v[120:123], v[162:165], v[186:189], v[120:123]
	v_mfma_f32_16x16x32_bf16 v[108:111], v[144:147], v[194:197], v[108:111]
	v_mfma_f32_16x16x32_bf16 v[104:107], v[162:165], v[194:197], v[104:107]
	v_mfma_f32_16x16x32_bf16 v[92:95], v[144:147], v[202:205], v[92:95]
	v_mfma_f32_16x16x32_bf16 v[88:91], v[162:165], v[202:205], v[88:91]
	v_mfma_f32_16x16x32_bf16 v[76:79], v[144:147], v[210:213], v[76:79]
	v_mfma_f32_16x16x32_bf16 v[72:75], v[162:165], v[210:213], v[72:75]
	v_mfma_f32_16x16x32_bf16 v[124:127], v[158:161], v[190:193], v[124:127]
	v_mfma_f32_16x16x32_bf16 v[120:123], v[166:169], v[190:193], v[120:123]
	v_mfma_f32_16x16x32_bf16 v[108:111], v[158:161], v[198:201], v[108:111]
	v_mfma_f32_16x16x32_bf16 v[104:107], v[166:169], v[198:201], v[104:107]
	v_mfma_f32_16x16x32_bf16 v[92:95], v[158:161], v[206:209], v[92:95]
	v_mfma_f32_16x16x32_bf16 v[88:91], v[166:169], v[206:209], v[88:91]
	v_mfma_f32_16x16x32_bf16 v[76:79], v[158:161], v[214:217], v[76:79]
	v_mfma_f32_16x16x32_bf16 v[72:75], v[166:169], v[214:217], v[72:75]
	v_mfma_f32_16x16x32_bf16 v[116:119], v[170:173], v[186:189], v[116:119]
	v_mfma_f32_16x16x32_bf16 v[112:115], v[178:181], v[186:189], v[112:115]
	v_mfma_f32_16x16x32_bf16 v[100:103], v[170:173], v[194:197], v[100:103]
	v_mfma_f32_16x16x32_bf16 v[96:99], v[178:181], v[194:197], v[96:99]
	v_mfma_f32_16x16x32_bf16 v[84:87], v[170:173], v[202:205], v[84:87]
	v_mfma_f32_16x16x32_bf16 v[80:83], v[178:181], v[202:205], v[80:83]
	v_mfma_f32_16x16x32_bf16 v[68:71], v[170:173], v[210:213], v[68:71]
	v_mfma_f32_16x16x32_bf16 v[64:67], v[178:181], v[210:213], v[64:67]
	v_mfma_f32_16x16x32_bf16 v[116:119], v[174:177], v[190:193], v[116:119]
	v_mfma_f32_16x16x32_bf16 v[112:115], v[182:185], v[190:193], v[112:115]
	v_mfma_f32_16x16x32_bf16 v[100:103], v[174:177], v[198:201], v[100:103]
	v_mfma_f32_16x16x32_bf16 v[96:99], v[182:185], v[198:201], v[96:99]
	v_mfma_f32_16x16x32_bf16 v[84:87], v[174:177], v[206:209], v[84:87]
	v_mfma_f32_16x16x32_bf16 v[80:83], v[182:185], v[206:209], v[80:83]
	v_mfma_f32_16x16x32_bf16 v[68:71], v[174:177], v[214:217], v[68:71]
	v_mfma_f32_16x16x32_bf16 v[64:67], v[182:185], v[214:217], v[64:67]
	s_barrier
	s_add_i32 s20, s61, s45
	v_lshl_add_u64 v[148:149], s[54:55], 0, v[130:131]
	s_mov_b32 m0, s20
	ds_read_b128 v[186:189], v156 offset:16384
	ds_read_b128 v[190:193], v156 offset:17408
	ds_read_b128 v[194:197], v156 offset:18432
	ds_read_b128 v[198:201], v156 offset:19456
	ds_read_b128 v[202:205], v156 offset:20480
	ds_read_b128 v[206:209], v156 offset:21504
	ds_read_b128 v[210:213], v156 offset:22528
	ds_read_b128 v[214:217], v156 offset:23552
	global_load_lds_dwordx4 v[148:149], off
	s_add_i32 m0, s20, 0x2000
	s_add_u32 s38, s54, 0x40000
	v_lshl_add_u64 v[218:219], s[54:55], 0, v[134:135]
	s_addc_u32 s39, s55, 0
	s_add_i32 s20, s62, s45
	global_load_lds_dwordx4 v[218:219], off
	s_mov_b32 m0, s20
	v_lshl_add_u64 v[222:223], s[56:57], 0, v[132:133]
	global_load_lds_dwordx4 v130, s[38:39]
	s_add_i32 m0, s20, 0x2000
	s_nop 0
	global_load_lds_dwordx4 v134, s[38:39]
	v_lshl_add_u64 v[220:221], s[56:57], 0, v[128:129]
	s_mov_b32 m0, s46
	s_nop 0
	global_load_lds_dwordx4 v[220:221], off
	s_mov_b32 m0, s47
	s_nop 0
	global_load_lds_dwordx4 v[222:223], off
	s_waitcnt vmcnt(8)
	s_waitcnt lgkmcnt(0)
	s_barrier
	v_mfma_f32_16x16x32_bf16 v[60:63], v[144:147], v[186:189], v[60:63]
	v_mfma_f32_16x16x32_bf16 v[56:59], v[162:165], v[186:189], v[56:59]
	v_mfma_f32_16x16x32_bf16 v[44:47], v[144:147], v[194:197], v[44:47]
	v_mfma_f32_16x16x32_bf16 v[40:43], v[162:165], v[194:197], v[40:43]
	v_mfma_f32_16x16x32_bf16 v[28:31], v[144:147], v[202:205], v[28:31]
	v_mfma_f32_16x16x32_bf16 v[24:27], v[162:165], v[202:205], v[24:27]
	v_mfma_f32_16x16x32_bf16 v[12:15], v[144:147], v[210:213], v[12:15]
	v_mfma_f32_16x16x32_bf16 v[8:11], v[162:165], v[210:213], v[8:11]
	v_mfma_f32_16x16x32_bf16 v[60:63], v[158:161], v[190:193], v[60:63]
	v_mfma_f32_16x16x32_bf16 v[56:59], v[166:169], v[190:193], v[56:59]
	v_mfma_f32_16x16x32_bf16 v[44:47], v[158:161], v[198:201], v[44:47]
	v_mfma_f32_16x16x32_bf16 v[40:43], v[166:169], v[198:201], v[40:43]
	v_mfma_f32_16x16x32_bf16 v[28:31], v[158:161], v[206:209], v[28:31]
	v_mfma_f32_16x16x32_bf16 v[24:27], v[166:169], v[206:209], v[24:27]
	v_mfma_f32_16x16x32_bf16 v[12:15], v[158:161], v[214:217], v[12:15]
	v_mfma_f32_16x16x32_bf16 v[8:11], v[166:169], v[214:217], v[8:11]
	v_mfma_f32_16x16x32_bf16 v[52:55], v[170:173], v[186:189], v[52:55]
	v_mfma_f32_16x16x32_bf16 v[48:51], v[178:181], v[186:189], v[48:51]
	v_mfma_f32_16x16x32_bf16 v[36:39], v[170:173], v[194:197], v[36:39]
	v_mfma_f32_16x16x32_bf16 v[32:35], v[178:181], v[194:197], v[32:35]
	v_mfma_f32_16x16x32_bf16 v[20:23], v[170:173], v[202:205], v[20:23]
	v_mfma_f32_16x16x32_bf16 v[16:19], v[178:181], v[202:205], v[16:19]
	v_mfma_f32_16x16x32_bf16 v[4:7], v[170:173], v[210:213], v[4:7]
	v_mfma_f32_16x16x32_bf16 v[0:3], v[178:181], v[210:213], v[0:3]
	v_mfma_f32_16x16x32_bf16 v[52:55], v[174:177], v[190:193], v[52:55]
	v_mfma_f32_16x16x32_bf16 v[48:51], v[182:185], v[190:193], v[48:51]
	v_mfma_f32_16x16x32_bf16 v[36:39], v[174:177], v[198:201], v[36:39]
	v_mfma_f32_16x16x32_bf16 v[32:35], v[182:185], v[198:201], v[32:35]
	v_mfma_f32_16x16x32_bf16 v[20:23], v[174:177], v[206:209], v[20:23]
	v_mfma_f32_16x16x32_bf16 v[16:19], v[182:185], v[206:209], v[16:19]
	v_mfma_f32_16x16x32_bf16 v[4:7], v[174:177], v[214:217], v[4:7]
	v_mfma_f32_16x16x32_bf16 v[0:3], v[182:185], v[214:217], v[0:3]
	s_barrier
	s_add_i32 s20, 0, 0x18000
	v_add_u32_e32 v157, s20, v152
	s_add_i32 s35, 0, 0x1c000
	ds_read_b128 v[144:147], v157
	ds_read_b128 v[158:161], v157 offset:1024
	ds_read_b128 v[162:165], v157 offset:2048
	ds_read_b128 v[166:169], v157 offset:3072
	v_add_u32_e32 v157, s35, v152
	ds_read_b128 v[170:173], v157
	ds_read_b128 v[174:177], v157 offset:1024
	ds_read_b128 v[178:181], v157 offset:2048
	ds_read_b128 v[182:185], v157 offset:3072
	s_add_u32 s38, s56, 0x40000
	s_addc_u32 s39, s57, 0
	s_mov_b32 m0, s48
	ds_read_b128 v[186:189], v156 offset:32768
	ds_read_b128 v[190:193], v156 offset:33792
	ds_read_b128 v[194:197], v156 offset:34816
	ds_read_b128 v[198:201], v156 offset:35840
	ds_read_b128 v[202:205], v156 offset:36864
	ds_read_b128 v[206:209], v156 offset:37888
	ds_read_b128 v[210:213], v156 offset:38912
	ds_read_b128 v[214:217], v156 offset:39936
	global_load_lds_dwordx4 v128, s[38:39]
	s_mov_b32 m0, s49
	s_nop 0
	global_load_lds_dwordx4 v132, s[38:39]
	s_waitcnt vmcnt(8)
	s_waitcnt lgkmcnt(0)
	s_barrier
	v_mfma_f32_16x16x32_bf16 v[124:127], v[144:147], v[186:189], v[124:127]
	v_mfma_f32_16x16x32_bf16 v[120:123], v[162:165], v[186:189], v[120:123]
	v_mfma_f32_16x16x32_bf16 v[108:111], v[144:147], v[194:197], v[108:111]
	v_mfma_f32_16x16x32_bf16 v[104:107], v[162:165], v[194:197], v[104:107]
	v_mfma_f32_16x16x32_bf16 v[92:95], v[144:147], v[202:205], v[92:95]
	v_mfma_f32_16x16x32_bf16 v[88:91], v[162:165], v[202:205], v[88:91]
	v_mfma_f32_16x16x32_bf16 v[76:79], v[144:147], v[210:213], v[76:79]
	v_mfma_f32_16x16x32_bf16 v[72:75], v[162:165], v[210:213], v[72:75]
	v_mfma_f32_16x16x32_bf16 v[124:127], v[158:161], v[190:193], v[124:127]
	v_mfma_f32_16x16x32_bf16 v[120:123], v[166:169], v[190:193], v[120:123]
	v_mfma_f32_16x16x32_bf16 v[108:111], v[158:161], v[198:201], v[108:111]
	v_mfma_f32_16x16x32_bf16 v[104:107], v[166:169], v[198:201], v[104:107]
	v_mfma_f32_16x16x32_bf16 v[92:95], v[158:161], v[206:209], v[92:95]
	v_mfma_f32_16x16x32_bf16 v[88:91], v[166:169], v[206:209], v[88:91]
	v_mfma_f32_16x16x32_bf16 v[76:79], v[158:161], v[214:217], v[76:79]
	v_mfma_f32_16x16x32_bf16 v[72:75], v[166:169], v[214:217], v[72:75]
	v_mfma_f32_16x16x32_bf16 v[116:119], v[170:173], v[186:189], v[116:119]
	v_mfma_f32_16x16x32_bf16 v[112:115], v[178:181], v[186:189], v[112:115]
	v_mfma_f32_16x16x32_bf16 v[100:103], v[170:173], v[194:197], v[100:103]
	v_mfma_f32_16x16x32_bf16 v[96:99], v[178:181], v[194:197], v[96:99]
	v_mfma_f32_16x16x32_bf16 v[84:87], v[170:173], v[202:205], v[84:87]
	v_mfma_f32_16x16x32_bf16 v[80:83], v[178:181], v[202:205], v[80:83]
	v_mfma_f32_16x16x32_bf16 v[68:71], v[170:173], v[210:213], v[68:71]
	v_mfma_f32_16x16x32_bf16 v[64:67], v[178:181], v[210:213], v[64:67]
	v_mfma_f32_16x16x32_bf16 v[116:119], v[174:177], v[190:193], v[116:119]
	v_mfma_f32_16x16x32_bf16 v[112:115], v[182:185], v[190:193], v[112:115]
	v_mfma_f32_16x16x32_bf16 v[100:103], v[174:177], v[198:201], v[100:103]
	v_mfma_f32_16x16x32_bf16 v[96:99], v[182:185], v[198:201], v[96:99]
	v_mfma_f32_16x16x32_bf16 v[84:87], v[174:177], v[206:209], v[84:87]
	v_mfma_f32_16x16x32_bf16 v[80:83], v[182:185], v[206:209], v[80:83]
	v_mfma_f32_16x16x32_bf16 v[68:71], v[174:177], v[214:217], v[68:71]
	v_mfma_f32_16x16x32_bf16 v[64:67], v[182:185], v[214:217], v[64:67]
	s_barrier
	s_add_i32 s20, s20, s45
	v_lshl_add_u64 v[148:149], v[148:149], 0, s[6:7]
	s_mov_b32 m0, s20
	ds_read_b128 v[186:189], v156 offset:49152
	ds_read_b128 v[190:193], v156 offset:50176
	ds_read_b128 v[194:197], v156 offset:51200
	ds_read_b128 v[198:201], v156 offset:52224
	ds_read_b128 v[202:205], v156 offset:53248
	ds_read_b128 v[206:209], v156 offset:54272
	ds_read_b128 v[210:213], v156 offset:55296
	ds_read_b128 v[214:217], v156 offset:56320
	global_load_lds_dwordx4 v[148:149], off
	s_add_i32 m0, s20, 0x2000
	s_add_u32 s38, s54, 0x40080
	v_lshl_add_u64 v[148:149], v[218:219], 0, s[6:7]
	s_addc_u32 s39, s55, 0
	s_add_i32 s20, s35, s45
	global_load_lds_dwordx4 v[148:149], off
	s_mov_b32 m0, s20
	s_nop 0
	global_load_lds_dwordx4 v130, s[38:39]
	s_add_i32 m0, s20, 0x2000
	s_nop 0
	global_load_lds_dwordx4 v134, s[38:39]
	v_lshl_add_u64 v[148:149], v[220:221], 0, s[6:7]
	s_mov_b32 m0, s51
	s_nop 0
	global_load_lds_dwordx4 v[148:149], off
	v_lshl_add_u64 v[148:149], v[222:223], 0, s[6:7]
	s_mov_b32 m0, s58
	s_nop 0
	global_load_lds_dwordx4 v[148:149], off
	s_waitcnt vmcnt(8)
	s_waitcnt lgkmcnt(0)
	s_barrier
	v_mfma_f32_16x16x32_bf16 v[60:63], v[144:147], v[186:189], v[60:63]
	v_mfma_f32_16x16x32_bf16 v[56:59], v[162:165], v[186:189], v[56:59]
	v_mfma_f32_16x16x32_bf16 v[44:47], v[144:147], v[194:197], v[44:47]
	v_mfma_f32_16x16x32_bf16 v[40:43], v[162:165], v[194:197], v[40:43]
	v_mfma_f32_16x16x32_bf16 v[28:31], v[144:147], v[202:205], v[28:31]
	v_mfma_f32_16x16x32_bf16 v[24:27], v[162:165], v[202:205], v[24:27]
	v_mfma_f32_16x16x32_bf16 v[12:15], v[144:147], v[210:213], v[12:15]
	v_mfma_f32_16x16x32_bf16 v[8:11], v[162:165], v[210:213], v[8:11]
	v_mfma_f32_16x16x32_bf16 v[60:63], v[158:161], v[190:193], v[60:63]
	v_mfma_f32_16x16x32_bf16 v[56:59], v[166:169], v[190:193], v[56:59]
	v_mfma_f32_16x16x32_bf16 v[44:47], v[158:161], v[198:201], v[44:47]
	v_mfma_f32_16x16x32_bf16 v[40:43], v[166:169], v[198:201], v[40:43]
	v_mfma_f32_16x16x32_bf16 v[28:31], v[158:161], v[206:209], v[28:31]
	v_mfma_f32_16x16x32_bf16 v[24:27], v[166:169], v[206:209], v[24:27]
	v_mfma_f32_16x16x32_bf16 v[12:15], v[158:161], v[214:217], v[12:15]
	v_mfma_f32_16x16x32_bf16 v[8:11], v[166:169], v[214:217], v[8:11]
	v_mfma_f32_16x16x32_bf16 v[52:55], v[170:173], v[186:189], v[52:55]
	v_mfma_f32_16x16x32_bf16 v[48:51], v[178:181], v[186:189], v[48:51]
	v_mfma_f32_16x16x32_bf16 v[36:39], v[170:173], v[194:197], v[36:39]
	v_mfma_f32_16x16x32_bf16 v[32:35], v[178:181], v[194:197], v[32:35]
	v_mfma_f32_16x16x32_bf16 v[20:23], v[170:173], v[202:205], v[20:23]
	v_mfma_f32_16x16x32_bf16 v[16:19], v[178:181], v[202:205], v[16:19]
	v_mfma_f32_16x16x32_bf16 v[4:7], v[170:173], v[210:213], v[4:7]
	v_mfma_f32_16x16x32_bf16 v[0:3], v[178:181], v[210:213], v[0:3]
	v_mfma_f32_16x16x32_bf16 v[52:55], v[174:177], v[190:193], v[52:55]
	v_mfma_f32_16x16x32_bf16 v[48:51], v[182:185], v[190:193], v[48:51]
	v_mfma_f32_16x16x32_bf16 v[36:39], v[174:177], v[198:201], v[36:39]
	v_mfma_f32_16x16x32_bf16 v[32:35], v[182:185], v[198:201], v[32:35]
	v_mfma_f32_16x16x32_bf16 v[20:23], v[174:177], v[206:209], v[20:23]
	v_mfma_f32_16x16x32_bf16 v[16:19], v[182:185], v[206:209], v[16:19]
	v_mfma_f32_16x16x32_bf16 v[4:7], v[174:177], v[214:217], v[4:7]
	v_mfma_f32_16x16x32_bf16 v[0:3], v[182:185], v[214:217], v[0:3]
	s_barrier
	s_add_i32 s65, s65, 2
	s_add_u32 s52, s52, 0x100
	s_addc_u32 s53, s53, 0
	s_add_u32 s63, s63, 0x100
	s_addc_u32 s64, s64, 0
	s_cmp_gt_u32 s65, 13
	s_cbranch_scc0 .LBB0_1207
	s_and_b64 vcc, exec, s[8:9]
	s_cbranch_vccz .LBB0_1210
	s_barrier

.LBB0_1411:
	ds_read_b128 v[154:157], v150
	ds_read_b128 v[158:161], v150 offset:1024
	ds_read_b128 v[162:165], v150 offset:2048
	ds_read_b128 v[166:169], v150 offset:3072
	ds_read_b128 v[170:173], v151
	ds_read_b128 v[174:177], v151 offset:1024
	ds_read_b128 v[178:181], v151 offset:2048
	ds_read_b128 v[182:185], v151 offset:3072
	s_add_u32 s20, s44, 0xfffc0080
	s_addc_u32 s35, s45, -1
	s_cmp_eq_u32 s67, 12
	s_cselect_b32 s53, s0, s35
	s_cselect_b32 s52, s1, s20
	s_cselect_b32 s49, s11, s66
	s_cselect_b32 s48, s13, s65
	s_add_i32 m0, s19, 0xc000
	ds_read_b128 v[186:189], v152
	ds_read_b128 v[190:193], v152 offset:1024
	ds_read_b128 v[194:197], v152 offset:2048
	ds_read_b128 v[198:201], v152 offset:3072
	ds_read_b128 v[202:205], v152 offset:4096
	ds_read_b128 v[206:209], v152 offset:5120
	ds_read_b128 v[210:213], v152 offset:6144
	ds_read_b128 v[214:217], v152 offset:7168
	global_load_lds_dwordx4 v136, s[44:45]
	s_add_i32 m0, s19, 0xe000
	s_nop 0
	global_load_lds_dwordx4 v138, s[44:45]
	s_waitcnt vmcnt(8)
	s_waitcnt lgkmcnt(0)
	s_barrier
	v_mfma_f32_16x16x32_bf16 v[124:127], v[154:157], v[186:189], v[124:127]
	v_mfma_f32_16x16x32_bf16 v[120:123], v[162:165], v[186:189], v[120:123]
	v_mfma_f32_16x16x32_bf16 v[108:111], v[154:157], v[194:197], v[108:111]
	v_mfma_f32_16x16x32_bf16 v[104:107], v[162:165], v[194:197], v[104:107]
	v_mfma_f32_16x16x32_bf16 v[92:95], v[154:157], v[202:205], v[92:95]
	v_mfma_f32_16x16x32_bf16 v[88:91], v[162:165], v[202:205], v[88:91]
	v_mfma_f32_16x16x32_bf16 v[76:79], v[154:157], v[210:213], v[76:79]
	v_mfma_f32_16x16x32_bf16 v[72:75], v[162:165], v[210:213], v[72:75]
	v_mfma_f32_16x16x32_bf16 v[124:127], v[158:161], v[190:193], v[124:127]
	v_mfma_f32_16x16x32_bf16 v[120:123], v[166:169], v[190:193], v[120:123]
	v_mfma_f32_16x16x32_bf16 v[108:111], v[158:161], v[198:201], v[108:111]
	v_mfma_f32_16x16x32_bf16 v[104:107], v[166:169], v[198:201], v[104:107]
	v_mfma_f32_16x16x32_bf16 v[92:95], v[158:161], v[206:209], v[92:95]
	v_mfma_f32_16x16x32_bf16 v[88:91], v[166:169], v[206:209], v[88:91]
	v_mfma_f32_16x16x32_bf16 v[76:79], v[158:161], v[214:217], v[76:79]
	v_mfma_f32_16x16x32_bf16 v[72:75], v[166:169], v[214:217], v[72:75]
	v_mfma_f32_16x16x32_bf16 v[116:119], v[170:173], v[186:189], v[116:119]
	v_mfma_f32_16x16x32_bf16 v[112:115], v[178:181], v[186:189], v[112:115]
	v_mfma_f32_16x16x32_bf16 v[100:103], v[170:173], v[194:197], v[100:103]
	v_mfma_f32_16x16x32_bf16 v[96:99], v[178:181], v[194:197], v[96:99]
	v_mfma_f32_16x16x32_bf16 v[84:87], v[170:173], v[202:205], v[84:87]
	v_mfma_f32_16x16x32_bf16 v[80:83], v[178:181], v[202:205], v[80:83]
	v_mfma_f32_16x16x32_bf16 v[68:71], v[170:173], v[210:213], v[68:71]
	v_mfma_f32_16x16x32_bf16 v[64:67], v[178:181], v[210:213], v[64:67]
	v_mfma_f32_16x16x32_bf16 v[116:119], v[174:177], v[190:193], v[116:119]
	v_mfma_f32_16x16x32_bf16 v[112:115], v[182:185], v[190:193], v[112:115]
	v_mfma_f32_16x16x32_bf16 v[100:103], v[174:177], v[198:201], v[100:103]
	v_mfma_f32_16x16x32_bf16 v[96:99], v[182:185], v[198:201], v[96:99]
	v_mfma_f32_16x16x32_bf16 v[84:87], v[174:177], v[206:209], v[84:87]
	v_mfma_f32_16x16x32_bf16 v[80:83], v[182:185], v[206:209], v[80:83]
	v_mfma_f32_16x16x32_bf16 v[68:71], v[174:177], v[214:217], v[68:71]
	v_mfma_f32_16x16x32_bf16 v[64:67], v[182:185], v[214:217], v[64:67]
	s_barrier
	s_add_i32 s20, s61, s46
	v_lshl_add_u64 v[144:145], s[48:49], 0, v[128:129]
	s_mov_b32 m0, s20
	ds_read_b128 v[186:189], v152 offset:16384
	ds_read_b128 v[190:193], v152 offset:17408
	ds_read_b128 v[194:197], v152 offset:18432
	ds_read_b128 v[198:201], v152 offset:19456
	ds_read_b128 v[202:205], v152 offset:20480
	ds_read_b128 v[206:209], v152 offset:21504
	ds_read_b128 v[210:213], v152 offset:22528
	ds_read_b128 v[214:217], v152 offset:23552
	global_load_lds_dwordx4 v[144:145], off
	s_add_i32 m0, s20, 0x2000
	s_add_u32 s38, s48, 0x40000
	v_lshl_add_u64 v[218:219], s[48:49], 0, v[130:131]
	s_addc_u32 s39, s49, 0
	s_add_i32 s20, s62, s46
	global_load_lds_dwordx4 v[218:219], off
	s_mov_b32 m0, s20
	v_lshl_add_u64 v[222:223], s[52:53], 0, v[132:133]
	global_load_lds_dwordx4 v128, s[38:39]
	s_add_i32 m0, s20, 0x2000
	s_nop 0
	global_load_lds_dwordx4 v130, s[38:39]
	v_lshl_add_u64 v[220:221], s[52:53], 0, v[134:135]
	s_mov_b32 m0, s19
	s_nop 0
	global_load_lds_dwordx4 v[220:221], off
	s_mov_b32 m0, s51
	s_nop 0
	global_load_lds_dwordx4 v[222:223], off
	s_waitcnt vmcnt(8)
	s_waitcnt lgkmcnt(0)
	s_barrier
	v_mfma_f32_16x16x32_bf16 v[60:63], v[154:157], v[186:189], v[60:63]
	v_mfma_f32_16x16x32_bf16 v[56:59], v[162:165], v[186:189], v[56:59]
	v_mfma_f32_16x16x32_bf16 v[44:47], v[154:157], v[194:197], v[44:47]
	v_mfma_f32_16x16x32_bf16 v[40:43], v[162:165], v[194:197], v[40:43]
	v_mfma_f32_16x16x32_bf16 v[28:31], v[154:157], v[202:205], v[28:31]
	v_mfma_f32_16x16x32_bf16 v[24:27], v[162:165], v[202:205], v[24:27]
	v_mfma_f32_16x16x32_bf16 v[12:15], v[154:157], v[210:213], v[12:15]
	v_mfma_f32_16x16x32_bf16 v[8:11], v[162:165], v[210:213], v[8:11]
	v_mfma_f32_16x16x32_bf16 v[60:63], v[158:161], v[190:193], v[60:63]
	v_mfma_f32_16x16x32_bf16 v[56:59], v[166:169], v[190:193], v[56:59]
	v_mfma_f32_16x16x32_bf16 v[44:47], v[158:161], v[198:201], v[44:47]
	v_mfma_f32_16x16x32_bf16 v[40:43], v[166:169], v[198:201], v[40:43]
	v_mfma_f32_16x16x32_bf16 v[28:31], v[158:161], v[206:209], v[28:31]
	v_mfma_f32_16x16x32_bf16 v[24:27], v[166:169], v[206:209], v[24:27]
	v_mfma_f32_16x16x32_bf16 v[12:15], v[158:161], v[214:217], v[12:15]
	v_mfma_f32_16x16x32_bf16 v[8:11], v[166:169], v[214:217], v[8:11]
	v_mfma_f32_16x16x32_bf16 v[52:55], v[170:173], v[186:189], v[52:55]
	v_mfma_f32_16x16x32_bf16 v[48:51], v[178:181], v[186:189], v[48:51]
	v_mfma_f32_16x16x32_bf16 v[36:39], v[170:173], v[194:197], v[36:39]
	v_mfma_f32_16x16x32_bf16 v[32:35], v[178:181], v[194:197], v[32:35]
	v_mfma_f32_16x16x32_bf16 v[20:23], v[170:173], v[202:205], v[20:23]
	v_mfma_f32_16x16x32_bf16 v[16:19], v[178:181], v[202:205], v[16:19]
	v_mfma_f32_16x16x32_bf16 v[4:7], v[170:173], v[210:213], v[4:7]
	v_mfma_f32_16x16x32_bf16 v[0:3], v[178:181], v[210:213], v[0:3]
	v_mfma_f32_16x16x32_bf16 v[52:55], v[174:177], v[190:193], v[52:55]
	v_mfma_f32_16x16x32_bf16 v[48:51], v[182:185], v[190:193], v[48:51]
	v_mfma_f32_16x16x32_bf16 v[36:39], v[174:177], v[198:201], v[36:39]
	v_mfma_f32_16x16x32_bf16 v[32:35], v[182:185], v[198:201], v[32:35]
	v_mfma_f32_16x16x32_bf16 v[20:23], v[174:177], v[206:209], v[20:23]
	v_mfma_f32_16x16x32_bf16 v[16:19], v[182:185], v[206:209], v[16:19]
	v_mfma_f32_16x16x32_bf16 v[4:7], v[174:177], v[214:217], v[4:7]
	v_mfma_f32_16x16x32_bf16 v[0:3], v[182:185], v[214:217], v[0:3]
	s_barrier
	s_add_i32 s20, 0, 0x18000
	v_add_u32_e32 v153, s20, v148
	s_add_i32 s35, 0, 0x1c000
	ds_read_b128 v[154:157], v153
	ds_read_b128 v[158:161], v153 offset:1024
	ds_read_b128 v[162:165], v153 offset:2048
	ds_read_b128 v[166:169], v153 offset:3072
	v_add_u32_e32 v153, s35, v148
	ds_read_b128 v[170:173], v153
	ds_read_b128 v[174:177], v153 offset:1024
	ds_read_b128 v[178:181], v153 offset:2048
	ds_read_b128 v[182:185], v153 offset:3072
	s_add_u32 s38, s52, 0x40000
	s_addc_u32 s39, s53, 0
	s_mov_b32 m0, s54
	ds_read_b128 v[186:189], v152 offset:32768
	ds_read_b128 v[190:193], v152 offset:33792
	ds_read_b128 v[194:197], v152 offset:34816
	ds_read_b128 v[198:201], v152 offset:35840
	ds_read_b128 v[202:205], v152 offset:36864
	ds_read_b128 v[206:209], v152 offset:37888
	ds_read_b128 v[210:213], v152 offset:38912
	ds_read_b128 v[214:217], v152 offset:39936
	global_load_lds_dwordx4 v134, s[38:39]
	s_mov_b32 m0, s55
	s_nop 0
	global_load_lds_dwordx4 v132, s[38:39]
	s_waitcnt vmcnt(8)
	s_waitcnt lgkmcnt(0)
	s_barrier
	v_mfma_f32_16x16x32_bf16 v[124:127], v[154:157], v[186:189], v[124:127]
	v_mfma_f32_16x16x32_bf16 v[120:123], v[162:165], v[186:189], v[120:123]
	v_mfma_f32_16x16x32_bf16 v[108:111], v[154:157], v[194:197], v[108:111]
	v_mfma_f32_16x16x32_bf16 v[104:107], v[162:165], v[194:197], v[104:107]
	v_mfma_f32_16x16x32_bf16 v[92:95], v[154:157], v[202:205], v[92:95]
	v_mfma_f32_16x16x32_bf16 v[88:91], v[162:165], v[202:205], v[88:91]
	v_mfma_f32_16x16x32_bf16 v[76:79], v[154:157], v[210:213], v[76:79]
	v_mfma_f32_16x16x32_bf16 v[72:75], v[162:165], v[210:213], v[72:75]
	v_mfma_f32_16x16x32_bf16 v[124:127], v[158:161], v[190:193], v[124:127]
	v_mfma_f32_16x16x32_bf16 v[120:123], v[166:169], v[190:193], v[120:123]
	v_mfma_f32_16x16x32_bf16 v[108:111], v[158:161], v[198:201], v[108:111]
	v_mfma_f32_16x16x32_bf16 v[104:107], v[166:169], v[198:201], v[104:107]
	v_mfma_f32_16x16x32_bf16 v[92:95], v[158:161], v[206:209], v[92:95]
	v_mfma_f32_16x16x32_bf16 v[88:91], v[166:169], v[206:209], v[88:91]
	v_mfma_f32_16x16x32_bf16 v[76:79], v[158:161], v[214:217], v[76:79]
	v_mfma_f32_16x16x32_bf16 v[72:75], v[166:169], v[214:217], v[72:75]
	v_mfma_f32_16x16x32_bf16 v[116:119], v[170:173], v[186:189], v[116:119]
	v_mfma_f32_16x16x32_bf16 v[112:115], v[178:181], v[186:189], v[112:115]
	v_mfma_f32_16x16x32_bf16 v[100:103], v[170:173], v[194:197], v[100:103]
	v_mfma_f32_16x16x32_bf16 v[96:99], v[178:181], v[194:197], v[96:99]
	v_mfma_f32_16x16x32_bf16 v[84:87], v[170:173], v[202:205], v[84:87]
	v_mfma_f32_16x16x32_bf16 v[80:83], v[178:181], v[202:205], v[80:83]
	v_mfma_f32_16x16x32_bf16 v[68:71], v[170:173], v[210:213], v[68:71]
	v_mfma_f32_16x16x32_bf16 v[64:67], v[178:181], v[210:213], v[64:67]
	v_mfma_f32_16x16x32_bf16 v[116:119], v[174:177], v[190:193], v[116:119]
	v_mfma_f32_16x16x32_bf16 v[112:115], v[182:185], v[190:193], v[112:115]
	v_mfma_f32_16x16x32_bf16 v[100:103], v[174:177], v[198:201], v[100:103]
	v_mfma_f32_16x16x32_bf16 v[96:99], v[182:185], v[198:201], v[96:99]
	v_mfma_f32_16x16x32_bf16 v[84:87], v[174:177], v[206:209], v[84:87]
	v_mfma_f32_16x16x32_bf16 v[80:83], v[182:185], v[206:209], v[80:83]
	v_mfma_f32_16x16x32_bf16 v[68:71], v[174:177], v[214:217], v[68:71]
	v_mfma_f32_16x16x32_bf16 v[64:67], v[182:185], v[214:217], v[64:67]
	s_barrier
	s_add_i32 s20, s20, s46
	v_lshl_add_u64 v[144:145], v[144:145], 0, s[6:7]
	s_mov_b32 m0, s20
	ds_read_b128 v[186:189], v152 offset:49152
	ds_read_b128 v[190:193], v152 offset:50176
	ds_read_b128 v[194:197], v152 offset:51200
	ds_read_b128 v[198:201], v152 offset:52224
	ds_read_b128 v[202:205], v152 offset:53248
	ds_read_b128 v[206:209], v152 offset:54272
	ds_read_b128 v[210:213], v152 offset:55296
	ds_read_b128 v[214:217], v152 offset:56320
	global_load_lds_dwordx4 v[144:145], off
	s_add_i32 m0, s20, 0x2000
	s_add_u32 s38, s48, 0x40080
	v_lshl_add_u64 v[144:145], v[218:219], 0, s[6:7]
	s_addc_u32 s39, s49, 0
	s_add_i32 s20, s35, s46
	global_load_lds_dwordx4 v[144:145], off
	s_mov_b32 m0, s20
	s_nop 0
	global_load_lds_dwordx4 v128, s[38:39]
	s_add_i32 m0, s20, 0x2000
	s_nop 0
	global_load_lds_dwordx4 v130, s[38:39]
	v_lshl_add_u64 v[144:145], v[220:221], 0, s[6:7]
	s_mov_b32 m0, s57
	s_nop 0
	global_load_lds_dwordx4 v[144:145], off
	v_lshl_add_u64 v[144:145], v[222:223], 0, s[6:7]
	s_mov_b32 m0, s58
	s_nop 0
	global_load_lds_dwordx4 v[144:145], off
	s_waitcnt vmcnt(8)
	s_waitcnt lgkmcnt(0)
	s_barrier
	v_mfma_f32_16x16x32_bf16 v[60:63], v[154:157], v[186:189], v[60:63]
	v_mfma_f32_16x16x32_bf16 v[56:59], v[162:165], v[186:189], v[56:59]
	v_mfma_f32_16x16x32_bf16 v[44:47], v[154:157], v[194:197], v[44:47]
	v_mfma_f32_16x16x32_bf16 v[40:43], v[162:165], v[194:197], v[40:43]
	v_mfma_f32_16x16x32_bf16 v[28:31], v[154:157], v[202:205], v[28:31]
	v_mfma_f32_16x16x32_bf16 v[24:27], v[162:165], v[202:205], v[24:27]
	v_mfma_f32_16x16x32_bf16 v[12:15], v[154:157], v[210:213], v[12:15]
	v_mfma_f32_16x16x32_bf16 v[8:11], v[162:165], v[210:213], v[8:11]
	v_mfma_f32_16x16x32_bf16 v[60:63], v[158:161], v[190:193], v[60:63]
	v_mfma_f32_16x16x32_bf16 v[56:59], v[166:169], v[190:193], v[56:59]
	v_mfma_f32_16x16x32_bf16 v[44:47], v[158:161], v[198:201], v[44:47]
	v_mfma_f32_16x16x32_bf16 v[40:43], v[166:169], v[198:201], v[40:43]
	v_mfma_f32_16x16x32_bf16 v[28:31], v[158:161], v[206:209], v[28:31]
	v_mfma_f32_16x16x32_bf16 v[24:27], v[166:169], v[206:209], v[24:27]
	v_mfma_f32_16x16x32_bf16 v[12:15], v[158:161], v[214:217], v[12:15]
	v_mfma_f32_16x16x32_bf16 v[8:11], v[166:169], v[214:217], v[8:11]
	v_mfma_f32_16x16x32_bf16 v[52:55], v[170:173], v[186:189], v[52:55]
	v_mfma_f32_16x16x32_bf16 v[48:51], v[178:181], v[186:189], v[48:51]
	v_mfma_f32_16x16x32_bf16 v[36:39], v[170:173], v[194:197], v[36:39]
	v_mfma_f32_16x16x32_bf16 v[32:35], v[178:181], v[194:197], v[32:35]
	v_mfma_f32_16x16x32_bf16 v[20:23], v[170:173], v[202:205], v[20:23]
	v_mfma_f32_16x16x32_bf16 v[16:19], v[178:181], v[202:205], v[16:19]
	v_mfma_f32_16x16x32_bf16 v[4:7], v[170:173], v[210:213], v[4:7]
	v_mfma_f32_16x16x32_bf16 v[0:3], v[178:181], v[210:213], v[0:3]
	v_mfma_f32_16x16x32_bf16 v[52:55], v[174:177], v[190:193], v[52:55]
	v_mfma_f32_16x16x32_bf16 v[48:51], v[182:185], v[190:193], v[48:51]
	v_mfma_f32_16x16x32_bf16 v[36:39], v[174:177], v[198:201], v[36:39]
	v_mfma_f32_16x16x32_bf16 v[32:35], v[182:185], v[198:201], v[32:35]
	v_mfma_f32_16x16x32_bf16 v[20:23], v[174:177], v[206:209], v[20:23]
	v_mfma_f32_16x16x32_bf16 v[16:19], v[182:185], v[206:209], v[16:19]
	v_mfma_f32_16x16x32_bf16 v[4:7], v[174:177], v[214:217], v[4:7]
	v_mfma_f32_16x16x32_bf16 v[0:3], v[182:185], v[214:217], v[0:3]
	s_barrier
	s_add_i32 s67, s67, 2
	s_add_u32 s44, s44, 0x100
	s_addc_u32 s45, s45, 0
	s_add_u32 s65, s65, 0x100
	s_addc_u32 s66, s66, 0
	s_cmp_gt_u32 s67, 13
	s_cbranch_scc0 .LBB0_1411
	s_and_b64 vcc, exec, s[8:9]
	s_cbranch_vccz .LBB0_1414
	s_barrier

.LBB0_1491:
	ds_read_b128 v[154:157], v150
	ds_read_b128 v[158:161], v150 offset:1024
	ds_read_b128 v[162:165], v150 offset:2048
	ds_read_b128 v[166:169], v150 offset:3072
	ds_read_b128 v[170:173], v151
	ds_read_b128 v[174:177], v151 offset:1024
	ds_read_b128 v[178:181], v151 offset:2048
	ds_read_b128 v[182:185], v151 offset:3072
	s_add_u32 s16, s14, 0x100
	s_addc_u32 s17, s15, 0
	s_cmp_eq_u32 s63, 40
	s_cselect_b32 s45, s5, s17
	s_cselect_b32 s44, s4, s16
	s_cselect_b32 s19, s13, s1
	s_cselect_b32 s18, s12, s0
	s_add_i32 m0, s48, 0xc000
	ds_read_b128 v[186:189], v152
	ds_read_b128 v[190:193], v152 offset:1024
	ds_read_b128 v[194:197], v152 offset:2048
	ds_read_b128 v[198:201], v152 offset:3072
	ds_read_b128 v[202:205], v152 offset:4096
	ds_read_b128 v[206:209], v152 offset:5120
	ds_read_b128 v[210:213], v152 offset:6144
	ds_read_b128 v[214:217], v152 offset:7168
	global_load_lds_dwordx4 v136, s[14:15]
	s_add_i32 m0, s48, 0xe000
	s_nop 0
	global_load_lds_dwordx4 v138, s[14:15]
	s_waitcnt vmcnt(8)
	s_waitcnt lgkmcnt(0)
	s_barrier
	v_mfma_f32_16x16x32_bf16 v[124:127], v[154:157], v[186:189], v[124:127]
	v_mfma_f32_16x16x32_bf16 v[120:123], v[162:165], v[186:189], v[120:123]
	v_mfma_f32_16x16x32_bf16 v[112:115], v[154:157], v[194:197], v[112:115]
	v_mfma_f32_16x16x32_bf16 v[104:107], v[162:165], v[194:197], v[104:107]
	v_mfma_f32_16x16x32_bf16 v[96:99], v[154:157], v[202:205], v[96:99]
	v_mfma_f32_16x16x32_bf16 v[88:91], v[162:165], v[202:205], v[88:91]
	v_mfma_f32_16x16x32_bf16 v[80:83], v[154:157], v[210:213], v[80:83]
	v_mfma_f32_16x16x32_bf16 v[72:75], v[162:165], v[210:213], v[72:75]
	v_mfma_f32_16x16x32_bf16 v[124:127], v[158:161], v[190:193], v[124:127]
	v_mfma_f32_16x16x32_bf16 v[120:123], v[166:169], v[190:193], v[120:123]
	v_mfma_f32_16x16x32_bf16 v[112:115], v[158:161], v[198:201], v[112:115]
	v_mfma_f32_16x16x32_bf16 v[104:107], v[166:169], v[198:201], v[104:107]
	v_mfma_f32_16x16x32_bf16 v[96:99], v[158:161], v[206:209], v[96:99]
	v_mfma_f32_16x16x32_bf16 v[88:91], v[166:169], v[206:209], v[88:91]
	v_mfma_f32_16x16x32_bf16 v[80:83], v[158:161], v[214:217], v[80:83]
	v_mfma_f32_16x16x32_bf16 v[72:75], v[166:169], v[214:217], v[72:75]
	v_mfma_f32_16x16x32_bf16 v[116:119], v[170:173], v[186:189], v[116:119]
	v_mfma_f32_16x16x32_bf16 v[108:111], v[178:181], v[186:189], v[108:111]
	v_mfma_f32_16x16x32_bf16 v[100:103], v[170:173], v[194:197], v[100:103]
	v_mfma_f32_16x16x32_bf16 v[92:95], v[178:181], v[194:197], v[92:95]
	v_mfma_f32_16x16x32_bf16 v[84:87], v[170:173], v[202:205], v[84:87]
	v_mfma_f32_16x16x32_bf16 v[76:79], v[178:181], v[202:205], v[76:79]
	v_mfma_f32_16x16x32_bf16 v[68:71], v[170:173], v[210:213], v[68:71]
	v_mfma_f32_16x16x32_bf16 v[64:67], v[178:181], v[210:213], v[64:67]
	v_mfma_f32_16x16x32_bf16 v[116:119], v[174:177], v[190:193], v[116:119]
	v_mfma_f32_16x16x32_bf16 v[108:111], v[182:185], v[190:193], v[108:111]
	v_mfma_f32_16x16x32_bf16 v[100:103], v[174:177], v[198:201], v[100:103]
	v_mfma_f32_16x16x32_bf16 v[92:95], v[182:185], v[198:201], v[92:95]
	v_mfma_f32_16x16x32_bf16 v[84:87], v[174:177], v[206:209], v[84:87]
	v_mfma_f32_16x16x32_bf16 v[76:79], v[182:185], v[206:209], v[76:79]
	v_mfma_f32_16x16x32_bf16 v[68:71], v[174:177], v[214:217], v[68:71]
	v_mfma_f32_16x16x32_bf16 v[64:67], v[182:185], v[214:217], v[64:67]
	s_barrier
	s_add_i32 s14, s57, s47
	v_lshl_add_u64 v[144:145], s[18:19], 0, v[130:131]
	s_mov_b32 m0, s14
	ds_read_b128 v[186:189], v152 offset:16384
	ds_read_b128 v[190:193], v152 offset:17408
	ds_read_b128 v[194:197], v152 offset:18432
	ds_read_b128 v[198:201], v152 offset:19456
	ds_read_b128 v[202:205], v152 offset:20480
	ds_read_b128 v[206:209], v152 offset:21504
	ds_read_b128 v[210:213], v152 offset:22528
	ds_read_b128 v[214:217], v152 offset:23552
	global_load_lds_dwordx4 v[144:145], off
	s_add_i32 m0, s14, 0x2000
	s_add_u32 s14, s18, 0xb0000
	v_lshl_add_u64 v[218:219], s[18:19], 0, v[134:135]
	s_addc_u32 s15, s19, 0
	s_add_i32 s20, s58, s47
	global_load_lds_dwordx4 v[218:219], off
	s_mov_b32 m0, s20
	v_lshl_add_u64 v[222:223], s[44:45], 0, v[132:133]
	global_load_lds_dwordx4 v130, s[14:15]
	s_add_i32 m0, s20, 0x2000
	s_nop 0
	global_load_lds_dwordx4 v134, s[14:15]
	v_lshl_add_u64 v[220:221], s[44:45], 0, v[128:129]
	s_mov_b32 m0, s48
	s_nop 0
	global_load_lds_dwordx4 v[220:221], off
	s_mov_b32 m0, s49
	s_nop 0
	global_load_lds_dwordx4 v[222:223], off
	s_waitcnt vmcnt(8)
	s_waitcnt lgkmcnt(0)
	s_barrier
	v_mfma_f32_16x16x32_bf16 v[60:63], v[154:157], v[186:189], v[60:63]
	v_mfma_f32_16x16x32_bf16 v[56:59], v[162:165], v[186:189], v[56:59]
	v_mfma_f32_16x16x32_bf16 v[48:51], v[154:157], v[194:197], v[48:51]
	v_mfma_f32_16x16x32_bf16 v[40:43], v[162:165], v[194:197], v[40:43]
	v_mfma_f32_16x16x32_bf16 v[32:35], v[154:157], v[202:205], v[32:35]
	v_mfma_f32_16x16x32_bf16 v[24:27], v[162:165], v[202:205], v[24:27]
	v_mfma_f32_16x16x32_bf16 v[16:19], v[154:157], v[210:213], v[16:19]
	v_mfma_f32_16x16x32_bf16 v[8:11], v[162:165], v[210:213], v[8:11]
	v_mfma_f32_16x16x32_bf16 v[60:63], v[158:161], v[190:193], v[60:63]
	v_mfma_f32_16x16x32_bf16 v[56:59], v[166:169], v[190:193], v[56:59]
	v_mfma_f32_16x16x32_bf16 v[48:51], v[158:161], v[198:201], v[48:51]
	v_mfma_f32_16x16x32_bf16 v[40:43], v[166:169], v[198:201], v[40:43]
	v_mfma_f32_16x16x32_bf16 v[32:35], v[158:161], v[206:209], v[32:35]
	v_mfma_f32_16x16x32_bf16 v[24:27], v[166:169], v[206:209], v[24:27]
	v_mfma_f32_16x16x32_bf16 v[16:19], v[158:161], v[214:217], v[16:19]
	v_mfma_f32_16x16x32_bf16 v[8:11], v[166:169], v[214:217], v[8:11]
	v_mfma_f32_16x16x32_bf16 v[52:55], v[170:173], v[186:189], v[52:55]
	v_mfma_f32_16x16x32_bf16 v[44:47], v[178:181], v[186:189], v[44:47]
	v_mfma_f32_16x16x32_bf16 v[36:39], v[170:173], v[194:197], v[36:39]
	v_mfma_f32_16x16x32_bf16 v[28:31], v[178:181], v[194:197], v[28:31]
	v_mfma_f32_16x16x32_bf16 v[20:23], v[170:173], v[202:205], v[20:23]
	v_mfma_f32_16x16x32_bf16 v[12:15], v[178:181], v[202:205], v[12:15]
	v_mfma_f32_16x16x32_bf16 v[4:7], v[170:173], v[210:213], v[4:7]
	v_mfma_f32_16x16x32_bf16 v[0:3], v[178:181], v[210:213], v[0:3]
	v_mfma_f32_16x16x32_bf16 v[52:55], v[174:177], v[190:193], v[52:55]
	v_mfma_f32_16x16x32_bf16 v[44:47], v[182:185], v[190:193], v[44:47]
	v_mfma_f32_16x16x32_bf16 v[36:39], v[174:177], v[198:201], v[36:39]
	v_mfma_f32_16x16x32_bf16 v[28:31], v[182:185], v[198:201], v[28:31]
	v_mfma_f32_16x16x32_bf16 v[20:23], v[174:177], v[206:209], v[20:23]
	v_mfma_f32_16x16x32_bf16 v[12:15], v[182:185], v[206:209], v[12:15]
	v_mfma_f32_16x16x32_bf16 v[4:7], v[174:177], v[214:217], v[4:7]
	v_mfma_f32_16x16x32_bf16 v[0:3], v[182:185], v[214:217], v[0:3]
	s_barrier
	s_add_i32 s20, 0, 0x18000
	v_add_u32_e32 v153, s20, v148
	s_add_i32 s35, 0, 0x1c000
	ds_read_b128 v[154:157], v153
	ds_read_b128 v[158:161], v153 offset:1024
	ds_read_b128 v[162:165], v153 offset:2048
	ds_read_b128 v[166:169], v153 offset:3072
	v_add_u32_e32 v153, s35, v148
	ds_read_b128 v[170:173], v153
	ds_read_b128 v[174:177], v153 offset:1024
	ds_read_b128 v[178:181], v153 offset:2048
	ds_read_b128 v[182:185], v153 offset:3072
	s_add_u32 s14, s44, 0xb0000
	s_addc_u32 s15, s45, 0
	s_mov_b32 m0, s50
	ds_read_b128 v[186:189], v152 offset:32768
	ds_read_b128 v[190:193], v152 offset:33792
	ds_read_b128 v[194:197], v152 offset:34816
	ds_read_b128 v[198:201], v152 offset:35840
	ds_read_b128 v[202:205], v152 offset:36864
	ds_read_b128 v[206:209], v152 offset:37888
	ds_read_b128 v[210:213], v152 offset:38912
	ds_read_b128 v[214:217], v152 offset:39936
	global_load_lds_dwordx4 v128, s[14:15]
	s_mov_b32 m0, s51
	s_nop 0
	global_load_lds_dwordx4 v132, s[14:15]
	s_waitcnt vmcnt(8)
	s_waitcnt lgkmcnt(0)
	s_barrier
	v_mfma_f32_16x16x32_bf16 v[124:127], v[154:157], v[186:189], v[124:127]
	v_mfma_f32_16x16x32_bf16 v[120:123], v[162:165], v[186:189], v[120:123]
	v_mfma_f32_16x16x32_bf16 v[112:115], v[154:157], v[194:197], v[112:115]
	v_mfma_f32_16x16x32_bf16 v[104:107], v[162:165], v[194:197], v[104:107]
	v_mfma_f32_16x16x32_bf16 v[96:99], v[154:157], v[202:205], v[96:99]
	v_mfma_f32_16x16x32_bf16 v[88:91], v[162:165], v[202:205], v[88:91]
	v_mfma_f32_16x16x32_bf16 v[80:83], v[154:157], v[210:213], v[80:83]
	v_mfma_f32_16x16x32_bf16 v[72:75], v[162:165], v[210:213], v[72:75]
	v_mfma_f32_16x16x32_bf16 v[124:127], v[158:161], v[190:193], v[124:127]
	v_mfma_f32_16x16x32_bf16 v[120:123], v[166:169], v[190:193], v[120:123]
	v_mfma_f32_16x16x32_bf16 v[112:115], v[158:161], v[198:201], v[112:115]
	v_mfma_f32_16x16x32_bf16 v[104:107], v[166:169], v[198:201], v[104:107]
	v_mfma_f32_16x16x32_bf16 v[96:99], v[158:161], v[206:209], v[96:99]
	v_mfma_f32_16x16x32_bf16 v[88:91], v[166:169], v[206:209], v[88:91]
	v_mfma_f32_16x16x32_bf16 v[80:83], v[158:161], v[214:217], v[80:83]
	v_mfma_f32_16x16x32_bf16 v[72:75], v[166:169], v[214:217], v[72:75]
	v_mfma_f32_16x16x32_bf16 v[116:119], v[170:173], v[186:189], v[116:119]
	v_mfma_f32_16x16x32_bf16 v[108:111], v[178:181], v[186:189], v[108:111]
	v_mfma_f32_16x16x32_bf16 v[100:103], v[170:173], v[194:197], v[100:103]
	v_mfma_f32_16x16x32_bf16 v[92:95], v[178:181], v[194:197], v[92:95]
	v_mfma_f32_16x16x32_bf16 v[84:87], v[170:173], v[202:205], v[84:87]
	v_mfma_f32_16x16x32_bf16 v[76:79], v[178:181], v[202:205], v[76:79]
	v_mfma_f32_16x16x32_bf16 v[68:71], v[170:173], v[210:213], v[68:71]
	v_mfma_f32_16x16x32_bf16 v[64:67], v[178:181], v[210:213], v[64:67]
	v_mfma_f32_16x16x32_bf16 v[116:119], v[174:177], v[190:193], v[116:119]
	v_mfma_f32_16x16x32_bf16 v[108:111], v[182:185], v[190:193], v[108:111]
	v_mfma_f32_16x16x32_bf16 v[100:103], v[174:177], v[198:201], v[100:103]
	v_mfma_f32_16x16x32_bf16 v[92:95], v[182:185], v[198:201], v[92:95]
	v_mfma_f32_16x16x32_bf16 v[84:87], v[174:177], v[206:209], v[84:87]
	v_mfma_f32_16x16x32_bf16 v[76:79], v[182:185], v[206:209], v[76:79]
	v_mfma_f32_16x16x32_bf16 v[68:71], v[174:177], v[214:217], v[68:71]
	v_mfma_f32_16x16x32_bf16 v[64:67], v[182:185], v[214:217], v[64:67]
	s_barrier
	s_add_i32 s14, s20, s47
	v_lshl_add_u64 v[144:145], v[144:145], 0, s[8:9]
	s_mov_b32 m0, s14
	ds_read_b128 v[186:189], v152 offset:49152
	ds_read_b128 v[190:193], v152 offset:50176
	ds_read_b128 v[194:197], v152 offset:51200
	ds_read_b128 v[198:201], v152 offset:52224
	ds_read_b128 v[202:205], v152 offset:53248
	ds_read_b128 v[206:209], v152 offset:54272
	ds_read_b128 v[210:213], v152 offset:55296
	ds_read_b128 v[214:217], v152 offset:56320
	global_load_lds_dwordx4 v[144:145], off
	s_add_i32 m0, s14, 0x2000
	s_add_u32 s14, s18, 0xb0080
	v_lshl_add_u64 v[144:145], v[218:219], 0, s[8:9]
	s_addc_u32 s15, s19, 0
	s_add_i32 s18, s35, s47
	global_load_lds_dwordx4 v[144:145], off
	s_mov_b32 m0, s18
	s_nop 0
	global_load_lds_dwordx4 v130, s[14:15]
	s_add_i32 m0, s18, 0x2000
	s_nop 0
	global_load_lds_dwordx4 v134, s[14:15]
	v_lshl_add_u64 v[144:145], v[220:221], 0, s[8:9]
	s_mov_b32 m0, s53
	s_nop 0
	global_load_lds_dwordx4 v[144:145], off
	v_lshl_add_u64 v[144:145], v[222:223], 0, s[8:9]
	s_mov_b32 m0, s54
	s_nop 0
	global_load_lds_dwordx4 v[144:145], off
	s_waitcnt vmcnt(8)
	s_waitcnt lgkmcnt(0)
	s_barrier
	v_mfma_f32_16x16x32_bf16 v[60:63], v[154:157], v[186:189], v[60:63]
	v_mfma_f32_16x16x32_bf16 v[56:59], v[162:165], v[186:189], v[56:59]
	v_mfma_f32_16x16x32_bf16 v[48:51], v[154:157], v[194:197], v[48:51]
	v_mfma_f32_16x16x32_bf16 v[40:43], v[162:165], v[194:197], v[40:43]
	v_mfma_f32_16x16x32_bf16 v[32:35], v[154:157], v[202:205], v[32:35]
	v_mfma_f32_16x16x32_bf16 v[24:27], v[162:165], v[202:205], v[24:27]
	v_mfma_f32_16x16x32_bf16 v[16:19], v[154:157], v[210:213], v[16:19]
	v_mfma_f32_16x16x32_bf16 v[8:11], v[162:165], v[210:213], v[8:11]
	v_mfma_f32_16x16x32_bf16 v[60:63], v[158:161], v[190:193], v[60:63]
	v_mfma_f32_16x16x32_bf16 v[56:59], v[166:169], v[190:193], v[56:59]
	v_mfma_f32_16x16x32_bf16 v[48:51], v[158:161], v[198:201], v[48:51]
	v_mfma_f32_16x16x32_bf16 v[40:43], v[166:169], v[198:201], v[40:43]
	v_mfma_f32_16x16x32_bf16 v[32:35], v[158:161], v[206:209], v[32:35]
	v_mfma_f32_16x16x32_bf16 v[24:27], v[166:169], v[206:209], v[24:27]
	v_mfma_f32_16x16x32_bf16 v[16:19], v[158:161], v[214:217], v[16:19]
	v_mfma_f32_16x16x32_bf16 v[8:11], v[166:169], v[214:217], v[8:11]
	v_mfma_f32_16x16x32_bf16 v[52:55], v[170:173], v[186:189], v[52:55]
	v_mfma_f32_16x16x32_bf16 v[44:47], v[178:181], v[186:189], v[44:47]
	v_mfma_f32_16x16x32_bf16 v[36:39], v[170:173], v[194:197], v[36:39]
	v_mfma_f32_16x16x32_bf16 v[28:31], v[178:181], v[194:197], v[28:31]
	v_mfma_f32_16x16x32_bf16 v[20:23], v[170:173], v[202:205], v[20:23]
	v_mfma_f32_16x16x32_bf16 v[12:15], v[178:181], v[202:205], v[12:15]
	v_mfma_f32_16x16x32_bf16 v[4:7], v[170:173], v[210:213], v[4:7]
	v_mfma_f32_16x16x32_bf16 v[0:3], v[178:181], v[210:213], v[0:3]
	v_mfma_f32_16x16x32_bf16 v[52:55], v[174:177], v[190:193], v[52:55]
	v_mfma_f32_16x16x32_bf16 v[44:47], v[182:185], v[190:193], v[44:47]
	v_mfma_f32_16x16x32_bf16 v[36:39], v[174:177], v[198:201], v[36:39]
	v_mfma_f32_16x16x32_bf16 v[28:31], v[182:185], v[198:201], v[28:31]
	v_mfma_f32_16x16x32_bf16 v[20:23], v[174:177], v[206:209], v[20:23]
	v_mfma_f32_16x16x32_bf16 v[12:15], v[182:185], v[206:209], v[12:15]
	v_mfma_f32_16x16x32_bf16 v[4:7], v[174:177], v[214:217], v[4:7]
	v_mfma_f32_16x16x32_bf16 v[0:3], v[182:185], v[214:217], v[0:3]
	s_barrier
	s_add_i32 s63, s63, 2
	s_add_u32 s0, s0, 0x100
	s_addc_u32 s1, s1, 0
	s_cmp_gt_u32 s63, 41
	s_mov_b64 s[14:15], s[16:17]
	s_cbranch_scc0 .LBB0_1491
	s_and_b64 vcc, exec, s[10:11]
	s_cbranch_vccz .LBB0_1494
	s_barrier

.LBB0_1626:
	ds_read_b128 v[154:157], v150
	ds_read_b128 v[158:161], v150 offset:1024
	ds_read_b128 v[162:165], v150 offset:2048
	ds_read_b128 v[166:169], v150 offset:3072
	ds_read_b128 v[170:173], v151
	ds_read_b128 v[174:177], v151 offset:1024
	ds_read_b128 v[178:181], v151 offset:2048
	ds_read_b128 v[182:185], v151 offset:3072
	s_add_u32 s20, s44, 0xfffc0080
	s_addc_u32 s35, s45, -1
	s_cmp_eq_u32 s65, 12
	s_cselect_b32 s53, s0, s35
	s_cselect_b32 s52, s1, s20
	s_cselect_b32 s49, s11, s64
	s_cselect_b32 s48, s13, s63
	s_add_i32 m0, s19, 0xc000
	ds_read_b128 v[186:189], v152
	ds_read_b128 v[190:193], v152 offset:1024
	ds_read_b128 v[194:197], v152 offset:2048
	ds_read_b128 v[198:201], v152 offset:3072
	ds_read_b128 v[202:205], v152 offset:4096
	ds_read_b128 v[206:209], v152 offset:5120
	ds_read_b128 v[210:213], v152 offset:6144
	ds_read_b128 v[214:217], v152 offset:7168
	global_load_lds_dwordx4 v136, s[44:45]
	s_add_i32 m0, s19, 0xe000
	s_nop 0
	global_load_lds_dwordx4 v138, s[44:45]
	s_waitcnt vmcnt(8)
	s_waitcnt lgkmcnt(0)
	s_barrier
	v_mfma_f32_16x16x32_bf16 v[124:127], v[154:157], v[186:189], v[124:127]
	v_mfma_f32_16x16x32_bf16 v[120:123], v[162:165], v[186:189], v[120:123]
	v_mfma_f32_16x16x32_bf16 v[112:115], v[154:157], v[194:197], v[112:115]
	v_mfma_f32_16x16x32_bf16 v[104:107], v[162:165], v[194:197], v[104:107]
	v_mfma_f32_16x16x32_bf16 v[96:99], v[154:157], v[202:205], v[96:99]
	v_mfma_f32_16x16x32_bf16 v[88:91], v[162:165], v[202:205], v[88:91]
	v_mfma_f32_16x16x32_bf16 v[80:83], v[154:157], v[210:213], v[80:83]
	v_mfma_f32_16x16x32_bf16 v[72:75], v[162:165], v[210:213], v[72:75]
	v_mfma_f32_16x16x32_bf16 v[124:127], v[158:161], v[190:193], v[124:127]
	v_mfma_f32_16x16x32_bf16 v[120:123], v[166:169], v[190:193], v[120:123]
	v_mfma_f32_16x16x32_bf16 v[112:115], v[158:161], v[198:201], v[112:115]
	v_mfma_f32_16x16x32_bf16 v[104:107], v[166:169], v[198:201], v[104:107]
	v_mfma_f32_16x16x32_bf16 v[96:99], v[158:161], v[206:209], v[96:99]
	v_mfma_f32_16x16x32_bf16 v[88:91], v[166:169], v[206:209], v[88:91]
	v_mfma_f32_16x16x32_bf16 v[80:83], v[158:161], v[214:217], v[80:83]
	v_mfma_f32_16x16x32_bf16 v[72:75], v[166:169], v[214:217], v[72:75]
	v_mfma_f32_16x16x32_bf16 v[116:119], v[170:173], v[186:189], v[116:119]
	v_mfma_f32_16x16x32_bf16 v[108:111], v[178:181], v[186:189], v[108:111]
	v_mfma_f32_16x16x32_bf16 v[100:103], v[170:173], v[194:197], v[100:103]
	v_mfma_f32_16x16x32_bf16 v[92:95], v[178:181], v[194:197], v[92:95]
	v_mfma_f32_16x16x32_bf16 v[84:87], v[170:173], v[202:205], v[84:87]
	v_mfma_f32_16x16x32_bf16 v[76:79], v[178:181], v[202:205], v[76:79]
	v_mfma_f32_16x16x32_bf16 v[68:71], v[170:173], v[210:213], v[68:71]
	v_mfma_f32_16x16x32_bf16 v[64:67], v[178:181], v[210:213], v[64:67]
	v_mfma_f32_16x16x32_bf16 v[116:119], v[174:177], v[190:193], v[116:119]
	v_mfma_f32_16x16x32_bf16 v[108:111], v[182:185], v[190:193], v[108:111]
	v_mfma_f32_16x16x32_bf16 v[100:103], v[174:177], v[198:201], v[100:103]
	v_mfma_f32_16x16x32_bf16 v[92:95], v[182:185], v[198:201], v[92:95]
	v_mfma_f32_16x16x32_bf16 v[84:87], v[174:177], v[206:209], v[84:87]
	v_mfma_f32_16x16x32_bf16 v[76:79], v[182:185], v[206:209], v[76:79]
	v_mfma_f32_16x16x32_bf16 v[68:71], v[174:177], v[214:217], v[68:71]
	v_mfma_f32_16x16x32_bf16 v[64:67], v[182:185], v[214:217], v[64:67]
	s_barrier
	s_add_i32 s20, s60, s47
	v_lshl_add_u64 v[144:145], s[48:49], 0, v[130:131]
	s_mov_b32 m0, s20
	ds_read_b128 v[186:189], v152 offset:16384
	ds_read_b128 v[190:193], v152 offset:17408
	ds_read_b128 v[194:197], v152 offset:18432
	ds_read_b128 v[198:201], v152 offset:19456
	ds_read_b128 v[202:205], v152 offset:20480
	ds_read_b128 v[206:209], v152 offset:21504
	ds_read_b128 v[210:213], v152 offset:22528
	ds_read_b128 v[214:217], v152 offset:23552
	global_load_lds_dwordx4 v[144:145], off
	s_add_i32 m0, s20, 0x2000
	s_add_u32 s38, s48, 0x40000
	v_lshl_add_u64 v[218:219], s[48:49], 0, v[134:135]
	s_addc_u32 s39, s49, 0
	s_add_i32 s20, s61, s47
	global_load_lds_dwordx4 v[218:219], off
	s_mov_b32 m0, s20
	v_lshl_add_u64 v[222:223], s[52:53], 0, v[132:133]
	global_load_lds_dwordx4 v130, s[38:39]
	s_add_i32 m0, s20, 0x2000
	s_nop 0
	global_load_lds_dwordx4 v134, s[38:39]
	v_lshl_add_u64 v[220:221], s[52:53], 0, v[128:129]
	s_mov_b32 m0, s19
	s_nop 0
	global_load_lds_dwordx4 v[220:221], off
	s_mov_b32 m0, s50
	s_nop 0
	global_load_lds_dwordx4 v[222:223], off
	s_waitcnt vmcnt(8)
	s_waitcnt lgkmcnt(0)
	s_barrier
	v_mfma_f32_16x16x32_bf16 v[60:63], v[154:157], v[186:189], v[60:63]
	v_mfma_f32_16x16x32_bf16 v[56:59], v[162:165], v[186:189], v[56:59]
	v_mfma_f32_16x16x32_bf16 v[48:51], v[154:157], v[194:197], v[48:51]
	v_mfma_f32_16x16x32_bf16 v[40:43], v[162:165], v[194:197], v[40:43]
	v_mfma_f32_16x16x32_bf16 v[32:35], v[154:157], v[202:205], v[32:35]
	v_mfma_f32_16x16x32_bf16 v[24:27], v[162:165], v[202:205], v[24:27]
	v_mfma_f32_16x16x32_bf16 v[16:19], v[154:157], v[210:213], v[16:19]
	v_mfma_f32_16x16x32_bf16 v[8:11], v[162:165], v[210:213], v[8:11]
	v_mfma_f32_16x16x32_bf16 v[60:63], v[158:161], v[190:193], v[60:63]
	v_mfma_f32_16x16x32_bf16 v[56:59], v[166:169], v[190:193], v[56:59]
	v_mfma_f32_16x16x32_bf16 v[48:51], v[158:161], v[198:201], v[48:51]
	v_mfma_f32_16x16x32_bf16 v[40:43], v[166:169], v[198:201], v[40:43]
	v_mfma_f32_16x16x32_bf16 v[32:35], v[158:161], v[206:209], v[32:35]
	v_mfma_f32_16x16x32_bf16 v[24:27], v[166:169], v[206:209], v[24:27]
	v_mfma_f32_16x16x32_bf16 v[16:19], v[158:161], v[214:217], v[16:19]
	v_mfma_f32_16x16x32_bf16 v[8:11], v[166:169], v[214:217], v[8:11]
	v_mfma_f32_16x16x32_bf16 v[52:55], v[170:173], v[186:189], v[52:55]
	v_mfma_f32_16x16x32_bf16 v[44:47], v[178:181], v[186:189], v[44:47]
	v_mfma_f32_16x16x32_bf16 v[36:39], v[170:173], v[194:197], v[36:39]
	v_mfma_f32_16x16x32_bf16 v[28:31], v[178:181], v[194:197], v[28:31]
	v_mfma_f32_16x16x32_bf16 v[20:23], v[170:173], v[202:205], v[20:23]
	v_mfma_f32_16x16x32_bf16 v[12:15], v[178:181], v[202:205], v[12:15]
	v_mfma_f32_16x16x32_bf16 v[4:7], v[170:173], v[210:213], v[4:7]
	v_mfma_f32_16x16x32_bf16 v[0:3], v[178:181], v[210:213], v[0:3]
	v_mfma_f32_16x16x32_bf16 v[52:55], v[174:177], v[190:193], v[52:55]
	v_mfma_f32_16x16x32_bf16 v[44:47], v[182:185], v[190:193], v[44:47]
	v_mfma_f32_16x16x32_bf16 v[36:39], v[174:177], v[198:201], v[36:39]
	v_mfma_f32_16x16x32_bf16 v[28:31], v[182:185], v[198:201], v[28:31]
	v_mfma_f32_16x16x32_bf16 v[20:23], v[174:177], v[206:209], v[20:23]
	v_mfma_f32_16x16x32_bf16 v[12:15], v[182:185], v[206:209], v[12:15]
	v_mfma_f32_16x16x32_bf16 v[4:7], v[174:177], v[214:217], v[4:7]
	v_mfma_f32_16x16x32_bf16 v[0:3], v[182:185], v[214:217], v[0:3]
	s_barrier
	s_add_i32 s20, 0, 0x18000
	v_add_u32_e32 v153, s20, v148
	s_add_i32 s35, 0, 0x1c000
	ds_read_b128 v[154:157], v153
	ds_read_b128 v[158:161], v153 offset:1024
	ds_read_b128 v[162:165], v153 offset:2048
	ds_read_b128 v[166:169], v153 offset:3072
	v_add_u32_e32 v153, s35, v148
	ds_read_b128 v[170:173], v153
	ds_read_b128 v[174:177], v153 offset:1024
	ds_read_b128 v[178:181], v153 offset:2048
	ds_read_b128 v[182:185], v153 offset:3072
	s_add_u32 s38, s52, 0x40000
	s_addc_u32 s39, s53, 0
	s_mov_b32 m0, s51
	ds_read_b128 v[186:189], v152 offset:32768
	ds_read_b128 v[190:193], v152 offset:33792
	ds_read_b128 v[194:197], v152 offset:34816
	ds_read_b128 v[198:201], v152 offset:35840
	ds_read_b128 v[202:205], v152 offset:36864
	ds_read_b128 v[206:209], v152 offset:37888
	ds_read_b128 v[210:213], v152 offset:38912
	ds_read_b128 v[214:217], v152 offset:39936
	global_load_lds_dwordx4 v128, s[38:39]
	s_mov_b32 m0, s54
	s_nop 0
	global_load_lds_dwordx4 v132, s[38:39]
	s_waitcnt vmcnt(8)
	s_waitcnt lgkmcnt(0)
	s_barrier
	v_mfma_f32_16x16x32_bf16 v[124:127], v[154:157], v[186:189], v[124:127]
	v_mfma_f32_16x16x32_bf16 v[120:123], v[162:165], v[186:189], v[120:123]
	v_mfma_f32_16x16x32_bf16 v[112:115], v[154:157], v[194:197], v[112:115]
	v_mfma_f32_16x16x32_bf16 v[104:107], v[162:165], v[194:197], v[104:107]
	v_mfma_f32_16x16x32_bf16 v[96:99], v[154:157], v[202:205], v[96:99]
	v_mfma_f32_16x16x32_bf16 v[88:91], v[162:165], v[202:205], v[88:91]
	v_mfma_f32_16x16x32_bf16 v[80:83], v[154:157], v[210:213], v[80:83]
	v_mfma_f32_16x16x32_bf16 v[72:75], v[162:165], v[210:213], v[72:75]
	v_mfma_f32_16x16x32_bf16 v[124:127], v[158:161], v[190:193], v[124:127]
	v_mfma_f32_16x16x32_bf16 v[120:123], v[166:169], v[190:193], v[120:123]
	v_mfma_f32_16x16x32_bf16 v[112:115], v[158:161], v[198:201], v[112:115]
	v_mfma_f32_16x16x32_bf16 v[104:107], v[166:169], v[198:201], v[104:107]
	v_mfma_f32_16x16x32_bf16 v[96:99], v[158:161], v[206:209], v[96:99]
	v_mfma_f32_16x16x32_bf16 v[88:91], v[166:169], v[206:209], v[88:91]
	v_mfma_f32_16x16x32_bf16 v[80:83], v[158:161], v[214:217], v[80:83]
	v_mfma_f32_16x16x32_bf16 v[72:75], v[166:169], v[214:217], v[72:75]
	v_mfma_f32_16x16x32_bf16 v[116:119], v[170:173], v[186:189], v[116:119]
	v_mfma_f32_16x16x32_bf16 v[108:111], v[178:181], v[186:189], v[108:111]
	v_mfma_f32_16x16x32_bf16 v[100:103], v[170:173], v[194:197], v[100:103]
	v_mfma_f32_16x16x32_bf16 v[92:95], v[178:181], v[194:197], v[92:95]
	v_mfma_f32_16x16x32_bf16 v[84:87], v[170:173], v[202:205], v[84:87]
	v_mfma_f32_16x16x32_bf16 v[76:79], v[178:181], v[202:205], v[76:79]
	v_mfma_f32_16x16x32_bf16 v[68:71], v[170:173], v[210:213], v[68:71]
	v_mfma_f32_16x16x32_bf16 v[64:67], v[178:181], v[210:213], v[64:67]
	v_mfma_f32_16x16x32_bf16 v[116:119], v[174:177], v[190:193], v[116:119]
	v_mfma_f32_16x16x32_bf16 v[108:111], v[182:185], v[190:193], v[108:111]
	v_mfma_f32_16x16x32_bf16 v[100:103], v[174:177], v[198:201], v[100:103]
	v_mfma_f32_16x16x32_bf16 v[92:95], v[182:185], v[198:201], v[92:95]
	v_mfma_f32_16x16x32_bf16 v[84:87], v[174:177], v[206:209], v[84:87]
	v_mfma_f32_16x16x32_bf16 v[76:79], v[182:185], v[206:209], v[76:79]
	v_mfma_f32_16x16x32_bf16 v[68:71], v[174:177], v[214:217], v[68:71]
	v_mfma_f32_16x16x32_bf16 v[64:67], v[182:185], v[214:217], v[64:67]
	s_barrier
	s_add_i32 s20, s20, s47
	v_lshl_add_u64 v[144:145], v[144:145], 0, s[6:7]
	s_mov_b32 m0, s20
	ds_read_b128 v[186:189], v152 offset:49152
	ds_read_b128 v[190:193], v152 offset:50176
	ds_read_b128 v[194:197], v152 offset:51200
	ds_read_b128 v[198:201], v152 offset:52224
	ds_read_b128 v[202:205], v152 offset:53248
	ds_read_b128 v[206:209], v152 offset:54272
	ds_read_b128 v[210:213], v152 offset:55296
	ds_read_b128 v[214:217], v152 offset:56320
	global_load_lds_dwordx4 v[144:145], off
	s_add_i32 m0, s20, 0x2000
	s_add_u32 s38, s48, 0x40080
	v_lshl_add_u64 v[144:145], v[218:219], 0, s[6:7]
	s_addc_u32 s39, s49, 0
	s_add_i32 s20, s35, s47
	global_load_lds_dwordx4 v[144:145], off
	s_mov_b32 m0, s20
	s_nop 0
	global_load_lds_dwordx4 v130, s[38:39]
	s_add_i32 m0, s20, 0x2000
	s_nop 0
	global_load_lds_dwordx4 v134, s[38:39]
	v_lshl_add_u64 v[144:145], v[220:221], 0, s[6:7]
	s_mov_b32 m0, s56
	s_nop 0
	global_load_lds_dwordx4 v[144:145], off
	v_lshl_add_u64 v[144:145], v[222:223], 0, s[6:7]
	s_mov_b32 m0, s57
	s_nop 0
	global_load_lds_dwordx4 v[144:145], off
	s_waitcnt vmcnt(8)
	s_waitcnt lgkmcnt(0)
	s_barrier
	v_mfma_f32_16x16x32_bf16 v[60:63], v[154:157], v[186:189], v[60:63]
	v_mfma_f32_16x16x32_bf16 v[56:59], v[162:165], v[186:189], v[56:59]
	v_mfma_f32_16x16x32_bf16 v[48:51], v[154:157], v[194:197], v[48:51]
	v_mfma_f32_16x16x32_bf16 v[40:43], v[162:165], v[194:197], v[40:43]
	v_mfma_f32_16x16x32_bf16 v[32:35], v[154:157], v[202:205], v[32:35]
	v_mfma_f32_16x16x32_bf16 v[24:27], v[162:165], v[202:205], v[24:27]
	v_mfma_f32_16x16x32_bf16 v[16:19], v[154:157], v[210:213], v[16:19]
	v_mfma_f32_16x16x32_bf16 v[8:11], v[162:165], v[210:213], v[8:11]
	v_mfma_f32_16x16x32_bf16 v[60:63], v[158:161], v[190:193], v[60:63]
	v_mfma_f32_16x16x32_bf16 v[56:59], v[166:169], v[190:193], v[56:59]
	v_mfma_f32_16x16x32_bf16 v[48:51], v[158:161], v[198:201], v[48:51]
	v_mfma_f32_16x16x32_bf16 v[40:43], v[166:169], v[198:201], v[40:43]
	v_mfma_f32_16x16x32_bf16 v[32:35], v[158:161], v[206:209], v[32:35]
	v_mfma_f32_16x16x32_bf16 v[24:27], v[166:169], v[206:209], v[24:27]
	v_mfma_f32_16x16x32_bf16 v[16:19], v[158:161], v[214:217], v[16:19]
	v_mfma_f32_16x16x32_bf16 v[8:11], v[166:169], v[214:217], v[8:11]
	v_mfma_f32_16x16x32_bf16 v[52:55], v[170:173], v[186:189], v[52:55]
	v_mfma_f32_16x16x32_bf16 v[44:47], v[178:181], v[186:189], v[44:47]
	v_mfma_f32_16x16x32_bf16 v[36:39], v[170:173], v[194:197], v[36:39]
	v_mfma_f32_16x16x32_bf16 v[28:31], v[178:181], v[194:197], v[28:31]
	v_mfma_f32_16x16x32_bf16 v[20:23], v[170:173], v[202:205], v[20:23]
	v_mfma_f32_16x16x32_bf16 v[12:15], v[178:181], v[202:205], v[12:15]
	v_mfma_f32_16x16x32_bf16 v[4:7], v[170:173], v[210:213], v[4:7]
	v_mfma_f32_16x16x32_bf16 v[0:3], v[178:181], v[210:213], v[0:3]
	v_mfma_f32_16x16x32_bf16 v[52:55], v[174:177], v[190:193], v[52:55]
	v_mfma_f32_16x16x32_bf16 v[44:47], v[182:185], v[190:193], v[44:47]
	v_mfma_f32_16x16x32_bf16 v[36:39], v[174:177], v[198:201], v[36:39]
	v_mfma_f32_16x16x32_bf16 v[28:31], v[182:185], v[198:201], v[28:31]
	v_mfma_f32_16x16x32_bf16 v[20:23], v[174:177], v[206:209], v[20:23]
	v_mfma_f32_16x16x32_bf16 v[12:15], v[182:185], v[206:209], v[12:15]
	v_mfma_f32_16x16x32_bf16 v[4:7], v[174:177], v[214:217], v[4:7]
	v_mfma_f32_16x16x32_bf16 v[0:3], v[182:185], v[214:217], v[0:3]
	s_barrier
	s_add_i32 s65, s65, 2
	s_add_u32 s44, s44, 0x100
	s_addc_u32 s45, s45, 0
	s_add_u32 s63, s63, 0x100
	s_addc_u32 s64, s64, 0
	s_cmp_gt_u32 s65, 13
	s_cbranch_scc0 .LBB0_1626
	s_and_b64 vcc, exec, s[8:9]
	s_cbranch_vccz .LBB0_1629
	s_barrier

.LBB0_1760:
	ds_read_b128 v[130:133], v242
	ds_read_b128 v[134:137], v242 offset:1024
	ds_read_b128 v[138:141], v242 offset:2048
	ds_read_b128 v[142:145], v242 offset:3072
	ds_read_b128 v[146:149], v243
	ds_read_b128 v[150:153], v243 offset:1024
	ds_read_b128 v[154:157], v243 offset:2048
	ds_read_b128 v[158:161], v243 offset:3072
	s_add_i32 s52, s10, 2
	s_add_u32 s20, s48, 0x80
	s_addc_u32 s35, s49, 0
	s_cmp_eq_u32 s62, s10
	s_cselect_b32 s51, s5, s35
	s_cselect_b32 s50, s4, s20
	s_cselect_b32 s39, s47, s1
	s_cselect_b32 s38, s46, s0
	v_lshl_add_u64 v[194:195], s[48:49], 0, v[230:231]
	s_add_i32 m0, s55, 0xc000
	ds_read_b128 v[162:165], v244
	ds_read_b128 v[166:169], v244 offset:1024
	ds_read_b128 v[170:173], v244 offset:2048
	ds_read_b128 v[174:177], v244 offset:3072
	ds_read_b128 v[178:181], v244 offset:4096
	ds_read_b128 v[182:185], v244 offset:5120
	ds_read_b128 v[186:189], v244 offset:6144
	ds_read_b128 v[190:193], v244 offset:7168
	global_load_lds_dwordx4 v[194:195], off
	v_lshl_add_u64 v[194:195], s[48:49], 0, v[232:233]
	s_add_i32 m0, s55, 0xe000
	s_nop 0
	global_load_lds_dwordx4 v[194:195], off
	s_waitcnt vmcnt(8)
	s_waitcnt lgkmcnt(0)
	s_barrier
	v_mfma_f32_16x16x32_bf16 v[126:129], v[130:133], v[162:165], v[126:129]
	v_mfma_f32_16x16x32_bf16 v[122:125], v[138:141], v[162:165], v[122:125]
	v_mfma_f32_16x16x32_bf16 v[118:121], v[130:133], v[170:173], v[118:121]
	v_mfma_f32_16x16x32_bf16 v[114:117], v[138:141], v[170:173], v[114:117]
	v_mfma_f32_16x16x32_bf16 v[110:113], v[130:133], v[178:181], v[110:113]
	v_mfma_f32_16x16x32_bf16 v[106:109], v[138:141], v[178:181], v[106:109]
	v_mfma_f32_16x16x32_bf16 v[102:105], v[130:133], v[186:189], v[102:105]
	v_mfma_f32_16x16x32_bf16 v[98:101], v[138:141], v[186:189], v[98:101]
	v_mfma_f32_16x16x32_bf16 v[126:129], v[134:137], v[166:169], v[126:129]
	v_mfma_f32_16x16x32_bf16 v[122:125], v[142:145], v[166:169], v[122:125]
	v_mfma_f32_16x16x32_bf16 v[118:121], v[134:137], v[174:177], v[118:121]
	v_mfma_f32_16x16x32_bf16 v[114:117], v[142:145], v[174:177], v[114:117]
	v_mfma_f32_16x16x32_bf16 v[110:113], v[134:137], v[182:185], v[110:113]
	v_mfma_f32_16x16x32_bf16 v[106:109], v[142:145], v[182:185], v[106:109]
	v_mfma_f32_16x16x32_bf16 v[102:105], v[134:137], v[190:193], v[102:105]
	v_mfma_f32_16x16x32_bf16 v[98:101], v[142:145], v[190:193], v[98:101]
	v_mfma_f32_16x16x32_bf16 v[62:65], v[146:149], v[162:165], v[62:65]
	v_mfma_f32_16x16x32_bf16 v[58:61], v[154:157], v[162:165], v[58:61]
	v_mfma_f32_16x16x32_bf16 v[54:57], v[146:149], v[170:173], v[54:57]
	v_mfma_f32_16x16x32_bf16 v[50:53], v[154:157], v[170:173], v[50:53]
	v_mfma_f32_16x16x32_bf16 v[46:49], v[146:149], v[178:181], v[46:49]
	v_mfma_f32_16x16x32_bf16 v[42:45], v[154:157], v[178:181], v[42:45]
	v_mfma_f32_16x16x32_bf16 v[38:41], v[146:149], v[186:189], v[38:41]
	v_mfma_f32_16x16x32_bf16 v[34:37], v[154:157], v[186:189], v[34:37]
	v_mfma_f32_16x16x32_bf16 v[62:65], v[150:153], v[166:169], v[62:65]
	v_mfma_f32_16x16x32_bf16 v[58:61], v[158:161], v[166:169], v[58:61]
	v_mfma_f32_16x16x32_bf16 v[54:57], v[150:153], v[174:177], v[54:57]
	v_mfma_f32_16x16x32_bf16 v[50:53], v[158:161], v[174:177], v[50:53]
	v_mfma_f32_16x16x32_bf16 v[46:49], v[150:153], v[182:185], v[46:49]
	v_mfma_f32_16x16x32_bf16 v[42:45], v[158:161], v[182:185], v[42:45]
	v_mfma_f32_16x16x32_bf16 v[38:41], v[150:153], v[190:193], v[38:41]
	v_mfma_f32_16x16x32_bf16 v[34:37], v[158:161], v[190:193], v[34:37]
	s_barrier
	s_add_i32 s10, s79, s54
	v_lshl_add_u64 v[194:195], s[38:39], 0, v[222:223]
	s_mov_b32 m0, s10
	ds_read_b128 v[162:165], v244 offset:16384
	ds_read_b128 v[166:169], v244 offset:17408
	ds_read_b128 v[170:173], v244 offset:18432
	ds_read_b128 v[174:177], v244 offset:19456
	ds_read_b128 v[178:181], v244 offset:20480
	ds_read_b128 v[182:185], v244 offset:21504
	ds_read_b128 v[186:189], v244 offset:22528
	ds_read_b128 v[190:193], v244 offset:23552
	global_load_lds_dwordx4 v[194:195], off
	s_add_i32 m0, s10, 0x2000
	v_lshl_add_u64 v[196:197], s[38:39], 0, v[226:227]
	s_add_u32 s38, s38, s6
	s_addc_u32 s39, s39, s7
	s_add_i32 s10, s82, s54
	global_load_lds_dwordx4 v[196:197], off
	v_lshl_add_u64 v[198:199], s[38:39], 0, v[222:223]
	s_mov_b32 m0, s10
	v_lshl_add_u64 v[200:201], s[38:39], 0, v[226:227]
	global_load_lds_dwordx4 v[198:199], off
	s_add_i32 m0, s10, 0x2000
	v_lshl_add_u64 v[202:203], s[50:51], 0, v[220:221]
	global_load_lds_dwordx4 v[200:201], off
	s_mov_b32 m0, s55
	v_lshl_add_u64 v[204:205], s[50:51], 0, v[224:225]
	global_load_lds_dwordx4 v[202:203], off
	s_mov_b32 m0, s56
	s_nop 0
	global_load_lds_dwordx4 v[204:205], off
	s_waitcnt vmcnt(8)
	s_waitcnt lgkmcnt(0)
	s_barrier
	v_mfma_f32_16x16x32_bf16 v[94:97], v[130:133], v[162:165], v[94:97]
	v_mfma_f32_16x16x32_bf16 v[90:93], v[138:141], v[162:165], v[90:93]
	v_mfma_f32_16x16x32_bf16 v[86:89], v[130:133], v[170:173], v[86:89]
	v_mfma_f32_16x16x32_bf16 v[82:85], v[138:141], v[170:173], v[82:85]
	v_mfma_f32_16x16x32_bf16 v[78:81], v[130:133], v[178:181], v[78:81]
	v_mfma_f32_16x16x32_bf16 v[74:77], v[138:141], v[178:181], v[74:77]
	v_mfma_f32_16x16x32_bf16 v[70:73], v[130:133], v[186:189], v[70:73]
	v_mfma_f32_16x16x32_bf16 v[66:69], v[138:141], v[186:189], v[66:69]
	v_mfma_f32_16x16x32_bf16 v[94:97], v[134:137], v[166:169], v[94:97]
	v_mfma_f32_16x16x32_bf16 v[90:93], v[142:145], v[166:169], v[90:93]
	v_mfma_f32_16x16x32_bf16 v[86:89], v[134:137], v[174:177], v[86:89]
	v_mfma_f32_16x16x32_bf16 v[82:85], v[142:145], v[174:177], v[82:85]
	v_mfma_f32_16x16x32_bf16 v[78:81], v[134:137], v[182:185], v[78:81]
	v_mfma_f32_16x16x32_bf16 v[74:77], v[142:145], v[182:185], v[74:77]
	v_mfma_f32_16x16x32_bf16 v[70:73], v[134:137], v[190:193], v[70:73]
	v_mfma_f32_16x16x32_bf16 v[66:69], v[142:145], v[190:193], v[66:69]
	v_mfma_f32_16x16x32_bf16 v[30:33], v[146:149], v[162:165], v[30:33]
	v_mfma_f32_16x16x32_bf16 v[26:29], v[154:157], v[162:165], v[26:29]
	v_mfma_f32_16x16x32_bf16 v[22:25], v[146:149], v[170:173], v[22:25]
	v_mfma_f32_16x16x32_bf16 v[18:21], v[154:157], v[170:173], v[18:21]
	v_mfma_f32_16x16x32_bf16 v[14:17], v[146:149], v[178:181], v[14:17]
	v_mfma_f32_16x16x32_bf16 v[10:13], v[154:157], v[178:181], v[10:13]
	v_mfma_f32_16x16x32_bf16 v[6:9], v[146:149], v[186:189], v[6:9]
	v_mfma_f32_16x16x32_bf16 v[2:5], v[154:157], v[186:189], v[2:5]
	v_mfma_f32_16x16x32_bf16 v[30:33], v[150:153], v[166:169], v[30:33]
	v_mfma_f32_16x16x32_bf16 v[26:29], v[158:161], v[166:169], v[26:29]
	v_mfma_f32_16x16x32_bf16 v[22:25], v[150:153], v[174:177], v[22:25]
	v_mfma_f32_16x16x32_bf16 v[18:21], v[158:161], v[174:177], v[18:21]
	v_mfma_f32_16x16x32_bf16 v[14:17], v[150:153], v[182:185], v[14:17]
	v_mfma_f32_16x16x32_bf16 v[10:13], v[158:161], v[182:185], v[10:13]
	v_mfma_f32_16x16x32_bf16 v[6:9], v[150:153], v[190:193], v[6:9]
	v_mfma_f32_16x16x32_bf16 v[2:5], v[158:161], v[190:193], v[2:5]
	s_barrier
	s_add_i32 s10, 0, 0x18000
	s_add_i32 s20, 0, 0x1c000
	v_add_u32_e32 v142, s10, v241
	v_add_u32_e32 v158, s20, v241
	ds_read_b128 v[130:133], v142
	ds_read_b128 v[134:137], v142 offset:1024
	ds_read_b128 v[138:141], v142 offset:2048
	ds_read_b128 v[142:145], v142 offset:3072
	ds_read_b128 v[146:149], v158
	ds_read_b128 v[150:153], v158 offset:1024
	ds_read_b128 v[154:157], v158 offset:2048
	ds_read_b128 v[158:161], v158 offset:3072
	s_add_u32 s38, s50, s6
	s_addc_u32 s39, s51, s7
	s_mov_b32 m0, s57
	ds_read_b128 v[162:165], v244 offset:32768
	ds_read_b128 v[166:169], v244 offset:33792
	ds_read_b128 v[170:173], v244 offset:34816
	ds_read_b128 v[174:177], v244 offset:35840
	ds_read_b128 v[178:181], v244 offset:36864
	ds_read_b128 v[182:185], v244 offset:37888
	ds_read_b128 v[186:189], v244 offset:38912
	ds_read_b128 v[190:193], v244 offset:39936
	global_load_lds_dwordx4 v220, s[38:39]
	s_mov_b32 m0, s58
	s_nop 0
	global_load_lds_dwordx4 v224, s[38:39]
	s_waitcnt vmcnt(8)
	s_waitcnt lgkmcnt(0)
	s_barrier
	v_mfma_f32_16x16x32_bf16 v[126:129], v[130:133], v[162:165], v[126:129]
	v_mfma_f32_16x16x32_bf16 v[122:125], v[138:141], v[162:165], v[122:125]
	v_mfma_f32_16x16x32_bf16 v[118:121], v[130:133], v[170:173], v[118:121]
	v_mfma_f32_16x16x32_bf16 v[114:117], v[138:141], v[170:173], v[114:117]
	v_mfma_f32_16x16x32_bf16 v[110:113], v[130:133], v[178:181], v[110:113]
	v_mfma_f32_16x16x32_bf16 v[106:109], v[138:141], v[178:181], v[106:109]
	v_mfma_f32_16x16x32_bf16 v[102:105], v[130:133], v[186:189], v[102:105]
	v_mfma_f32_16x16x32_bf16 v[98:101], v[138:141], v[186:189], v[98:101]
	v_mfma_f32_16x16x32_bf16 v[126:129], v[134:137], v[166:169], v[126:129]
	v_mfma_f32_16x16x32_bf16 v[122:125], v[142:145], v[166:169], v[122:125]
	v_mfma_f32_16x16x32_bf16 v[118:121], v[134:137], v[174:177], v[118:121]
	v_mfma_f32_16x16x32_bf16 v[114:117], v[142:145], v[174:177], v[114:117]
	v_mfma_f32_16x16x32_bf16 v[110:113], v[134:137], v[182:185], v[110:113]
	v_mfma_f32_16x16x32_bf16 v[106:109], v[142:145], v[182:185], v[106:109]
	v_mfma_f32_16x16x32_bf16 v[102:105], v[134:137], v[190:193], v[102:105]
	v_mfma_f32_16x16x32_bf16 v[98:101], v[142:145], v[190:193], v[98:101]
	v_mfma_f32_16x16x32_bf16 v[62:65], v[146:149], v[162:165], v[62:65]
	v_mfma_f32_16x16x32_bf16 v[58:61], v[154:157], v[162:165], v[58:61]
	v_mfma_f32_16x16x32_bf16 v[54:57], v[146:149], v[170:173], v[54:57]
	v_mfma_f32_16x16x32_bf16 v[50:53], v[154:157], v[170:173], v[50:53]
	v_mfma_f32_16x16x32_bf16 v[46:49], v[146:149], v[178:181], v[46:49]
	v_mfma_f32_16x16x32_bf16 v[42:45], v[154:157], v[178:181], v[42:45]
	v_mfma_f32_16x16x32_bf16 v[38:41], v[146:149], v[186:189], v[38:41]
	v_mfma_f32_16x16x32_bf16 v[34:37], v[154:157], v[186:189], v[34:37]
	v_mfma_f32_16x16x32_bf16 v[62:65], v[150:153], v[166:169], v[62:65]
	v_mfma_f32_16x16x32_bf16 v[58:61], v[158:161], v[166:169], v[58:61]
	v_mfma_f32_16x16x32_bf16 v[54:57], v[150:153], v[174:177], v[54:57]
	v_mfma_f32_16x16x32_bf16 v[50:53], v[158:161], v[174:177], v[50:53]
	v_mfma_f32_16x16x32_bf16 v[46:49], v[150:153], v[182:185], v[46:49]
	v_mfma_f32_16x16x32_bf16 v[42:45], v[158:161], v[182:185], v[42:45]
	v_mfma_f32_16x16x32_bf16 v[38:41], v[150:153], v[190:193], v[38:41]
	v_mfma_f32_16x16x32_bf16 v[34:37], v[158:161], v[190:193], v[34:37]
	s_barrier
	s_add_i32 s10, s10, s54
	v_lshl_add_u64 v[194:195], v[194:195], 0, s[14:15]
	s_mov_b32 m0, s10
	ds_read_b128 v[162:165], v244 offset:49152
	ds_read_b128 v[166:169], v244 offset:50176
	ds_read_b128 v[170:173], v244 offset:51200
	ds_read_b128 v[174:177], v244 offset:52224
	ds_read_b128 v[178:181], v244 offset:53248
	ds_read_b128 v[182:185], v244 offset:54272
	ds_read_b128 v[186:189], v244 offset:55296
	ds_read_b128 v[190:193], v244 offset:56320
	global_load_lds_dwordx4 v[194:195], off
	v_lshl_add_u64 v[194:195], v[196:197], 0, s[14:15]
	s_add_i32 m0, s10, 0x2000
	s_add_i32 s10, s20, s54
	global_load_lds_dwordx4 v[194:195], off
	v_lshl_add_u64 v[194:195], v[198:199], 0, s[14:15]
	s_mov_b32 m0, s10
	s_nop 0
	global_load_lds_dwordx4 v[194:195], off
	v_lshl_add_u64 v[194:195], v[200:201], 0, s[14:15]
	s_add_i32 m0, s10, 0x2000
	s_nop 0
	global_load_lds_dwordx4 v[194:195], off
	v_lshl_add_u64 v[194:195], v[202:203], 0, s[14:15]
	s_mov_b32 m0, s59
	s_nop 0
	global_load_lds_dwordx4 v[194:195], off
	v_lshl_add_u64 v[194:195], v[204:205], 0, s[14:15]
	s_mov_b32 m0, s60
	s_nop 0
	global_load_lds_dwordx4 v[194:195], off
	s_waitcnt vmcnt(8)
	s_waitcnt lgkmcnt(0)
	s_barrier
	v_mfma_f32_16x16x32_bf16 v[94:97], v[130:133], v[162:165], v[94:97]
	v_mfma_f32_16x16x32_bf16 v[90:93], v[138:141], v[162:165], v[90:93]
	v_mfma_f32_16x16x32_bf16 v[86:89], v[130:133], v[170:173], v[86:89]
	v_mfma_f32_16x16x32_bf16 v[82:85], v[138:141], v[170:173], v[82:85]
	v_mfma_f32_16x16x32_bf16 v[78:81], v[130:133], v[178:181], v[78:81]
	v_mfma_f32_16x16x32_bf16 v[74:77], v[138:141], v[178:181], v[74:77]
	v_mfma_f32_16x16x32_bf16 v[70:73], v[130:133], v[186:189], v[70:73]
	v_mfma_f32_16x16x32_bf16 v[66:69], v[138:141], v[186:189], v[66:69]
	v_mfma_f32_16x16x32_bf16 v[94:97], v[134:137], v[166:169], v[94:97]
	v_mfma_f32_16x16x32_bf16 v[90:93], v[142:145], v[166:169], v[90:93]
	v_mfma_f32_16x16x32_bf16 v[86:89], v[134:137], v[174:177], v[86:89]
	v_mfma_f32_16x16x32_bf16 v[82:85], v[142:145], v[174:177], v[82:85]
	v_mfma_f32_16x16x32_bf16 v[78:81], v[134:137], v[182:185], v[78:81]
	v_mfma_f32_16x16x32_bf16 v[74:77], v[142:145], v[182:185], v[74:77]
	v_mfma_f32_16x16x32_bf16 v[70:73], v[134:137], v[190:193], v[70:73]
	v_mfma_f32_16x16x32_bf16 v[66:69], v[142:145], v[190:193], v[66:69]
	v_mfma_f32_16x16x32_bf16 v[30:33], v[146:149], v[162:165], v[30:33]
	v_mfma_f32_16x16x32_bf16 v[26:29], v[154:157], v[162:165], v[26:29]
	v_mfma_f32_16x16x32_bf16 v[22:25], v[146:149], v[170:173], v[22:25]
	v_mfma_f32_16x16x32_bf16 v[18:21], v[154:157], v[170:173], v[18:21]
	v_mfma_f32_16x16x32_bf16 v[14:17], v[146:149], v[178:181], v[14:17]
	v_mfma_f32_16x16x32_bf16 v[10:13], v[154:157], v[178:181], v[10:13]
	v_mfma_f32_16x16x32_bf16 v[6:9], v[146:149], v[186:189], v[6:9]
	v_mfma_f32_16x16x32_bf16 v[2:5], v[154:157], v[186:189], v[2:5]
	v_mfma_f32_16x16x32_bf16 v[30:33], v[150:153], v[166:169], v[30:33]
	v_mfma_f32_16x16x32_bf16 v[26:29], v[158:161], v[166:169], v[26:29]
	v_mfma_f32_16x16x32_bf16 v[22:25], v[150:153], v[174:177], v[22:25]
	v_mfma_f32_16x16x32_bf16 v[18:21], v[158:161], v[174:177], v[18:21]
	v_mfma_f32_16x16x32_bf16 v[14:17], v[150:153], v[182:185], v[14:17]
	v_mfma_f32_16x16x32_bf16 v[10:13], v[158:161], v[182:185], v[10:13]
	v_mfma_f32_16x16x32_bf16 v[6:9], v[150:153], v[190:193], v[6:9]
	v_mfma_f32_16x16x32_bf16 v[2:5], v[158:161], v[190:193], v[2:5]
	s_barrier
	s_add_u32 s48, s48, 0x100
	s_addc_u32 s49, s49, 0
	s_add_u32 s0, s0, 0x100
	s_addc_u32 s1, s1, 0
	s_cmp_ge_i32 s52, s61
	s_mov_b32 s10, s52
	s_cbranch_scc0 .LBB0_1760
	v_mov_b64_e32 v[194:195], v[104:105]
	v_mov_b64_e32 v[172:173], v[64:65]
	v_mov_b64_e32 v[150:151], v[40:41]
	v_mov_b64_e32 v[196:197], v[100:101]
	v_mov_b64_e32 v[174:175], v[60:61]
	v_mov_b64_e32 v[152:153], v[36:37]
	v_mov_b64_e32 v[216:217], v[128:129]
	v_mov_b64_e32 v[210:211], v[120:121]
	v_mov_b64_e32 v[204:205], v[112:113]
	v_mov_b64_e32 v[166:167], v[56:57]
	v_mov_b64_e32 v[160:161], v[48:49]
	v_mov_b64_e32 v[198:199], v[96:97]
	v_mov_b64_e32 v[188:189], v[88:89]
	v_mov_b64_e32 v[182:183], v[80:81]
	v_mov_b64_e32 v[176:177], v[72:73]
	v_mov_b64_e32 v[154:155], v[32:33]
	v_mov_b64_e32 v[144:145], v[24:25]
	v_mov_b64_e32 v[138:139], v[16:17]
	v_mov_b64_e32 v[132:133], v[8:9]
	v_mov_b64_e32 v[218:219], v[124:125]
	v_mov_b64_e32 v[212:213], v[116:117]
	v_mov_b64_e32 v[206:207], v[108:109]
	v_mov_b64_e32 v[168:169], v[52:53]
	v_mov_b64_e32 v[162:163], v[44:45]
	v_mov_b64_e32 v[200:201], v[92:93]
	v_mov_b64_e32 v[190:191], v[84:85]
	v_mov_b64_e32 v[184:185], v[76:77]
	v_mov_b64_e32 v[178:179], v[68:69]
	v_mov_b64_e32 v[156:157], v[28:29]
	v_mov_b64_e32 v[146:147], v[20:21]
	v_mov_b64_e32 v[140:141], v[12:13]
	v_mov_b64_e32 v[134:135], v[4:5]
	v_mov_b64_e32 v[214:215], v[126:127]
	v_mov_b64_e32 v[216:217], v[122:123]
	v_mov_b64_e32 v[208:209], v[118:119]
	v_mov_b64_e32 v[210:211], v[114:115]
	v_mov_b64_e32 v[202:203], v[110:111]
	v_mov_b64_e32 v[204:205], v[106:107]
	v_mov_b64_e32 v[192:193], v[102:103]
	v_mov_b64_e32 v[194:195], v[98:99]
	v_mov_b64_e32 v[170:171], v[62:63]
	v_mov_b64_e32 v[172:173], v[58:59]
	v_mov_b64_e32 v[164:165], v[54:55]
	v_mov_b64_e32 v[166:167], v[50:51]
	v_mov_b64_e32 v[158:159], v[46:47]
	v_mov_b64_e32 v[160:161], v[42:43]
	v_mov_b64_e32 v[148:149], v[38:39]
	v_mov_b64_e32 v[150:151], v[34:35]
	v_mov_b64_e32 v[196:197], v[94:95]
	v_mov_b64_e32 v[198:199], v[90:91]
	v_mov_b64_e32 v[186:187], v[86:87]
	v_mov_b64_e32 v[188:189], v[82:83]
	v_mov_b64_e32 v[180:181], v[78:79]
	v_mov_b64_e32 v[182:183], v[74:75]
	v_mov_b64_e32 v[174:175], v[70:71]
	v_mov_b64_e32 v[176:177], v[66:67]
	v_mov_b64_e32 v[152:153], v[30:31]
	v_mov_b64_e32 v[154:155], v[26:27]
	v_mov_b64_e32 v[142:143], v[22:23]
	v_mov_b64_e32 v[144:145], v[18:19]
	v_mov_b64_e32 v[136:137], v[14:15]
	v_mov_b64_e32 v[138:139], v[10:11]
	v_mov_b64_e32 v[130:131], v[6:7]
	v_mov_b64_e32 v[132:133], v[2:3]

.LBB0_2129:
	ds_read_b128 v[154:157], v150
	ds_read_b128 v[158:161], v150 offset:1024
	ds_read_b128 v[162:165], v150 offset:2048
	ds_read_b128 v[166:169], v150 offset:3072
	ds_read_b128 v[170:173], v151
	ds_read_b128 v[174:177], v151 offset:1024
	ds_read_b128 v[178:181], v151 offset:2048
	ds_read_b128 v[182:185], v151 offset:3072
	s_add_u32 s54, s52, 0xfffc0080
	s_addc_u32 s55, s53, -1
	s_cmp_eq_u32 s72, 12
	s_cselect_b32 s57, s0, s55
	s_cselect_b32 s56, s1, s54
	s_cselect_b32 s55, s19, s71
	s_cselect_b32 s54, s45, s70
	s_add_i32 m0, s38, 0xc000
	ds_read_b128 v[186:189], v152
	ds_read_b128 v[190:193], v152 offset:1024
	ds_read_b128 v[194:197], v152 offset:2048
	ds_read_b128 v[198:201], v152 offset:3072
	ds_read_b128 v[202:205], v152 offset:4096
	ds_read_b128 v[206:209], v152 offset:5120
	ds_read_b128 v[210:213], v152 offset:6144
	ds_read_b128 v[214:217], v152 offset:7168
	global_load_lds_dwordx4 v136, s[52:53]
	s_add_i32 m0, s38, 0xe000
	s_nop 0
	global_load_lds_dwordx4 v138, s[52:53]
	s_waitcnt vmcnt(8)
	s_waitcnt lgkmcnt(0)
	s_barrier
	v_mfma_f32_16x16x32_bf16 v[124:127], v[154:157], v[186:189], v[124:127]
	v_mfma_f32_16x16x32_bf16 v[120:123], v[162:165], v[186:189], v[120:123]
	v_mfma_f32_16x16x32_bf16 v[112:115], v[154:157], v[194:197], v[112:115]
	v_mfma_f32_16x16x32_bf16 v[104:107], v[162:165], v[194:197], v[104:107]
	v_mfma_f32_16x16x32_bf16 v[96:99], v[154:157], v[202:205], v[96:99]
	v_mfma_f32_16x16x32_bf16 v[88:91], v[162:165], v[202:205], v[88:91]
	v_mfma_f32_16x16x32_bf16 v[80:83], v[154:157], v[210:213], v[80:83]
	v_mfma_f32_16x16x32_bf16 v[72:75], v[162:165], v[210:213], v[72:75]
	v_mfma_f32_16x16x32_bf16 v[124:127], v[158:161], v[190:193], v[124:127]
	v_mfma_f32_16x16x32_bf16 v[120:123], v[166:169], v[190:193], v[120:123]
	v_mfma_f32_16x16x32_bf16 v[112:115], v[158:161], v[198:201], v[112:115]
	v_mfma_f32_16x16x32_bf16 v[104:107], v[166:169], v[198:201], v[104:107]
	v_mfma_f32_16x16x32_bf16 v[96:99], v[158:161], v[206:209], v[96:99]
	v_mfma_f32_16x16x32_bf16 v[88:91], v[166:169], v[206:209], v[88:91]
	v_mfma_f32_16x16x32_bf16 v[80:83], v[158:161], v[214:217], v[80:83]
	v_mfma_f32_16x16x32_bf16 v[72:75], v[166:169], v[214:217], v[72:75]
	v_mfma_f32_16x16x32_bf16 v[116:119], v[170:173], v[186:189], v[116:119]
	v_mfma_f32_16x16x32_bf16 v[108:111], v[178:181], v[186:189], v[108:111]
	v_mfma_f32_16x16x32_bf16 v[100:103], v[170:173], v[194:197], v[100:103]
	v_mfma_f32_16x16x32_bf16 v[92:95], v[178:181], v[194:197], v[92:95]
	v_mfma_f32_16x16x32_bf16 v[84:87], v[170:173], v[202:205], v[84:87]
	v_mfma_f32_16x16x32_bf16 v[76:79], v[178:181], v[202:205], v[76:79]
	v_mfma_f32_16x16x32_bf16 v[68:71], v[170:173], v[210:213], v[68:71]
	v_mfma_f32_16x16x32_bf16 v[64:67], v[178:181], v[210:213], v[64:67]
	v_mfma_f32_16x16x32_bf16 v[116:119], v[174:177], v[190:193], v[116:119]
	v_mfma_f32_16x16x32_bf16 v[108:111], v[182:185], v[190:193], v[108:111]
	v_mfma_f32_16x16x32_bf16 v[100:103], v[174:177], v[198:201], v[100:103]
	v_mfma_f32_16x16x32_bf16 v[92:95], v[182:185], v[198:201], v[92:95]
	v_mfma_f32_16x16x32_bf16 v[84:87], v[174:177], v[206:209], v[84:87]
	v_mfma_f32_16x16x32_bf16 v[76:79], v[182:185], v[206:209], v[76:79]
	v_mfma_f32_16x16x32_bf16 v[68:71], v[174:177], v[214:217], v[68:71]
	v_mfma_f32_16x16x32_bf16 v[64:67], v[182:185], v[214:217], v[64:67]
	s_barrier
	s_add_i32 s73, s62, s35
	v_lshl_add_u64 v[144:145], s[54:55], 0, v[130:131]
	s_mov_b32 m0, s73
	ds_read_b128 v[186:189], v152 offset:16384
	ds_read_b128 v[190:193], v152 offset:17408
	ds_read_b128 v[194:197], v152 offset:18432
	ds_read_b128 v[198:201], v152 offset:19456
	ds_read_b128 v[202:205], v152 offset:20480
	ds_read_b128 v[206:209], v152 offset:21504
	ds_read_b128 v[210:213], v152 offset:22528
	ds_read_b128 v[214:217], v152 offset:23552
	global_load_lds_dwordx4 v[144:145], off
	s_add_i32 m0, s73, 0x2000
	s_add_u32 s74, s54, 0x40000
	v_lshl_add_u64 v[218:219], s[54:55], 0, v[134:135]
	s_addc_u32 s75, s55, 0
	s_add_i32 s73, s63, s35
	global_load_lds_dwordx4 v[218:219], off
	s_mov_b32 m0, s73
	v_lshl_add_u64 v[222:223], s[56:57], 0, v[132:133]
	global_load_lds_dwordx4 v130, s[74:75]
	s_add_i32 m0, s73, 0x2000
	s_nop 0
	global_load_lds_dwordx4 v134, s[74:75]
	v_lshl_add_u64 v[220:221], s[56:57], 0, v[128:129]
	s_mov_b32 m0, s38
	s_nop 0
	global_load_lds_dwordx4 v[220:221], off
	s_mov_b32 m0, s39
	s_nop 0
	global_load_lds_dwordx4 v[222:223], off
	s_waitcnt vmcnt(8)
	s_waitcnt lgkmcnt(0)
	s_barrier
	v_mfma_f32_16x16x32_bf16 v[60:63], v[154:157], v[186:189], v[60:63]
	v_mfma_f32_16x16x32_bf16 v[56:59], v[162:165], v[186:189], v[56:59]
	v_mfma_f32_16x16x32_bf16 v[48:51], v[154:157], v[194:197], v[48:51]
	v_mfma_f32_16x16x32_bf16 v[40:43], v[162:165], v[194:197], v[40:43]
	v_mfma_f32_16x16x32_bf16 v[32:35], v[154:157], v[202:205], v[32:35]
	v_mfma_f32_16x16x32_bf16 v[24:27], v[162:165], v[202:205], v[24:27]
	v_mfma_f32_16x16x32_bf16 v[16:19], v[154:157], v[210:213], v[16:19]
	v_mfma_f32_16x16x32_bf16 v[8:11], v[162:165], v[210:213], v[8:11]
	v_mfma_f32_16x16x32_bf16 v[60:63], v[158:161], v[190:193], v[60:63]
	v_mfma_f32_16x16x32_bf16 v[56:59], v[166:169], v[190:193], v[56:59]
	v_mfma_f32_16x16x32_bf16 v[48:51], v[158:161], v[198:201], v[48:51]
	v_mfma_f32_16x16x32_bf16 v[40:43], v[166:169], v[198:201], v[40:43]
	v_mfma_f32_16x16x32_bf16 v[32:35], v[158:161], v[206:209], v[32:35]
	v_mfma_f32_16x16x32_bf16 v[24:27], v[166:169], v[206:209], v[24:27]
	v_mfma_f32_16x16x32_bf16 v[16:19], v[158:161], v[214:217], v[16:19]
	v_mfma_f32_16x16x32_bf16 v[8:11], v[166:169], v[214:217], v[8:11]
	v_mfma_f32_16x16x32_bf16 v[52:55], v[170:173], v[186:189], v[52:55]
	v_mfma_f32_16x16x32_bf16 v[44:47], v[178:181], v[186:189], v[44:47]
	v_mfma_f32_16x16x32_bf16 v[36:39], v[170:173], v[194:197], v[36:39]
	v_mfma_f32_16x16x32_bf16 v[28:31], v[178:181], v[194:197], v[28:31]
	v_mfma_f32_16x16x32_bf16 v[20:23], v[170:173], v[202:205], v[20:23]
	v_mfma_f32_16x16x32_bf16 v[12:15], v[178:181], v[202:205], v[12:15]
	v_mfma_f32_16x16x32_bf16 v[4:7], v[170:173], v[210:213], v[4:7]
	v_mfma_f32_16x16x32_bf16 v[0:3], v[178:181], v[210:213], v[0:3]
	v_mfma_f32_16x16x32_bf16 v[52:55], v[174:177], v[190:193], v[52:55]
	v_mfma_f32_16x16x32_bf16 v[44:47], v[182:185], v[190:193], v[44:47]
	v_mfma_f32_16x16x32_bf16 v[36:39], v[174:177], v[198:201], v[36:39]
	v_mfma_f32_16x16x32_bf16 v[28:31], v[182:185], v[198:201], v[28:31]
	v_mfma_f32_16x16x32_bf16 v[20:23], v[174:177], v[206:209], v[20:23]
	v_mfma_f32_16x16x32_bf16 v[12:15], v[182:185], v[206:209], v[12:15]
	v_mfma_f32_16x16x32_bf16 v[4:7], v[174:177], v[214:217], v[4:7]
	v_mfma_f32_16x16x32_bf16 v[0:3], v[182:185], v[214:217], v[0:3]
	s_barrier
	s_add_i32 s73, 0, 0x18000
	v_add_u32_e32 v153, s73, v148
	s_add_i32 s74, 0, 0x1c000
	ds_read_b128 v[154:157], v153
	ds_read_b128 v[158:161], v153 offset:1024
	ds_read_b128 v[162:165], v153 offset:2048
	ds_read_b128 v[166:169], v153 offset:3072
	v_add_u32_e32 v153, s74, v148
	ds_read_b128 v[170:173], v153
	ds_read_b128 v[174:177], v153 offset:1024
	ds_read_b128 v[178:181], v153 offset:2048
	ds_read_b128 v[182:185], v153 offset:3072
	s_add_u32 s56, s56, 0x40000
	s_addc_u32 s57, s57, 0
	s_mov_b32 m0, s42
	ds_read_b128 v[186:189], v152 offset:32768
	ds_read_b128 v[190:193], v152 offset:33792
	ds_read_b128 v[194:197], v152 offset:34816
	ds_read_b128 v[198:201], v152 offset:35840
	ds_read_b128 v[202:205], v152 offset:36864
	ds_read_b128 v[206:209], v152 offset:37888
	ds_read_b128 v[210:213], v152 offset:38912
	ds_read_b128 v[214:217], v152 offset:39936
	global_load_lds_dwordx4 v128, s[56:57]
	s_mov_b32 m0, s43
	s_nop 0
	global_load_lds_dwordx4 v132, s[56:57]
	s_waitcnt vmcnt(8)
	s_waitcnt lgkmcnt(0)
	s_barrier
	v_mfma_f32_16x16x32_bf16 v[124:127], v[154:157], v[186:189], v[124:127]
	v_mfma_f32_16x16x32_bf16 v[120:123], v[162:165], v[186:189], v[120:123]
	v_mfma_f32_16x16x32_bf16 v[112:115], v[154:157], v[194:197], v[112:115]
	v_mfma_f32_16x16x32_bf16 v[104:107], v[162:165], v[194:197], v[104:107]
	v_mfma_f32_16x16x32_bf16 v[96:99], v[154:157], v[202:205], v[96:99]
	v_mfma_f32_16x16x32_bf16 v[88:91], v[162:165], v[202:205], v[88:91]
	v_mfma_f32_16x16x32_bf16 v[80:83], v[154:157], v[210:213], v[80:83]
	v_mfma_f32_16x16x32_bf16 v[72:75], v[162:165], v[210:213], v[72:75]
	v_mfma_f32_16x16x32_bf16 v[124:127], v[158:161], v[190:193], v[124:127]
	v_mfma_f32_16x16x32_bf16 v[120:123], v[166:169], v[190:193], v[120:123]
	v_mfma_f32_16x16x32_bf16 v[112:115], v[158:161], v[198:201], v[112:115]
	v_mfma_f32_16x16x32_bf16 v[104:107], v[166:169], v[198:201], v[104:107]
	v_mfma_f32_16x16x32_bf16 v[96:99], v[158:161], v[206:209], v[96:99]
	v_mfma_f32_16x16x32_bf16 v[88:91], v[166:169], v[206:209], v[88:91]
	v_mfma_f32_16x16x32_bf16 v[80:83], v[158:161], v[214:217], v[80:83]
	v_mfma_f32_16x16x32_bf16 v[72:75], v[166:169], v[214:217], v[72:75]
	v_mfma_f32_16x16x32_bf16 v[116:119], v[170:173], v[186:189], v[116:119]
	v_mfma_f32_16x16x32_bf16 v[108:111], v[178:181], v[186:189], v[108:111]
	v_mfma_f32_16x16x32_bf16 v[100:103], v[170:173], v[194:197], v[100:103]
	v_mfma_f32_16x16x32_bf16 v[92:95], v[178:181], v[194:197], v[92:95]
	v_mfma_f32_16x16x32_bf16 v[84:87], v[170:173], v[202:205], v[84:87]
	v_mfma_f32_16x16x32_bf16 v[76:79], v[178:181], v[202:205], v[76:79]
	v_mfma_f32_16x16x32_bf16 v[68:71], v[170:173], v[210:213], v[68:71]
	v_mfma_f32_16x16x32_bf16 v[64:67], v[178:181], v[210:213], v[64:67]
	v_mfma_f32_16x16x32_bf16 v[116:119], v[174:177], v[190:193], v[116:119]
	v_mfma_f32_16x16x32_bf16 v[108:111], v[182:185], v[190:193], v[108:111]
	v_mfma_f32_16x16x32_bf16 v[100:103], v[174:177], v[198:201], v[100:103]
	v_mfma_f32_16x16x32_bf16 v[92:95], v[182:185], v[198:201], v[92:95]
	v_mfma_f32_16x16x32_bf16 v[84:87], v[174:177], v[206:209], v[84:87]
	v_mfma_f32_16x16x32_bf16 v[76:79], v[182:185], v[206:209], v[76:79]
	v_mfma_f32_16x16x32_bf16 v[68:71], v[174:177], v[214:217], v[68:71]
	v_mfma_f32_16x16x32_bf16 v[64:67], v[182:185], v[214:217], v[64:67]
	s_barrier
	s_add_i32 s56, s73, s35
	v_lshl_add_u64 v[144:145], v[144:145], 0, s[8:9]
	s_mov_b32 m0, s56
	ds_read_b128 v[186:189], v152 offset:49152
	ds_read_b128 v[190:193], v152 offset:50176
	ds_read_b128 v[194:197], v152 offset:51200
	ds_read_b128 v[198:201], v152 offset:52224
	ds_read_b128 v[202:205], v152 offset:53248
	ds_read_b128 v[206:209], v152 offset:54272
	ds_read_b128 v[210:213], v152 offset:55296
	ds_read_b128 v[214:217], v152 offset:56320
	global_load_lds_dwordx4 v[144:145], off
	s_add_i32 m0, s56, 0x2000
	s_add_u32 s54, s54, 0x40080
	v_lshl_add_u64 v[144:145], v[218:219], 0, s[8:9]
	s_addc_u32 s55, s55, 0
	s_add_i32 s56, s74, s35
	global_load_lds_dwordx4 v[144:145], off
	s_mov_b32 m0, s56
	s_nop 0
	global_load_lds_dwordx4 v130, s[54:55]
	s_add_i32 m0, s56, 0x2000
	s_nop 0
	global_load_lds_dwordx4 v134, s[54:55]
	v_lshl_add_u64 v[144:145], v[220:221], 0, s[8:9]
	s_mov_b32 m0, s58
	s_nop 0
	global_load_lds_dwordx4 v[144:145], off
	v_lshl_add_u64 v[144:145], v[222:223], 0, s[8:9]
	s_mov_b32 m0, s59
	s_nop 0
	global_load_lds_dwordx4 v[144:145], off
	s_waitcnt vmcnt(8)
	s_waitcnt lgkmcnt(0)
	s_barrier
	v_mfma_f32_16x16x32_bf16 v[60:63], v[154:157], v[186:189], v[60:63]
	v_mfma_f32_16x16x32_bf16 v[56:59], v[162:165], v[186:189], v[56:59]
	v_mfma_f32_16x16x32_bf16 v[48:51], v[154:157], v[194:197], v[48:51]
	v_mfma_f32_16x16x32_bf16 v[40:43], v[162:165], v[194:197], v[40:43]
	v_mfma_f32_16x16x32_bf16 v[32:35], v[154:157], v[202:205], v[32:35]
	v_mfma_f32_16x16x32_bf16 v[24:27], v[162:165], v[202:205], v[24:27]
	v_mfma_f32_16x16x32_bf16 v[16:19], v[154:157], v[210:213], v[16:19]
	v_mfma_f32_16x16x32_bf16 v[8:11], v[162:165], v[210:213], v[8:11]
	v_mfma_f32_16x16x32_bf16 v[60:63], v[158:161], v[190:193], v[60:63]
	v_mfma_f32_16x16x32_bf16 v[56:59], v[166:169], v[190:193], v[56:59]
	v_mfma_f32_16x16x32_bf16 v[48:51], v[158:161], v[198:201], v[48:51]
	v_mfma_f32_16x16x32_bf16 v[40:43], v[166:169], v[198:201], v[40:43]
	v_mfma_f32_16x16x32_bf16 v[32:35], v[158:161], v[206:209], v[32:35]
	v_mfma_f32_16x16x32_bf16 v[24:27], v[166:169], v[206:209], v[24:27]
	v_mfma_f32_16x16x32_bf16 v[16:19], v[158:161], v[214:217], v[16:19]
	v_mfma_f32_16x16x32_bf16 v[8:11], v[166:169], v[214:217], v[8:11]
	v_mfma_f32_16x16x32_bf16 v[52:55], v[170:173], v[186:189], v[52:55]
	v_mfma_f32_16x16x32_bf16 v[44:47], v[178:181], v[186:189], v[44:47]
	v_mfma_f32_16x16x32_bf16 v[36:39], v[170:173], v[194:197], v[36:39]
	v_mfma_f32_16x16x32_bf16 v[28:31], v[178:181], v[194:197], v[28:31]
	v_mfma_f32_16x16x32_bf16 v[20:23], v[170:173], v[202:205], v[20:23]
	v_mfma_f32_16x16x32_bf16 v[12:15], v[178:181], v[202:205], v[12:15]
	v_mfma_f32_16x16x32_bf16 v[4:7], v[170:173], v[210:213], v[4:7]
	v_mfma_f32_16x16x32_bf16 v[0:3], v[178:181], v[210:213], v[0:3]
	v_mfma_f32_16x16x32_bf16 v[52:55], v[174:177], v[190:193], v[52:55]
	v_mfma_f32_16x16x32_bf16 v[44:47], v[182:185], v[190:193], v[44:47]
	v_mfma_f32_16x16x32_bf16 v[36:39], v[174:177], v[198:201], v[36:39]
	v_mfma_f32_16x16x32_bf16 v[28:31], v[182:185], v[198:201], v[28:31]
	v_mfma_f32_16x16x32_bf16 v[20:23], v[174:177], v[206:209], v[20:23]
	v_mfma_f32_16x16x32_bf16 v[12:15], v[182:185], v[206:209], v[12:15]
	v_mfma_f32_16x16x32_bf16 v[4:7], v[174:177], v[214:217], v[4:7]
	v_mfma_f32_16x16x32_bf16 v[0:3], v[182:185], v[214:217], v[0:3]
	s_barrier
	s_add_i32 s72, s72, 2
	s_add_u32 s52, s52, 0x100
	s_addc_u32 s53, s53, 0
	s_add_u32 s70, s70, 0x100
	s_addc_u32 s71, s71, 0
	s_cmp_gt_u32 s72, 13
	s_cbranch_scc0 .LBB0_2129
	v_readlane_b32 s72, v245, 54
	s_and_b64 vcc, exec, s[10:11]
	v_readlane_b32 s73, v245, 55
	s_cbranch_vccz .LBB0_2132
	s_barrier

.LBB0_2259:
	ds_read_b128 v[154:157], v150
	ds_read_b128 v[158:161], v150 offset:1024
	ds_read_b128 v[162:165], v150 offset:2048
	ds_read_b128 v[166:169], v150 offset:3072
	ds_read_b128 v[170:173], v151
	ds_read_b128 v[174:177], v151 offset:1024
	ds_read_b128 v[178:181], v151 offset:2048
	ds_read_b128 v[182:185], v151 offset:3072
	s_add_u32 s44, s38, 0xfffc0080
	s_addc_u32 s45, s39, -1
	s_cmp_eq_u32 s61, 12
	s_cselect_b32 s47, s0, s45
	s_cselect_b32 s46, s1, s44
	s_cselect_b32 s45, s11, s60
	s_cselect_b32 s44, s13, s59
	s_add_i32 m0, s19, 0xc000
	ds_read_b128 v[186:189], v152
	ds_read_b128 v[190:193], v152 offset:1024
	ds_read_b128 v[194:197], v152 offset:2048
	ds_read_b128 v[198:201], v152 offset:3072
	ds_read_b128 v[202:205], v152 offset:4096
	ds_read_b128 v[206:209], v152 offset:5120
	ds_read_b128 v[210:213], v152 offset:6144
	ds_read_b128 v[214:217], v152 offset:7168
	global_load_lds_dwordx4 v136, s[38:39]
	s_add_i32 m0, s19, 0xe000
	s_nop 0
	global_load_lds_dwordx4 v138, s[38:39]
	s_waitcnt vmcnt(8)
	s_waitcnt lgkmcnt(0)
	s_barrier
	v_mfma_f32_16x16x32_bf16 v[124:127], v[154:157], v[186:189], v[124:127]
	v_mfma_f32_16x16x32_bf16 v[120:123], v[162:165], v[186:189], v[120:123]
	v_mfma_f32_16x16x32_bf16 v[108:111], v[154:157], v[194:197], v[108:111]
	v_mfma_f32_16x16x32_bf16 v[104:107], v[162:165], v[194:197], v[104:107]
	v_mfma_f32_16x16x32_bf16 v[92:95], v[154:157], v[202:205], v[92:95]
	v_mfma_f32_16x16x32_bf16 v[88:91], v[162:165], v[202:205], v[88:91]
	v_mfma_f32_16x16x32_bf16 v[76:79], v[154:157], v[210:213], v[76:79]
	v_mfma_f32_16x16x32_bf16 v[72:75], v[162:165], v[210:213], v[72:75]
	v_mfma_f32_16x16x32_bf16 v[124:127], v[158:161], v[190:193], v[124:127]
	v_mfma_f32_16x16x32_bf16 v[120:123], v[166:169], v[190:193], v[120:123]
	v_mfma_f32_16x16x32_bf16 v[108:111], v[158:161], v[198:201], v[108:111]
	v_mfma_f32_16x16x32_bf16 v[104:107], v[166:169], v[198:201], v[104:107]
	v_mfma_f32_16x16x32_bf16 v[92:95], v[158:161], v[206:209], v[92:95]
	v_mfma_f32_16x16x32_bf16 v[88:91], v[166:169], v[206:209], v[88:91]
	v_mfma_f32_16x16x32_bf16 v[76:79], v[158:161], v[214:217], v[76:79]
	v_mfma_f32_16x16x32_bf16 v[72:75], v[166:169], v[214:217], v[72:75]
	v_mfma_f32_16x16x32_bf16 v[116:119], v[170:173], v[186:189], v[116:119]
	v_mfma_f32_16x16x32_bf16 v[112:115], v[178:181], v[186:189], v[112:115]
	v_mfma_f32_16x16x32_bf16 v[100:103], v[170:173], v[194:197], v[100:103]
	v_mfma_f32_16x16x32_bf16 v[96:99], v[178:181], v[194:197], v[96:99]
	v_mfma_f32_16x16x32_bf16 v[84:87], v[170:173], v[202:205], v[84:87]
	v_mfma_f32_16x16x32_bf16 v[80:83], v[178:181], v[202:205], v[80:83]
	v_mfma_f32_16x16x32_bf16 v[68:71], v[170:173], v[210:213], v[68:71]
	v_mfma_f32_16x16x32_bf16 v[64:67], v[178:181], v[210:213], v[64:67]
	v_mfma_f32_16x16x32_bf16 v[116:119], v[174:177], v[190:193], v[116:119]
	v_mfma_f32_16x16x32_bf16 v[112:115], v[182:185], v[190:193], v[112:115]
	v_mfma_f32_16x16x32_bf16 v[100:103], v[174:177], v[198:201], v[100:103]
	v_mfma_f32_16x16x32_bf16 v[96:99], v[182:185], v[198:201], v[96:99]
	v_mfma_f32_16x16x32_bf16 v[84:87], v[174:177], v[206:209], v[84:87]
	v_mfma_f32_16x16x32_bf16 v[80:83], v[182:185], v[206:209], v[80:83]
	v_mfma_f32_16x16x32_bf16 v[68:71], v[174:177], v[214:217], v[68:71]
	v_mfma_f32_16x16x32_bf16 v[64:67], v[182:185], v[214:217], v[64:67]
	s_barrier
	s_add_i32 s62, s55, s23
	v_lshl_add_u64 v[144:145], s[44:45], 0, v[128:129]
	s_mov_b32 m0, s62
	ds_read_b128 v[186:189], v152 offset:16384
	ds_read_b128 v[190:193], v152 offset:17408
	ds_read_b128 v[194:197], v152 offset:18432
	ds_read_b128 v[198:201], v152 offset:19456
	ds_read_b128 v[202:205], v152 offset:20480
	ds_read_b128 v[206:209], v152 offset:21504
	ds_read_b128 v[210:213], v152 offset:22528
	ds_read_b128 v[214:217], v152 offset:23552
	global_load_lds_dwordx4 v[144:145], off
	s_add_i32 m0, s62, 0x2000
	s_add_u32 s62, s44, 0x40000
	v_lshl_add_u64 v[218:219], s[44:45], 0, v[130:131]
	s_addc_u32 s63, s45, 0
	s_add_i32 s64, s56, s23
	global_load_lds_dwordx4 v[218:219], off
	s_mov_b32 m0, s64
	v_lshl_add_u64 v[222:223], s[46:47], 0, v[132:133]
	global_load_lds_dwordx4 v128, s[62:63]
	s_add_i32 m0, s64, 0x2000
	s_nop 0
	global_load_lds_dwordx4 v130, s[62:63]
	v_lshl_add_u64 v[220:221], s[46:47], 0, v[134:135]
	s_mov_b32 m0, s19
	s_nop 0
	global_load_lds_dwordx4 v[220:221], off
	s_mov_b32 m0, s43
	s_nop 0
	global_load_lds_dwordx4 v[222:223], off
	s_waitcnt vmcnt(8)
	s_waitcnt lgkmcnt(0)
	s_barrier
	v_mfma_f32_16x16x32_bf16 v[60:63], v[154:157], v[186:189], v[60:63]
	v_mfma_f32_16x16x32_bf16 v[56:59], v[162:165], v[186:189], v[56:59]
	v_mfma_f32_16x16x32_bf16 v[44:47], v[154:157], v[194:197], v[44:47]
	v_mfma_f32_16x16x32_bf16 v[40:43], v[162:165], v[194:197], v[40:43]
	v_mfma_f32_16x16x32_bf16 v[28:31], v[154:157], v[202:205], v[28:31]
	v_mfma_f32_16x16x32_bf16 v[24:27], v[162:165], v[202:205], v[24:27]
	v_mfma_f32_16x16x32_bf16 v[12:15], v[154:157], v[210:213], v[12:15]
	v_mfma_f32_16x16x32_bf16 v[8:11], v[162:165], v[210:213], v[8:11]
	v_mfma_f32_16x16x32_bf16 v[60:63], v[158:161], v[190:193], v[60:63]
	v_mfma_f32_16x16x32_bf16 v[56:59], v[166:169], v[190:193], v[56:59]
	v_mfma_f32_16x16x32_bf16 v[44:47], v[158:161], v[198:201], v[44:47]
	v_mfma_f32_16x16x32_bf16 v[40:43], v[166:169], v[198:201], v[40:43]
	v_mfma_f32_16x16x32_bf16 v[28:31], v[158:161], v[206:209], v[28:31]
	v_mfma_f32_16x16x32_bf16 v[24:27], v[166:169], v[206:209], v[24:27]
	v_mfma_f32_16x16x32_bf16 v[12:15], v[158:161], v[214:217], v[12:15]
	v_mfma_f32_16x16x32_bf16 v[8:11], v[166:169], v[214:217], v[8:11]
	v_mfma_f32_16x16x32_bf16 v[52:55], v[170:173], v[186:189], v[52:55]
	v_mfma_f32_16x16x32_bf16 v[48:51], v[178:181], v[186:189], v[48:51]
	v_mfma_f32_16x16x32_bf16 v[36:39], v[170:173], v[194:197], v[36:39]
	v_mfma_f32_16x16x32_bf16 v[32:35], v[178:181], v[194:197], v[32:35]
	v_mfma_f32_16x16x32_bf16 v[20:23], v[170:173], v[202:205], v[20:23]
	v_mfma_f32_16x16x32_bf16 v[16:19], v[178:181], v[202:205], v[16:19]
	v_mfma_f32_16x16x32_bf16 v[4:7], v[170:173], v[210:213], v[4:7]
	v_mfma_f32_16x16x32_bf16 v[0:3], v[178:181], v[210:213], v[0:3]
	v_mfma_f32_16x16x32_bf16 v[52:55], v[174:177], v[190:193], v[52:55]
	v_mfma_f32_16x16x32_bf16 v[48:51], v[182:185], v[190:193], v[48:51]
	v_mfma_f32_16x16x32_bf16 v[36:39], v[174:177], v[198:201], v[36:39]
	v_mfma_f32_16x16x32_bf16 v[32:35], v[182:185], v[198:201], v[32:35]
	v_mfma_f32_16x16x32_bf16 v[20:23], v[174:177], v[206:209], v[20:23]
	v_mfma_f32_16x16x32_bf16 v[16:19], v[182:185], v[206:209], v[16:19]
	v_mfma_f32_16x16x32_bf16 v[4:7], v[174:177], v[214:217], v[4:7]
	v_mfma_f32_16x16x32_bf16 v[0:3], v[182:185], v[214:217], v[0:3]
	s_barrier
	s_add_i32 s62, 0, 0x18000
	v_add_u32_e32 v153, s62, v148
	s_add_i32 s63, 0, 0x1c000
	ds_read_b128 v[154:157], v153
	ds_read_b128 v[158:161], v153 offset:1024
	ds_read_b128 v[162:165], v153 offset:2048
	ds_read_b128 v[166:169], v153 offset:3072
	v_add_u32_e32 v153, s63, v148
	ds_read_b128 v[170:173], v153
	ds_read_b128 v[174:177], v153 offset:1024
	ds_read_b128 v[178:181], v153 offset:2048
	ds_read_b128 v[182:185], v153 offset:3072
	s_add_u32 s46, s46, 0x40000
	s_addc_u32 s47, s47, 0
	s_mov_b32 m0, s48
	ds_read_b128 v[186:189], v152 offset:32768
	ds_read_b128 v[190:193], v152 offset:33792
	ds_read_b128 v[194:197], v152 offset:34816
	ds_read_b128 v[198:201], v152 offset:35840
	ds_read_b128 v[202:205], v152 offset:36864
	ds_read_b128 v[206:209], v152 offset:37888
	ds_read_b128 v[210:213], v152 offset:38912
	ds_read_b128 v[214:217], v152 offset:39936
	global_load_lds_dwordx4 v134, s[46:47]
	s_mov_b32 m0, s49
	s_nop 0
	global_load_lds_dwordx4 v132, s[46:47]
	s_waitcnt vmcnt(8)
	s_waitcnt lgkmcnt(0)
	s_barrier
	v_mfma_f32_16x16x32_bf16 v[124:127], v[154:157], v[186:189], v[124:127]
	v_mfma_f32_16x16x32_bf16 v[120:123], v[162:165], v[186:189], v[120:123]
	v_mfma_f32_16x16x32_bf16 v[108:111], v[154:157], v[194:197], v[108:111]
	v_mfma_f32_16x16x32_bf16 v[104:107], v[162:165], v[194:197], v[104:107]
	v_mfma_f32_16x16x32_bf16 v[92:95], v[154:157], v[202:205], v[92:95]
	v_mfma_f32_16x16x32_bf16 v[88:91], v[162:165], v[202:205], v[88:91]
	v_mfma_f32_16x16x32_bf16 v[76:79], v[154:157], v[210:213], v[76:79]
	v_mfma_f32_16x16x32_bf16 v[72:75], v[162:165], v[210:213], v[72:75]
	v_mfma_f32_16x16x32_bf16 v[124:127], v[158:161], v[190:193], v[124:127]
	v_mfma_f32_16x16x32_bf16 v[120:123], v[166:169], v[190:193], v[120:123]
	v_mfma_f32_16x16x32_bf16 v[108:111], v[158:161], v[198:201], v[108:111]
	v_mfma_f32_16x16x32_bf16 v[104:107], v[166:169], v[198:201], v[104:107]
	v_mfma_f32_16x16x32_bf16 v[92:95], v[158:161], v[206:209], v[92:95]
	v_mfma_f32_16x16x32_bf16 v[88:91], v[166:169], v[206:209], v[88:91]
	v_mfma_f32_16x16x32_bf16 v[76:79], v[158:161], v[214:217], v[76:79]
	v_mfma_f32_16x16x32_bf16 v[72:75], v[166:169], v[214:217], v[72:75]
	v_mfma_f32_16x16x32_bf16 v[116:119], v[170:173], v[186:189], v[116:119]
	v_mfma_f32_16x16x32_bf16 v[112:115], v[178:181], v[186:189], v[112:115]
	v_mfma_f32_16x16x32_bf16 v[100:103], v[170:173], v[194:197], v[100:103]
	v_mfma_f32_16x16x32_bf16 v[96:99], v[178:181], v[194:197], v[96:99]
	v_mfma_f32_16x16x32_bf16 v[84:87], v[170:173], v[202:205], v[84:87]
	v_mfma_f32_16x16x32_bf16 v[80:83], v[178:181], v[202:205], v[80:83]
	v_mfma_f32_16x16x32_bf16 v[68:71], v[170:173], v[210:213], v[68:71]
	v_mfma_f32_16x16x32_bf16 v[64:67], v[178:181], v[210:213], v[64:67]
	v_mfma_f32_16x16x32_bf16 v[116:119], v[174:177], v[190:193], v[116:119]
	v_mfma_f32_16x16x32_bf16 v[112:115], v[182:185], v[190:193], v[112:115]
	v_mfma_f32_16x16x32_bf16 v[100:103], v[174:177], v[198:201], v[100:103]
	v_mfma_f32_16x16x32_bf16 v[96:99], v[182:185], v[198:201], v[96:99]
	v_mfma_f32_16x16x32_bf16 v[84:87], v[174:177], v[206:209], v[84:87]
	v_mfma_f32_16x16x32_bf16 v[80:83], v[182:185], v[206:209], v[80:83]
	v_mfma_f32_16x16x32_bf16 v[68:71], v[174:177], v[214:217], v[68:71]
	v_mfma_f32_16x16x32_bf16 v[64:67], v[182:185], v[214:217], v[64:67]
	s_barrier
	s_add_i32 s46, s62, s23
	v_lshl_add_u64 v[144:145], v[144:145], 0, s[6:7]
	s_mov_b32 m0, s46
	ds_read_b128 v[186:189], v152 offset:49152
	ds_read_b128 v[190:193], v152 offset:50176
	ds_read_b128 v[194:197], v152 offset:51200
	ds_read_b128 v[198:201], v152 offset:52224
	ds_read_b128 v[202:205], v152 offset:53248
	ds_read_b128 v[206:209], v152 offset:54272
	ds_read_b128 v[210:213], v152 offset:55296
	ds_read_b128 v[214:217], v152 offset:56320
	global_load_lds_dwordx4 v[144:145], off
	s_add_i32 m0, s46, 0x2000
	s_add_u32 s44, s44, 0x40080
	v_lshl_add_u64 v[144:145], v[218:219], 0, s[6:7]
	s_addc_u32 s45, s45, 0
	s_add_i32 s46, s63, s23
	global_load_lds_dwordx4 v[144:145], off
	s_mov_b32 m0, s46
	s_nop 0
	global_load_lds_dwordx4 v128, s[44:45]
	s_add_i32 m0, s46, 0x2000
	s_nop 0
	global_load_lds_dwordx4 v130, s[44:45]
	v_lshl_add_u64 v[144:145], v[220:221], 0, s[6:7]
	s_mov_b32 m0, s51
	s_nop 0
	global_load_lds_dwordx4 v[144:145], off
	v_lshl_add_u64 v[144:145], v[222:223], 0, s[6:7]
	s_mov_b32 m0, s52
	s_nop 0
	global_load_lds_dwordx4 v[144:145], off
	s_waitcnt vmcnt(8)
	s_waitcnt lgkmcnt(0)
	s_barrier
	v_mfma_f32_16x16x32_bf16 v[60:63], v[154:157], v[186:189], v[60:63]
	v_mfma_f32_16x16x32_bf16 v[56:59], v[162:165], v[186:189], v[56:59]
	v_mfma_f32_16x16x32_bf16 v[44:47], v[154:157], v[194:197], v[44:47]
	v_mfma_f32_16x16x32_bf16 v[40:43], v[162:165], v[194:197], v[40:43]
	v_mfma_f32_16x16x32_bf16 v[28:31], v[154:157], v[202:205], v[28:31]
	v_mfma_f32_16x16x32_bf16 v[24:27], v[162:165], v[202:205], v[24:27]
	v_mfma_f32_16x16x32_bf16 v[12:15], v[154:157], v[210:213], v[12:15]
	v_mfma_f32_16x16x32_bf16 v[8:11], v[162:165], v[210:213], v[8:11]
	v_mfma_f32_16x16x32_bf16 v[60:63], v[158:161], v[190:193], v[60:63]
	v_mfma_f32_16x16x32_bf16 v[56:59], v[166:169], v[190:193], v[56:59]
	v_mfma_f32_16x16x32_bf16 v[44:47], v[158:161], v[198:201], v[44:47]
	v_mfma_f32_16x16x32_bf16 v[40:43], v[166:169], v[198:201], v[40:43]
	v_mfma_f32_16x16x32_bf16 v[28:31], v[158:161], v[206:209], v[28:31]
	v_mfma_f32_16x16x32_bf16 v[24:27], v[166:169], v[206:209], v[24:27]
	v_mfma_f32_16x16x32_bf16 v[12:15], v[158:161], v[214:217], v[12:15]
	v_mfma_f32_16x16x32_bf16 v[8:11], v[166:169], v[214:217], v[8:11]
	v_mfma_f32_16x16x32_bf16 v[52:55], v[170:173], v[186:189], v[52:55]
	v_mfma_f32_16x16x32_bf16 v[48:51], v[178:181], v[186:189], v[48:51]
	v_mfma_f32_16x16x32_bf16 v[36:39], v[170:173], v[194:197], v[36:39]
	v_mfma_f32_16x16x32_bf16 v[32:35], v[178:181], v[194:197], v[32:35]
	v_mfma_f32_16x16x32_bf16 v[20:23], v[170:173], v[202:205], v[20:23]
	v_mfma_f32_16x16x32_bf16 v[16:19], v[178:181], v[202:205], v[16:19]
	v_mfma_f32_16x16x32_bf16 v[4:7], v[170:173], v[210:213], v[4:7]
	v_mfma_f32_16x16x32_bf16 v[0:3], v[178:181], v[210:213], v[0:3]
	v_mfma_f32_16x16x32_bf16 v[52:55], v[174:177], v[190:193], v[52:55]
	v_mfma_f32_16x16x32_bf16 v[48:51], v[182:185], v[190:193], v[48:51]
	v_mfma_f32_16x16x32_bf16 v[36:39], v[174:177], v[198:201], v[36:39]
	v_mfma_f32_16x16x32_bf16 v[32:35], v[182:185], v[198:201], v[32:35]
	v_mfma_f32_16x16x32_bf16 v[20:23], v[174:177], v[206:209], v[20:23]
	v_mfma_f32_16x16x32_bf16 v[16:19], v[182:185], v[206:209], v[16:19]
	v_mfma_f32_16x16x32_bf16 v[4:7], v[174:177], v[214:217], v[4:7]
	v_mfma_f32_16x16x32_bf16 v[0:3], v[182:185], v[214:217], v[0:3]
	s_barrier
	s_add_i32 s61, s61, 2
	s_add_u32 s38, s38, 0x100
	s_addc_u32 s39, s39, 0
	s_add_u32 s59, s59, 0x100
	s_addc_u32 s60, s60, 0
	s_cmp_gt_u32 s61, 13
	s_cbranch_scc0 .LBB0_2259
	s_and_b64 vcc, exec, s[8:9]
	s_cbranch_vccz .LBB0_2262
	s_barrier

.LBB0_2339:
	ds_read_b128 v[154:157], v150
	ds_read_b128 v[158:161], v150 offset:1024
	ds_read_b128 v[162:165], v150 offset:2048
	ds_read_b128 v[166:169], v150 offset:3072
	ds_read_b128 v[170:173], v151
	ds_read_b128 v[174:177], v151 offset:1024
	ds_read_b128 v[178:181], v151 offset:2048
	ds_read_b128 v[182:185], v151 offset:3072
	s_add_u32 s46, s44, 0x100
	s_addc_u32 s47, s45, 0
	s_cmp_eq_u32 s69, 40
	s_cselect_b32 s51, s5, s47
	s_cselect_b32 s50, s4, s46
	s_cselect_b32 s49, s39, s1
	s_cselect_b32 s48, s38, s0
	s_add_i32 m0, s42, 0xc000
	ds_read_b128 v[186:189], v152
	ds_read_b128 v[190:193], v152 offset:1024
	ds_read_b128 v[194:197], v152 offset:2048
	ds_read_b128 v[198:201], v152 offset:3072
	ds_read_b128 v[202:205], v152 offset:4096
	ds_read_b128 v[206:209], v152 offset:5120
	ds_read_b128 v[210:213], v152 offset:6144
	ds_read_b128 v[214:217], v152 offset:7168
	global_load_lds_dwordx4 v136, s[44:45]
	s_add_i32 m0, s42, 0xe000
	s_nop 0
	global_load_lds_dwordx4 v138, s[44:45]
	s_waitcnt vmcnt(8)
	s_waitcnt lgkmcnt(0)
	s_barrier
	v_mfma_f32_16x16x32_bf16 v[124:127], v[154:157], v[186:189], v[124:127]
	v_mfma_f32_16x16x32_bf16 v[120:123], v[162:165], v[186:189], v[120:123]
	v_mfma_f32_16x16x32_bf16 v[112:115], v[154:157], v[194:197], v[112:115]
	v_mfma_f32_16x16x32_bf16 v[104:107], v[162:165], v[194:197], v[104:107]
	v_mfma_f32_16x16x32_bf16 v[96:99], v[154:157], v[202:205], v[96:99]
	v_mfma_f32_16x16x32_bf16 v[88:91], v[162:165], v[202:205], v[88:91]
	v_mfma_f32_16x16x32_bf16 v[80:83], v[154:157], v[210:213], v[80:83]
	v_mfma_f32_16x16x32_bf16 v[72:75], v[162:165], v[210:213], v[72:75]
	v_mfma_f32_16x16x32_bf16 v[124:127], v[158:161], v[190:193], v[124:127]
	v_mfma_f32_16x16x32_bf16 v[120:123], v[166:169], v[190:193], v[120:123]
	v_mfma_f32_16x16x32_bf16 v[112:115], v[158:161], v[198:201], v[112:115]
	v_mfma_f32_16x16x32_bf16 v[104:107], v[166:169], v[198:201], v[104:107]
	v_mfma_f32_16x16x32_bf16 v[96:99], v[158:161], v[206:209], v[96:99]
	v_mfma_f32_16x16x32_bf16 v[88:91], v[166:169], v[206:209], v[88:91]
	v_mfma_f32_16x16x32_bf16 v[80:83], v[158:161], v[214:217], v[80:83]
	v_mfma_f32_16x16x32_bf16 v[72:75], v[166:169], v[214:217], v[72:75]
	v_mfma_f32_16x16x32_bf16 v[116:119], v[170:173], v[186:189], v[116:119]
	v_mfma_f32_16x16x32_bf16 v[108:111], v[178:181], v[186:189], v[108:111]
	v_mfma_f32_16x16x32_bf16 v[100:103], v[170:173], v[194:197], v[100:103]
	v_mfma_f32_16x16x32_bf16 v[92:95], v[178:181], v[194:197], v[92:95]
	v_mfma_f32_16x16x32_bf16 v[84:87], v[170:173], v[202:205], v[84:87]
	v_mfma_f32_16x16x32_bf16 v[76:79], v[178:181], v[202:205], v[76:79]
	v_mfma_f32_16x16x32_bf16 v[68:71], v[170:173], v[210:213], v[68:71]
	v_mfma_f32_16x16x32_bf16 v[64:67], v[178:181], v[210:213], v[64:67]
	v_mfma_f32_16x16x32_bf16 v[116:119], v[174:177], v[190:193], v[116:119]
	v_mfma_f32_16x16x32_bf16 v[108:111], v[182:185], v[190:193], v[108:111]
	v_mfma_f32_16x16x32_bf16 v[100:103], v[174:177], v[198:201], v[100:103]
	v_mfma_f32_16x16x32_bf16 v[92:95], v[182:185], v[198:201], v[92:95]
	v_mfma_f32_16x16x32_bf16 v[84:87], v[174:177], v[206:209], v[84:87]
	v_mfma_f32_16x16x32_bf16 v[76:79], v[182:185], v[206:209], v[76:79]
	v_mfma_f32_16x16x32_bf16 v[68:71], v[174:177], v[214:217], v[68:71]
	v_mfma_f32_16x16x32_bf16 v[64:67], v[182:185], v[214:217], v[64:67]
	s_barrier
	s_add_i32 s44, s59, s35
	v_lshl_add_u64 v[144:145], s[48:49], 0, v[130:131]
	s_mov_b32 m0, s44
	ds_read_b128 v[186:189], v152 offset:16384
	ds_read_b128 v[190:193], v152 offset:17408
	ds_read_b128 v[194:197], v152 offset:18432
	ds_read_b128 v[198:201], v152 offset:19456
	ds_read_b128 v[202:205], v152 offset:20480
	ds_read_b128 v[206:209], v152 offset:21504
	ds_read_b128 v[210:213], v152 offset:22528
	ds_read_b128 v[214:217], v152 offset:23552
	global_load_lds_dwordx4 v[144:145], off
	s_add_i32 m0, s44, 0x2000
	s_add_u32 s44, s48, 0xb0000
	v_lshl_add_u64 v[218:219], s[48:49], 0, v[134:135]
	s_addc_u32 s45, s49, 0
	s_add_i32 s70, s60, s35
	global_load_lds_dwordx4 v[218:219], off
	s_mov_b32 m0, s70
	v_lshl_add_u64 v[222:223], s[50:51], 0, v[132:133]
	global_load_lds_dwordx4 v130, s[44:45]
	s_add_i32 m0, s70, 0x2000
	s_nop 0
	global_load_lds_dwordx4 v134, s[44:45]
	v_lshl_add_u64 v[220:221], s[50:51], 0, v[128:129]
	s_mov_b32 m0, s42
	s_nop 0
	global_load_lds_dwordx4 v[220:221], off
	s_mov_b32 m0, s43
	s_nop 0
	global_load_lds_dwordx4 v[222:223], off
	s_waitcnt vmcnt(8)
	s_waitcnt lgkmcnt(0)
	s_barrier
	v_mfma_f32_16x16x32_bf16 v[60:63], v[154:157], v[186:189], v[60:63]
	v_mfma_f32_16x16x32_bf16 v[56:59], v[162:165], v[186:189], v[56:59]
	v_mfma_f32_16x16x32_bf16 v[48:51], v[154:157], v[194:197], v[48:51]
	v_mfma_f32_16x16x32_bf16 v[40:43], v[162:165], v[194:197], v[40:43]
	v_mfma_f32_16x16x32_bf16 v[32:35], v[154:157], v[202:205], v[32:35]
	v_mfma_f32_16x16x32_bf16 v[24:27], v[162:165], v[202:205], v[24:27]
	v_mfma_f32_16x16x32_bf16 v[16:19], v[154:157], v[210:213], v[16:19]
	v_mfma_f32_16x16x32_bf16 v[8:11], v[162:165], v[210:213], v[8:11]
	v_mfma_f32_16x16x32_bf16 v[60:63], v[158:161], v[190:193], v[60:63]
	v_mfma_f32_16x16x32_bf16 v[56:59], v[166:169], v[190:193], v[56:59]
	v_mfma_f32_16x16x32_bf16 v[48:51], v[158:161], v[198:201], v[48:51]
	v_mfma_f32_16x16x32_bf16 v[40:43], v[166:169], v[198:201], v[40:43]
	v_mfma_f32_16x16x32_bf16 v[32:35], v[158:161], v[206:209], v[32:35]
	v_mfma_f32_16x16x32_bf16 v[24:27], v[166:169], v[206:209], v[24:27]
	v_mfma_f32_16x16x32_bf16 v[16:19], v[158:161], v[214:217], v[16:19]
	v_mfma_f32_16x16x32_bf16 v[8:11], v[166:169], v[214:217], v[8:11]
	v_mfma_f32_16x16x32_bf16 v[52:55], v[170:173], v[186:189], v[52:55]
	v_mfma_f32_16x16x32_bf16 v[44:47], v[178:181], v[186:189], v[44:47]
	v_mfma_f32_16x16x32_bf16 v[36:39], v[170:173], v[194:197], v[36:39]
	v_mfma_f32_16x16x32_bf16 v[28:31], v[178:181], v[194:197], v[28:31]
	v_mfma_f32_16x16x32_bf16 v[20:23], v[170:173], v[202:205], v[20:23]
	v_mfma_f32_16x16x32_bf16 v[12:15], v[178:181], v[202:205], v[12:15]
	v_mfma_f32_16x16x32_bf16 v[4:7], v[170:173], v[210:213], v[4:7]
	v_mfma_f32_16x16x32_bf16 v[0:3], v[178:181], v[210:213], v[0:3]
	v_mfma_f32_16x16x32_bf16 v[52:55], v[174:177], v[190:193], v[52:55]
	v_mfma_f32_16x16x32_bf16 v[44:47], v[182:185], v[190:193], v[44:47]
	v_mfma_f32_16x16x32_bf16 v[36:39], v[174:177], v[198:201], v[36:39]
	v_mfma_f32_16x16x32_bf16 v[28:31], v[182:185], v[198:201], v[28:31]
	v_mfma_f32_16x16x32_bf16 v[20:23], v[174:177], v[206:209], v[20:23]
	v_mfma_f32_16x16x32_bf16 v[12:15], v[182:185], v[206:209], v[12:15]
	v_mfma_f32_16x16x32_bf16 v[4:7], v[174:177], v[214:217], v[4:7]
	v_mfma_f32_16x16x32_bf16 v[0:3], v[182:185], v[214:217], v[0:3]
	s_barrier
	s_add_i32 s70, 0, 0x18000
	v_add_u32_e32 v153, s70, v148
	s_add_i32 s71, 0, 0x1c000
	ds_read_b128 v[154:157], v153
	ds_read_b128 v[158:161], v153 offset:1024
	ds_read_b128 v[162:165], v153 offset:2048
	ds_read_b128 v[166:169], v153 offset:3072
	v_add_u32_e32 v153, s71, v148
	ds_read_b128 v[170:173], v153
	ds_read_b128 v[174:177], v153 offset:1024
	ds_read_b128 v[178:181], v153 offset:2048
	ds_read_b128 v[182:185], v153 offset:3072
	s_add_u32 s44, s50, 0xb0000
	s_addc_u32 s45, s51, 0
	s_mov_b32 m0, s52
	ds_read_b128 v[186:189], v152 offset:32768
	ds_read_b128 v[190:193], v152 offset:33792
	ds_read_b128 v[194:197], v152 offset:34816
	ds_read_b128 v[198:201], v152 offset:35840
	ds_read_b128 v[202:205], v152 offset:36864
	ds_read_b128 v[206:209], v152 offset:37888
	ds_read_b128 v[210:213], v152 offset:38912
	ds_read_b128 v[214:217], v152 offset:39936
	global_load_lds_dwordx4 v128, s[44:45]
	s_mov_b32 m0, s53
	s_nop 0
	global_load_lds_dwordx4 v132, s[44:45]
	s_waitcnt vmcnt(8)
	s_waitcnt lgkmcnt(0)
	s_barrier
	v_mfma_f32_16x16x32_bf16 v[124:127], v[154:157], v[186:189], v[124:127]
	v_mfma_f32_16x16x32_bf16 v[120:123], v[162:165], v[186:189], v[120:123]
	v_mfma_f32_16x16x32_bf16 v[112:115], v[154:157], v[194:197], v[112:115]
	v_mfma_f32_16x16x32_bf16 v[104:107], v[162:165], v[194:197], v[104:107]
	v_mfma_f32_16x16x32_bf16 v[96:99], v[154:157], v[202:205], v[96:99]
	v_mfma_f32_16x16x32_bf16 v[88:91], v[162:165], v[202:205], v[88:91]
	v_mfma_f32_16x16x32_bf16 v[80:83], v[154:157], v[210:213], v[80:83]
	v_mfma_f32_16x16x32_bf16 v[72:75], v[162:165], v[210:213], v[72:75]
	v_mfma_f32_16x16x32_bf16 v[124:127], v[158:161], v[190:193], v[124:127]
	v_mfma_f32_16x16x32_bf16 v[120:123], v[166:169], v[190:193], v[120:123]
	v_mfma_f32_16x16x32_bf16 v[112:115], v[158:161], v[198:201], v[112:115]
	v_mfma_f32_16x16x32_bf16 v[104:107], v[166:169], v[198:201], v[104:107]
	v_mfma_f32_16x16x32_bf16 v[96:99], v[158:161], v[206:209], v[96:99]
	v_mfma_f32_16x16x32_bf16 v[88:91], v[166:169], v[206:209], v[88:91]
	v_mfma_f32_16x16x32_bf16 v[80:83], v[158:161], v[214:217], v[80:83]
	v_mfma_f32_16x16x32_bf16 v[72:75], v[166:169], v[214:217], v[72:75]
	v_mfma_f32_16x16x32_bf16 v[116:119], v[170:173], v[186:189], v[116:119]
	v_mfma_f32_16x16x32_bf16 v[108:111], v[178:181], v[186:189], v[108:111]
	v_mfma_f32_16x16x32_bf16 v[100:103], v[170:173], v[194:197], v[100:103]
	v_mfma_f32_16x16x32_bf16 v[92:95], v[178:181], v[194:197], v[92:95]
	v_mfma_f32_16x16x32_bf16 v[84:87], v[170:173], v[202:205], v[84:87]
	v_mfma_f32_16x16x32_bf16 v[76:79], v[178:181], v[202:205], v[76:79]
	v_mfma_f32_16x16x32_bf16 v[68:71], v[170:173], v[210:213], v[68:71]
	v_mfma_f32_16x16x32_bf16 v[64:67], v[178:181], v[210:213], v[64:67]
	v_mfma_f32_16x16x32_bf16 v[116:119], v[174:177], v[190:193], v[116:119]
	v_mfma_f32_16x16x32_bf16 v[108:111], v[182:185], v[190:193], v[108:111]
	v_mfma_f32_16x16x32_bf16 v[100:103], v[174:177], v[198:201], v[100:103]
	v_mfma_f32_16x16x32_bf16 v[92:95], v[182:185], v[198:201], v[92:95]
	v_mfma_f32_16x16x32_bf16 v[84:87], v[174:177], v[206:209], v[84:87]
	v_mfma_f32_16x16x32_bf16 v[76:79], v[182:185], v[206:209], v[76:79]
	v_mfma_f32_16x16x32_bf16 v[68:71], v[174:177], v[214:217], v[68:71]
	v_mfma_f32_16x16x32_bf16 v[64:67], v[182:185], v[214:217], v[64:67]
	s_barrier
	s_add_i32 s44, s70, s35
	v_lshl_add_u64 v[144:145], v[144:145], 0, s[8:9]
	s_mov_b32 m0, s44
	ds_read_b128 v[186:189], v152 offset:49152
	ds_read_b128 v[190:193], v152 offset:50176
	ds_read_b128 v[194:197], v152 offset:51200
	ds_read_b128 v[198:201], v152 offset:52224
	ds_read_b128 v[202:205], v152 offset:53248
	ds_read_b128 v[206:209], v152 offset:54272
	ds_read_b128 v[210:213], v152 offset:55296
	ds_read_b128 v[214:217], v152 offset:56320
	global_load_lds_dwordx4 v[144:145], off
	s_add_i32 m0, s44, 0x2000
	s_add_u32 s44, s48, 0xb0080
	v_lshl_add_u64 v[144:145], v[218:219], 0, s[8:9]
	s_addc_u32 s45, s49, 0
	s_add_i32 s48, s71, s35
	global_load_lds_dwordx4 v[144:145], off
	s_mov_b32 m0, s48
	s_nop 0
	global_load_lds_dwordx4 v130, s[44:45]
	s_add_i32 m0, s48, 0x2000
	s_nop 0
	global_load_lds_dwordx4 v134, s[44:45]
	v_lshl_add_u64 v[144:145], v[220:221], 0, s[8:9]
	s_mov_b32 m0, s55
	s_nop 0
	global_load_lds_dwordx4 v[144:145], off
	v_lshl_add_u64 v[144:145], v[222:223], 0, s[8:9]
	s_mov_b32 m0, s56
	s_nop 0
	global_load_lds_dwordx4 v[144:145], off
	s_waitcnt vmcnt(8)
	s_waitcnt lgkmcnt(0)
	s_barrier
	v_mfma_f32_16x16x32_bf16 v[60:63], v[154:157], v[186:189], v[60:63]
	v_mfma_f32_16x16x32_bf16 v[56:59], v[162:165], v[186:189], v[56:59]
	v_mfma_f32_16x16x32_bf16 v[48:51], v[154:157], v[194:197], v[48:51]
	v_mfma_f32_16x16x32_bf16 v[40:43], v[162:165], v[194:197], v[40:43]
	v_mfma_f32_16x16x32_bf16 v[32:35], v[154:157], v[202:205], v[32:35]
	v_mfma_f32_16x16x32_bf16 v[24:27], v[162:165], v[202:205], v[24:27]
	v_mfma_f32_16x16x32_bf16 v[16:19], v[154:157], v[210:213], v[16:19]
	v_mfma_f32_16x16x32_bf16 v[8:11], v[162:165], v[210:213], v[8:11]
	v_mfma_f32_16x16x32_bf16 v[60:63], v[158:161], v[190:193], v[60:63]
	v_mfma_f32_16x16x32_bf16 v[56:59], v[166:169], v[190:193], v[56:59]
	v_mfma_f32_16x16x32_bf16 v[48:51], v[158:161], v[198:201], v[48:51]
	v_mfma_f32_16x16x32_bf16 v[40:43], v[166:169], v[198:201], v[40:43]
	v_mfma_f32_16x16x32_bf16 v[32:35], v[158:161], v[206:209], v[32:35]
	v_mfma_f32_16x16x32_bf16 v[24:27], v[166:169], v[206:209], v[24:27]
	v_mfma_f32_16x16x32_bf16 v[16:19], v[158:161], v[214:217], v[16:19]
	v_mfma_f32_16x16x32_bf16 v[8:11], v[166:169], v[214:217], v[8:11]
	v_mfma_f32_16x16x32_bf16 v[52:55], v[170:173], v[186:189], v[52:55]
	v_mfma_f32_16x16x32_bf16 v[44:47], v[178:181], v[186:189], v[44:47]
	v_mfma_f32_16x16x32_bf16 v[36:39], v[170:173], v[194:197], v[36:39]
	v_mfma_f32_16x16x32_bf16 v[28:31], v[178:181], v[194:197], v[28:31]
	v_mfma_f32_16x16x32_bf16 v[20:23], v[170:173], v[202:205], v[20:23]
	v_mfma_f32_16x16x32_bf16 v[12:15], v[178:181], v[202:205], v[12:15]
	v_mfma_f32_16x16x32_bf16 v[4:7], v[170:173], v[210:213], v[4:7]
	v_mfma_f32_16x16x32_bf16 v[0:3], v[178:181], v[210:213], v[0:3]
	v_mfma_f32_16x16x32_bf16 v[52:55], v[174:177], v[190:193], v[52:55]
	v_mfma_f32_16x16x32_bf16 v[44:47], v[182:185], v[190:193], v[44:47]
	v_mfma_f32_16x16x32_bf16 v[36:39], v[174:177], v[198:201], v[36:39]
	v_mfma_f32_16x16x32_bf16 v[28:31], v[182:185], v[198:201], v[28:31]
	v_mfma_f32_16x16x32_bf16 v[20:23], v[174:177], v[206:209], v[20:23]
	v_mfma_f32_16x16x32_bf16 v[12:15], v[182:185], v[206:209], v[12:15]
	v_mfma_f32_16x16x32_bf16 v[4:7], v[174:177], v[214:217], v[4:7]
	v_mfma_f32_16x16x32_bf16 v[0:3], v[182:185], v[214:217], v[0:3]
	s_barrier
	s_add_i32 s69, s69, 2
	s_add_u32 s0, s0, 0x100
	s_addc_u32 s1, s1, 0
	s_cmp_gt_u32 s69, 41
	s_mov_b64 s[44:45], s[46:47]
	s_cbranch_scc0 .LBB0_2339
	s_and_b64 vcc, exec, s[10:11]
	s_cbranch_vccz .LBB0_2342
	s_barrier

.LBB0_2422:
	s_add_u32 s57, s50, s56
	s_addc_u32 s62, s51, 0
	s_add_u32 s60, s57, 0x100
	s_addc_u32 s61, s62, 0
	s_and_b64 s[58:59], s[54:55], exec
	s_cselect_b32 s59, s0, s61
	s_cselect_b32 s58, s1, s60
	s_add_u32 s56, s48, s56
	s_addc_u32 s60, s49, 0
	s_add_u32 s56, s56, 0x100
	s_addc_u32 s60, s60, 0
	s_and_b64 s[54:55], s[54:55], exec
	s_cselect_b32 s61, s17, s60
	s_cselect_b32 s60, s19, s56
	s_add_u32 s64, s57, 0x10080
	ds_read_b128 v[150:153], v146
	ds_read_b128 v[154:157], v146 offset:1024
	ds_read_b128 v[158:161], v146 offset:2048
	ds_read_b128 v[162:165], v146 offset:3072
	ds_read_b128 v[166:169], v147
	ds_read_b128 v[170:173], v147 offset:1024
	ds_read_b128 v[174:177], v147 offset:2048
	ds_read_b128 v[178:181], v147 offset:3072
	s_addc_u32 s65, s62, 0
	s_add_i32 s90, s72, s35
	s_add_i32 m0, s42, 0xc000
	s_add_i32 s91, s42, 0xe000
	s_add_i32 s87, s90, 0x2000
	s_add_u32 s62, s60, 0x10000
	s_addc_u32 s63, s61, 0
	s_add_i32 s89, s73, s35
	s_add_i32 s88, s89, 0x2000
	s_add_i32 s86, 0, 0x18000
	s_add_i32 s85, 0, 0x1c000
	s_add_u32 s56, s58, 0x10000
	s_addc_u32 s57, s59, 0
	s_add_i32 s84, s86, s35
	s_add_i32 s82, s84, 0x2000
	s_add_u32 s54, s60, 0x10080
	s_addc_u32 s55, s61, 0
	s_add_i32 s83, s85, s35
	s_add_i32 s79, s83, 0x2000
	ds_read_b128 v[182:185], v148
	ds_read_b128 v[186:189], v148 offset:1024
	ds_read_b128 v[190:193], v148 offset:2048
	ds_read_b128 v[194:197], v148 offset:3072
	ds_read_b128 v[198:201], v148 offset:4096
	ds_read_b128 v[202:205], v148 offset:5120
	ds_read_b128 v[206:209], v148 offset:6144
	ds_read_b128 v[210:213], v148 offset:7168
	global_load_lds_dwordx4 v128, s[64:65]
	s_mov_b32 m0, s91
	s_nop 0
	global_load_lds_dwordx4 v132, s[64:65]
	s_waitcnt vmcnt(8)
	s_waitcnt lgkmcnt(0)
	s_barrier
	v_mfma_f32_16x16x32_bf16 v[124:127], v[150:153], v[182:185], v[124:127]
	v_mfma_f32_16x16x32_bf16 v[120:123], v[158:161], v[182:185], v[120:123]
	v_mfma_f32_16x16x32_bf16 v[112:115], v[150:153], v[190:193], v[112:115]
	v_mfma_f32_16x16x32_bf16 v[104:107], v[158:161], v[190:193], v[104:107]
	v_mfma_f32_16x16x32_bf16 v[96:99], v[150:153], v[198:201], v[96:99]
	v_mfma_f32_16x16x32_bf16 v[88:91], v[158:161], v[198:201], v[88:91]
	v_mfma_f32_16x16x32_bf16 v[80:83], v[150:153], v[206:209], v[80:83]
	v_mfma_f32_16x16x32_bf16 v[72:75], v[158:161], v[206:209], v[72:75]
	v_mfma_f32_16x16x32_bf16 v[124:127], v[154:157], v[186:189], v[124:127]
	v_mfma_f32_16x16x32_bf16 v[120:123], v[162:165], v[186:189], v[120:123]
	v_mfma_f32_16x16x32_bf16 v[112:115], v[154:157], v[194:197], v[112:115]
	v_mfma_f32_16x16x32_bf16 v[104:107], v[162:165], v[194:197], v[104:107]
	v_mfma_f32_16x16x32_bf16 v[96:99], v[154:157], v[202:205], v[96:99]
	v_mfma_f32_16x16x32_bf16 v[88:91], v[162:165], v[202:205], v[88:91]
	v_mfma_f32_16x16x32_bf16 v[80:83], v[154:157], v[210:213], v[80:83]
	v_mfma_f32_16x16x32_bf16 v[72:75], v[162:165], v[210:213], v[72:75]
	v_mfma_f32_16x16x32_bf16 v[116:119], v[166:169], v[182:185], v[116:119]
	v_mfma_f32_16x16x32_bf16 v[108:111], v[174:177], v[182:185], v[108:111]
	v_mfma_f32_16x16x32_bf16 v[100:103], v[166:169], v[190:193], v[100:103]
	v_mfma_f32_16x16x32_bf16 v[92:95], v[174:177], v[190:193], v[92:95]
	v_mfma_f32_16x16x32_bf16 v[84:87], v[166:169], v[198:201], v[84:87]
	v_mfma_f32_16x16x32_bf16 v[76:79], v[174:177], v[198:201], v[76:79]
	v_mfma_f32_16x16x32_bf16 v[68:71], v[166:169], v[206:209], v[68:71]
	v_mfma_f32_16x16x32_bf16 v[64:67], v[174:177], v[206:209], v[64:67]
	v_mfma_f32_16x16x32_bf16 v[116:119], v[170:173], v[186:189], v[116:119]
	v_mfma_f32_16x16x32_bf16 v[108:111], v[178:181], v[186:189], v[108:111]
	v_mfma_f32_16x16x32_bf16 v[100:103], v[170:173], v[194:197], v[100:103]
	v_mfma_f32_16x16x32_bf16 v[92:95], v[178:181], v[194:197], v[92:95]
	v_mfma_f32_16x16x32_bf16 v[84:87], v[170:173], v[202:205], v[84:87]
	v_mfma_f32_16x16x32_bf16 v[76:79], v[178:181], v[202:205], v[76:79]
	v_mfma_f32_16x16x32_bf16 v[68:71], v[170:173], v[210:213], v[68:71]
	v_mfma_f32_16x16x32_bf16 v[64:67], v[178:181], v[210:213], v[64:67]
	s_barrier
	s_mov_b32 m0, s90
	v_lshl_add_u64 v[140:141], s[60:61], 0, v[130:131]
	ds_read_b128 v[182:185], v148 offset:16384
	ds_read_b128 v[186:189], v148 offset:17408
	ds_read_b128 v[190:193], v148 offset:18432
	ds_read_b128 v[194:197], v148 offset:19456
	ds_read_b128 v[198:201], v148 offset:20480
	ds_read_b128 v[202:205], v148 offset:21504
	ds_read_b128 v[206:209], v148 offset:22528
	ds_read_b128 v[210:213], v148 offset:23552
	global_load_lds_dwordx4 v[140:141], off
	v_lshl_add_u64 v[214:215], s[60:61], 0, v[134:135]
	s_mov_b32 m0, s87
	s_nop 0
	global_load_lds_dwordx4 v[214:215], off
	s_mov_b32 m0, s89
	v_lshl_add_u64 v[218:219], s[58:59], 0, v[132:133]
	global_load_lds_dwordx4 v130, s[62:63]
	s_mov_b32 m0, s88
	s_nop 0
	global_load_lds_dwordx4 v134, s[62:63]
	v_lshl_add_u64 v[216:217], s[58:59], 0, v[128:129]
	s_mov_b32 m0, s42
	s_nop 0
	global_load_lds_dwordx4 v[216:217], off
	s_mov_b32 m0, s43
	s_nop 0
	global_load_lds_dwordx4 v[218:219], off
	s_waitcnt vmcnt(8)
	s_waitcnt lgkmcnt(0)
	s_barrier
	v_mfma_f32_16x16x32_bf16 v[60:63], v[150:153], v[182:185], v[60:63]
	v_mfma_f32_16x16x32_bf16 v[56:59], v[158:161], v[182:185], v[56:59]
	v_mfma_f32_16x16x32_bf16 v[48:51], v[150:153], v[190:193], v[48:51]
	v_mfma_f32_16x16x32_bf16 v[40:43], v[158:161], v[190:193], v[40:43]
	v_mfma_f32_16x16x32_bf16 v[32:35], v[150:153], v[198:201], v[32:35]
	v_mfma_f32_16x16x32_bf16 v[24:27], v[158:161], v[198:201], v[24:27]
	v_mfma_f32_16x16x32_bf16 v[16:19], v[150:153], v[206:209], v[16:19]
	v_mfma_f32_16x16x32_bf16 v[8:11], v[158:161], v[206:209], v[8:11]
	v_mfma_f32_16x16x32_bf16 v[60:63], v[154:157], v[186:189], v[60:63]
	v_mfma_f32_16x16x32_bf16 v[56:59], v[162:165], v[186:189], v[56:59]
	v_mfma_f32_16x16x32_bf16 v[48:51], v[154:157], v[194:197], v[48:51]
	v_mfma_f32_16x16x32_bf16 v[40:43], v[162:165], v[194:197], v[40:43]
	v_mfma_f32_16x16x32_bf16 v[32:35], v[154:157], v[202:205], v[32:35]
	v_mfma_f32_16x16x32_bf16 v[24:27], v[162:165], v[202:205], v[24:27]
	v_mfma_f32_16x16x32_bf16 v[16:19], v[154:157], v[210:213], v[16:19]
	v_mfma_f32_16x16x32_bf16 v[8:11], v[162:165], v[210:213], v[8:11]
	v_mfma_f32_16x16x32_bf16 v[52:55], v[166:169], v[182:185], v[52:55]
	v_mfma_f32_16x16x32_bf16 v[44:47], v[174:177], v[182:185], v[44:47]
	v_mfma_f32_16x16x32_bf16 v[36:39], v[166:169], v[190:193], v[36:39]
	v_mfma_f32_16x16x32_bf16 v[28:31], v[174:177], v[190:193], v[28:31]
	v_mfma_f32_16x16x32_bf16 v[20:23], v[166:169], v[198:201], v[20:23]
	v_mfma_f32_16x16x32_bf16 v[12:15], v[174:177], v[198:201], v[12:15]
	v_mfma_f32_16x16x32_bf16 v[4:7], v[166:169], v[206:209], v[4:7]
	v_mfma_f32_16x16x32_bf16 v[0:3], v[174:177], v[206:209], v[0:3]
	v_mfma_f32_16x16x32_bf16 v[52:55], v[170:173], v[186:189], v[52:55]
	v_mfma_f32_16x16x32_bf16 v[44:47], v[178:181], v[186:189], v[44:47]
	v_mfma_f32_16x16x32_bf16 v[36:39], v[170:173], v[194:197], v[36:39]
	v_mfma_f32_16x16x32_bf16 v[28:31], v[178:181], v[194:197], v[28:31]
	v_mfma_f32_16x16x32_bf16 v[20:23], v[170:173], v[202:205], v[20:23]
	v_mfma_f32_16x16x32_bf16 v[12:15], v[178:181], v[202:205], v[12:15]
	v_mfma_f32_16x16x32_bf16 v[4:7], v[170:173], v[210:213], v[4:7]
	v_mfma_f32_16x16x32_bf16 v[0:3], v[178:181], v[210:213], v[0:3]
	s_barrier
	v_add_u32_e32 v149, s86, v144
	ds_read_b128 v[150:153], v149
	ds_read_b128 v[154:157], v149 offset:1024
	ds_read_b128 v[158:161], v149 offset:2048
	ds_read_b128 v[162:165], v149 offset:3072
	v_add_u32_e32 v149, s85, v144
	ds_read_b128 v[166:169], v149
	ds_read_b128 v[170:173], v149 offset:1024
	ds_read_b128 v[174:177], v149 offset:2048
	ds_read_b128 v[178:181], v149 offset:3072
	s_mov_b32 m0, s47
	ds_read_b128 v[182:185], v148 offset:32768
	ds_read_b128 v[186:189], v148 offset:33792
	ds_read_b128 v[190:193], v148 offset:34816
	ds_read_b128 v[194:197], v148 offset:35840
	ds_read_b128 v[198:201], v148 offset:36864
	ds_read_b128 v[202:205], v148 offset:37888
	ds_read_b128 v[206:209], v148 offset:38912
	ds_read_b128 v[210:213], v148 offset:39936
	global_load_lds_dwordx4 v128, s[56:57]
	s_mov_b32 m0, s66
	s_nop 0
	global_load_lds_dwordx4 v132, s[56:57]
	s_waitcnt vmcnt(8)
	s_waitcnt lgkmcnt(0)
	s_barrier
	v_mfma_f32_16x16x32_bf16 v[124:127], v[150:153], v[182:185], v[124:127]
	v_mfma_f32_16x16x32_bf16 v[120:123], v[158:161], v[182:185], v[120:123]
	v_mfma_f32_16x16x32_bf16 v[112:115], v[150:153], v[190:193], v[112:115]
	v_mfma_f32_16x16x32_bf16 v[104:107], v[158:161], v[190:193], v[104:107]
	v_mfma_f32_16x16x32_bf16 v[96:99], v[150:153], v[198:201], v[96:99]
	v_mfma_f32_16x16x32_bf16 v[88:91], v[158:161], v[198:201], v[88:91]
	v_mfma_f32_16x16x32_bf16 v[80:83], v[150:153], v[206:209], v[80:83]
	v_mfma_f32_16x16x32_bf16 v[72:75], v[158:161], v[206:209], v[72:75]
	v_mfma_f32_16x16x32_bf16 v[124:127], v[154:157], v[186:189], v[124:127]
	v_mfma_f32_16x16x32_bf16 v[120:123], v[162:165], v[186:189], v[120:123]
	v_mfma_f32_16x16x32_bf16 v[112:115], v[154:157], v[194:197], v[112:115]
	v_mfma_f32_16x16x32_bf16 v[104:107], v[162:165], v[194:197], v[104:107]
	v_mfma_f32_16x16x32_bf16 v[96:99], v[154:157], v[202:205], v[96:99]
	v_mfma_f32_16x16x32_bf16 v[88:91], v[162:165], v[202:205], v[88:91]
	v_mfma_f32_16x16x32_bf16 v[80:83], v[154:157], v[210:213], v[80:83]
	v_mfma_f32_16x16x32_bf16 v[72:75], v[162:165], v[210:213], v[72:75]
	v_mfma_f32_16x16x32_bf16 v[116:119], v[166:169], v[182:185], v[116:119]
	v_mfma_f32_16x16x32_bf16 v[108:111], v[174:177], v[182:185], v[108:111]
	v_mfma_f32_16x16x32_bf16 v[100:103], v[166:169], v[190:193], v[100:103]
	v_mfma_f32_16x16x32_bf16 v[92:95], v[174:177], v[190:193], v[92:95]
	v_mfma_f32_16x16x32_bf16 v[84:87], v[166:169], v[198:201], v[84:87]
	v_mfma_f32_16x16x32_bf16 v[76:79], v[174:177], v[198:201], v[76:79]
	v_mfma_f32_16x16x32_bf16 v[68:71], v[166:169], v[206:209], v[68:71]
	v_mfma_f32_16x16x32_bf16 v[64:67], v[174:177], v[206:209], v[64:67]
	v_mfma_f32_16x16x32_bf16 v[116:119], v[170:173], v[186:189], v[116:119]
	v_mfma_f32_16x16x32_bf16 v[108:111], v[178:181], v[186:189], v[108:111]
	v_mfma_f32_16x16x32_bf16 v[100:103], v[170:173], v[194:197], v[100:103]
	v_mfma_f32_16x16x32_bf16 v[92:95], v[178:181], v[194:197], v[92:95]
	v_mfma_f32_16x16x32_bf16 v[84:87], v[170:173], v[202:205], v[84:87]
	v_mfma_f32_16x16x32_bf16 v[76:79], v[178:181], v[202:205], v[76:79]
	v_mfma_f32_16x16x32_bf16 v[68:71], v[170:173], v[210:213], v[68:71]
	v_mfma_f32_16x16x32_bf16 v[64:67], v[178:181], v[210:213], v[64:67]
	s_barrier
	s_mov_b32 m0, s84
	v_lshl_add_u64 v[140:141], v[140:141], 0, s[6:7]
	ds_read_b128 v[182:185], v148 offset:49152
	ds_read_b128 v[186:189], v148 offset:50176
	ds_read_b128 v[190:193], v148 offset:51200
	ds_read_b128 v[194:197], v148 offset:52224
	ds_read_b128 v[198:201], v148 offset:53248
	ds_read_b128 v[202:205], v148 offset:54272
	ds_read_b128 v[206:209], v148 offset:55296
	ds_read_b128 v[210:213], v148 offset:56320
	global_load_lds_dwordx4 v[140:141], off
	v_lshl_add_u64 v[140:141], v[214:215], 0, s[6:7]
	s_mov_b32 m0, s82
	s_nop 0
	global_load_lds_dwordx4 v[140:141], off
	s_mov_b32 m0, s83
	s_nop 0
	global_load_lds_dwordx4 v130, s[54:55]
	s_mov_b32 m0, s79
	s_nop 0
	global_load_lds_dwordx4 v134, s[54:55]
	v_lshl_add_u64 v[140:141], v[216:217], 0, s[6:7]
	s_mov_b32 m0, s68
	s_nop 0
	global_load_lds_dwordx4 v[140:141], off
	v_lshl_add_u64 v[140:141], v[218:219], 0, s[6:7]
	s_mov_b32 m0, s69
	s_nop 0
	global_load_lds_dwordx4 v[140:141], off
	s_waitcnt vmcnt(8)
	s_waitcnt lgkmcnt(0)
	s_barrier
	v_mfma_f32_16x16x32_bf16 v[60:63], v[150:153], v[182:185], v[60:63]
	v_mfma_f32_16x16x32_bf16 v[56:59], v[158:161], v[182:185], v[56:59]
	v_mfma_f32_16x16x32_bf16 v[48:51], v[150:153], v[190:193], v[48:51]
	v_mfma_f32_16x16x32_bf16 v[40:43], v[158:161], v[190:193], v[40:43]
	v_mfma_f32_16x16x32_bf16 v[32:35], v[150:153], v[198:201], v[32:35]
	v_mfma_f32_16x16x32_bf16 v[24:27], v[158:161], v[198:201], v[24:27]
	v_mfma_f32_16x16x32_bf16 v[16:19], v[150:153], v[206:209], v[16:19]
	v_mfma_f32_16x16x32_bf16 v[8:11], v[158:161], v[206:209], v[8:11]
	v_mfma_f32_16x16x32_bf16 v[60:63], v[154:157], v[186:189], v[60:63]
	v_mfma_f32_16x16x32_bf16 v[56:59], v[162:165], v[186:189], v[56:59]
	v_mfma_f32_16x16x32_bf16 v[48:51], v[154:157], v[194:197], v[48:51]
	v_mfma_f32_16x16x32_bf16 v[40:43], v[162:165], v[194:197], v[40:43]
	v_mfma_f32_16x16x32_bf16 v[32:35], v[154:157], v[202:205], v[32:35]
	v_mfma_f32_16x16x32_bf16 v[24:27], v[162:165], v[202:205], v[24:27]
	v_mfma_f32_16x16x32_bf16 v[16:19], v[154:157], v[210:213], v[16:19]
	v_mfma_f32_16x16x32_bf16 v[8:11], v[162:165], v[210:213], v[8:11]
	v_mfma_f32_16x16x32_bf16 v[52:55], v[166:169], v[182:185], v[52:55]
	v_mfma_f32_16x16x32_bf16 v[44:47], v[174:177], v[182:185], v[44:47]
	v_mfma_f32_16x16x32_bf16 v[36:39], v[166:169], v[190:193], v[36:39]
	v_mfma_f32_16x16x32_bf16 v[28:31], v[174:177], v[190:193], v[28:31]
	v_mfma_f32_16x16x32_bf16 v[20:23], v[166:169], v[198:201], v[20:23]
	v_mfma_f32_16x16x32_bf16 v[12:15], v[174:177], v[198:201], v[12:15]
	v_mfma_f32_16x16x32_bf16 v[4:7], v[166:169], v[206:209], v[4:7]
	v_mfma_f32_16x16x32_bf16 v[0:3], v[174:177], v[206:209], v[0:3]
	v_mfma_f32_16x16x32_bf16 v[52:55], v[170:173], v[186:189], v[52:55]
	v_mfma_f32_16x16x32_bf16 v[44:47], v[178:181], v[186:189], v[44:47]
	v_mfma_f32_16x16x32_bf16 v[36:39], v[170:173], v[194:197], v[36:39]
	v_mfma_f32_16x16x32_bf16 v[28:31], v[178:181], v[194:197], v[28:31]
	v_mfma_f32_16x16x32_bf16 v[20:23], v[170:173], v[202:205], v[20:23]
	v_mfma_f32_16x16x32_bf16 v[12:15], v[178:181], v[202:205], v[12:15]
	v_mfma_f32_16x16x32_bf16 v[4:7], v[170:173], v[210:213], v[4:7]
	v_mfma_f32_16x16x32_bf16 v[0:3], v[178:181], v[210:213], v[0:3]
	s_barrier
	s_movk_i32 s56, 0x100
	s_andn2_b64 vcc, exec, s[52:53]
	s_mov_b64 s[54:55], -1
	s_mov_b64 s[52:53], 0
	s_cbranch_vccz .LBB0_2422
	s_and_b64 vcc, exec, s[8:9]
	s_cbranch_vccz .LBB0_2425
	s_barrier

.LBB0_2498:
	ds_read_b128 v[144:147], v154
	ds_read_b128 v[158:161], v154 offset:1024
	ds_read_b128 v[162:165], v154 offset:2048
	ds_read_b128 v[166:169], v154 offset:3072
	ds_read_b128 v[170:173], v155
	ds_read_b128 v[174:177], v155 offset:1024
	ds_read_b128 v[178:181], v155 offset:2048
	ds_read_b128 v[182:185], v155 offset:3072
	s_add_u32 s52, s50, 0xfffc0080
	s_addc_u32 s53, s51, -1
	s_cmp_eq_u32 s65, 12
	s_cselect_b32 s55, s0, s53
	s_cselect_b32 s54, s1, s52
	s_cselect_b32 s53, s19, s64
	s_cselect_b32 s52, s39, s63
	s_add_i32 m0, s34, 0xc000
	ds_read_b128 v[186:189], v156
	ds_read_b128 v[190:193], v156 offset:1024
	ds_read_b128 v[194:197], v156 offset:2048
	ds_read_b128 v[198:201], v156 offset:3072
	ds_read_b128 v[202:205], v156 offset:4096
	ds_read_b128 v[206:209], v156 offset:5120
	ds_read_b128 v[210:213], v156 offset:6144
	ds_read_b128 v[214:217], v156 offset:7168
	global_load_lds_dwordx4 v136, s[50:51]
	s_add_i32 m0, s34, 0xe000
	s_nop 0
	global_load_lds_dwordx4 v138, s[50:51]
	s_waitcnt vmcnt(8)
	s_waitcnt lgkmcnt(0)
	s_barrier
	v_mfma_f32_16x16x32_bf16 v[124:127], v[144:147], v[186:189], v[124:127]
	v_mfma_f32_16x16x32_bf16 v[120:123], v[162:165], v[186:189], v[120:123]
	v_mfma_f32_16x16x32_bf16 v[108:111], v[144:147], v[194:197], v[108:111]
	v_mfma_f32_16x16x32_bf16 v[104:107], v[162:165], v[194:197], v[104:107]
	v_mfma_f32_16x16x32_bf16 v[92:95], v[144:147], v[202:205], v[92:95]
	v_mfma_f32_16x16x32_bf16 v[88:91], v[162:165], v[202:205], v[88:91]
	v_mfma_f32_16x16x32_bf16 v[76:79], v[144:147], v[210:213], v[76:79]
	v_mfma_f32_16x16x32_bf16 v[72:75], v[162:165], v[210:213], v[72:75]
	v_mfma_f32_16x16x32_bf16 v[124:127], v[158:161], v[190:193], v[124:127]
	v_mfma_f32_16x16x32_bf16 v[120:123], v[166:169], v[190:193], v[120:123]
	v_mfma_f32_16x16x32_bf16 v[108:111], v[158:161], v[198:201], v[108:111]
	v_mfma_f32_16x16x32_bf16 v[104:107], v[166:169], v[198:201], v[104:107]
	v_mfma_f32_16x16x32_bf16 v[92:95], v[158:161], v[206:209], v[92:95]
	v_mfma_f32_16x16x32_bf16 v[88:91], v[166:169], v[206:209], v[88:91]
	v_mfma_f32_16x16x32_bf16 v[76:79], v[158:161], v[214:217], v[76:79]
	v_mfma_f32_16x16x32_bf16 v[72:75], v[166:169], v[214:217], v[72:75]
	v_mfma_f32_16x16x32_bf16 v[116:119], v[170:173], v[186:189], v[116:119]
	v_mfma_f32_16x16x32_bf16 v[112:115], v[178:181], v[186:189], v[112:115]
	v_mfma_f32_16x16x32_bf16 v[100:103], v[170:173], v[194:197], v[100:103]
	v_mfma_f32_16x16x32_bf16 v[96:99], v[178:181], v[194:197], v[96:99]
	v_mfma_f32_16x16x32_bf16 v[84:87], v[170:173], v[202:205], v[84:87]
	v_mfma_f32_16x16x32_bf16 v[80:83], v[178:181], v[202:205], v[80:83]
	v_mfma_f32_16x16x32_bf16 v[68:71], v[170:173], v[210:213], v[68:71]
	v_mfma_f32_16x16x32_bf16 v[64:67], v[178:181], v[210:213], v[64:67]
	v_mfma_f32_16x16x32_bf16 v[116:119], v[174:177], v[190:193], v[116:119]
	v_mfma_f32_16x16x32_bf16 v[112:115], v[182:185], v[190:193], v[112:115]
	v_mfma_f32_16x16x32_bf16 v[100:103], v[174:177], v[198:201], v[100:103]
	v_mfma_f32_16x16x32_bf16 v[96:99], v[182:185], v[198:201], v[96:99]
	v_mfma_f32_16x16x32_bf16 v[84:87], v[174:177], v[206:209], v[84:87]
	v_mfma_f32_16x16x32_bf16 v[80:83], v[182:185], v[206:209], v[80:83]
	v_mfma_f32_16x16x32_bf16 v[68:71], v[174:177], v[214:217], v[68:71]
	v_mfma_f32_16x16x32_bf16 v[64:67], v[182:185], v[214:217], v[64:67]
	s_barrier
	s_add_i32 s66, s60, s23
	v_lshl_add_u64 v[148:149], s[52:53], 0, v[130:131]
	s_mov_b32 m0, s66
	ds_read_b128 v[186:189], v156 offset:16384
	ds_read_b128 v[190:193], v156 offset:17408
	ds_read_b128 v[194:197], v156 offset:18432
	ds_read_b128 v[198:201], v156 offset:19456
	ds_read_b128 v[202:205], v156 offset:20480
	ds_read_b128 v[206:209], v156 offset:21504
	ds_read_b128 v[210:213], v156 offset:22528
	ds_read_b128 v[214:217], v156 offset:23552
	global_load_lds_dwordx4 v[148:149], off
	s_add_i32 m0, s66, 0x2000
	s_add_u32 s66, s52, 0x40000
	v_lshl_add_u64 v[218:219], s[52:53], 0, v[134:135]
	s_addc_u32 s67, s53, 0
	s_add_i32 s68, s61, s23
	global_load_lds_dwordx4 v[218:219], off
	s_mov_b32 m0, s68
	v_lshl_add_u64 v[222:223], s[54:55], 0, v[132:133]
	global_load_lds_dwordx4 v130, s[66:67]
	s_add_i32 m0, s68, 0x2000
	s_nop 0
	global_load_lds_dwordx4 v134, s[66:67]
	v_lshl_add_u64 v[220:221], s[54:55], 0, v[128:129]
	s_mov_b32 m0, s34
	s_nop 0
	global_load_lds_dwordx4 v[220:221], off
	s_mov_b32 m0, s35
	s_nop 0
	global_load_lds_dwordx4 v[222:223], off
	s_waitcnt vmcnt(8)
	s_waitcnt lgkmcnt(0)
	s_barrier
	v_mfma_f32_16x16x32_bf16 v[60:63], v[144:147], v[186:189], v[60:63]
	v_mfma_f32_16x16x32_bf16 v[56:59], v[162:165], v[186:189], v[56:59]
	v_mfma_f32_16x16x32_bf16 v[44:47], v[144:147], v[194:197], v[44:47]
	v_mfma_f32_16x16x32_bf16 v[40:43], v[162:165], v[194:197], v[40:43]
	v_mfma_f32_16x16x32_bf16 v[28:31], v[144:147], v[202:205], v[28:31]
	v_mfma_f32_16x16x32_bf16 v[24:27], v[162:165], v[202:205], v[24:27]
	v_mfma_f32_16x16x32_bf16 v[12:15], v[144:147], v[210:213], v[12:15]
	v_mfma_f32_16x16x32_bf16 v[8:11], v[162:165], v[210:213], v[8:11]
	v_mfma_f32_16x16x32_bf16 v[60:63], v[158:161], v[190:193], v[60:63]
	v_mfma_f32_16x16x32_bf16 v[56:59], v[166:169], v[190:193], v[56:59]
	v_mfma_f32_16x16x32_bf16 v[44:47], v[158:161], v[198:201], v[44:47]
	v_mfma_f32_16x16x32_bf16 v[40:43], v[166:169], v[198:201], v[40:43]
	v_mfma_f32_16x16x32_bf16 v[28:31], v[158:161], v[206:209], v[28:31]
	v_mfma_f32_16x16x32_bf16 v[24:27], v[166:169], v[206:209], v[24:27]
	v_mfma_f32_16x16x32_bf16 v[12:15], v[158:161], v[214:217], v[12:15]
	v_mfma_f32_16x16x32_bf16 v[8:11], v[166:169], v[214:217], v[8:11]
	v_mfma_f32_16x16x32_bf16 v[52:55], v[170:173], v[186:189], v[52:55]
	v_mfma_f32_16x16x32_bf16 v[48:51], v[178:181], v[186:189], v[48:51]
	v_mfma_f32_16x16x32_bf16 v[36:39], v[170:173], v[194:197], v[36:39]
	v_mfma_f32_16x16x32_bf16 v[32:35], v[178:181], v[194:197], v[32:35]
	v_mfma_f32_16x16x32_bf16 v[20:23], v[170:173], v[202:205], v[20:23]
	v_mfma_f32_16x16x32_bf16 v[16:19], v[178:181], v[202:205], v[16:19]
	v_mfma_f32_16x16x32_bf16 v[4:7], v[170:173], v[210:213], v[4:7]
	v_mfma_f32_16x16x32_bf16 v[0:3], v[178:181], v[210:213], v[0:3]
	v_mfma_f32_16x16x32_bf16 v[52:55], v[174:177], v[190:193], v[52:55]
	v_mfma_f32_16x16x32_bf16 v[48:51], v[182:185], v[190:193], v[48:51]
	v_mfma_f32_16x16x32_bf16 v[36:39], v[174:177], v[198:201], v[36:39]
	v_mfma_f32_16x16x32_bf16 v[32:35], v[182:185], v[198:201], v[32:35]
	v_mfma_f32_16x16x32_bf16 v[20:23], v[174:177], v[206:209], v[20:23]
	v_mfma_f32_16x16x32_bf16 v[16:19], v[182:185], v[206:209], v[16:19]
	v_mfma_f32_16x16x32_bf16 v[4:7], v[174:177], v[214:217], v[4:7]
	v_mfma_f32_16x16x32_bf16 v[0:3], v[182:185], v[214:217], v[0:3]
	s_barrier
	s_add_i32 s66, 0, 0x18000
	v_add_u32_e32 v157, s66, v152
	s_add_i32 s67, 0, 0x1c000
	ds_read_b128 v[144:147], v157
	ds_read_b128 v[158:161], v157 offset:1024
	ds_read_b128 v[162:165], v157 offset:2048
	ds_read_b128 v[166:169], v157 offset:3072
	v_add_u32_e32 v157, s67, v152
	ds_read_b128 v[170:173], v157
	ds_read_b128 v[174:177], v157 offset:1024
	ds_read_b128 v[178:181], v157 offset:2048
	ds_read_b128 v[182:185], v157 offset:3072
	s_add_u32 s54, s54, 0x40000
	s_addc_u32 s55, s55, 0
	s_mov_b32 m0, s42
	ds_read_b128 v[186:189], v156 offset:32768
	ds_read_b128 v[190:193], v156 offset:33792
	ds_read_b128 v[194:197], v156 offset:34816
	ds_read_b128 v[198:201], v156 offset:35840
	ds_read_b128 v[202:205], v156 offset:36864
	ds_read_b128 v[206:209], v156 offset:37888
	ds_read_b128 v[210:213], v156 offset:38912
	ds_read_b128 v[214:217], v156 offset:39936
	global_load_lds_dwordx4 v128, s[54:55]
	s_mov_b32 m0, s43
	s_nop 0
	global_load_lds_dwordx4 v132, s[54:55]
	s_waitcnt vmcnt(8)
	s_waitcnt lgkmcnt(0)
	s_barrier
	v_mfma_f32_16x16x32_bf16 v[124:127], v[144:147], v[186:189], v[124:127]
	v_mfma_f32_16x16x32_bf16 v[120:123], v[162:165], v[186:189], v[120:123]
	v_mfma_f32_16x16x32_bf16 v[108:111], v[144:147], v[194:197], v[108:111]
	v_mfma_f32_16x16x32_bf16 v[104:107], v[162:165], v[194:197], v[104:107]
	v_mfma_f32_16x16x32_bf16 v[92:95], v[144:147], v[202:205], v[92:95]
	v_mfma_f32_16x16x32_bf16 v[88:91], v[162:165], v[202:205], v[88:91]
	v_mfma_f32_16x16x32_bf16 v[76:79], v[144:147], v[210:213], v[76:79]
	v_mfma_f32_16x16x32_bf16 v[72:75], v[162:165], v[210:213], v[72:75]
	v_mfma_f32_16x16x32_bf16 v[124:127], v[158:161], v[190:193], v[124:127]
	v_mfma_f32_16x16x32_bf16 v[120:123], v[166:169], v[190:193], v[120:123]
	v_mfma_f32_16x16x32_bf16 v[108:111], v[158:161], v[198:201], v[108:111]
	v_mfma_f32_16x16x32_bf16 v[104:107], v[166:169], v[198:201], v[104:107]
	v_mfma_f32_16x16x32_bf16 v[92:95], v[158:161], v[206:209], v[92:95]
	v_mfma_f32_16x16x32_bf16 v[88:91], v[166:169], v[206:209], v[88:91]
	v_mfma_f32_16x16x32_bf16 v[76:79], v[158:161], v[214:217], v[76:79]
	v_mfma_f32_16x16x32_bf16 v[72:75], v[166:169], v[214:217], v[72:75]
	v_mfma_f32_16x16x32_bf16 v[116:119], v[170:173], v[186:189], v[116:119]
	v_mfma_f32_16x16x32_bf16 v[112:115], v[178:181], v[186:189], v[112:115]
	v_mfma_f32_16x16x32_bf16 v[100:103], v[170:173], v[194:197], v[100:103]
	v_mfma_f32_16x16x32_bf16 v[96:99], v[178:181], v[194:197], v[96:99]
	v_mfma_f32_16x16x32_bf16 v[84:87], v[170:173], v[202:205], v[84:87]
	v_mfma_f32_16x16x32_bf16 v[80:83], v[178:181], v[202:205], v[80:83]
	v_mfma_f32_16x16x32_bf16 v[68:71], v[170:173], v[210:213], v[68:71]
	v_mfma_f32_16x16x32_bf16 v[64:67], v[178:181], v[210:213], v[64:67]
	v_mfma_f32_16x16x32_bf16 v[116:119], v[174:177], v[190:193], v[116:119]
	v_mfma_f32_16x16x32_bf16 v[112:115], v[182:185], v[190:193], v[112:115]
	v_mfma_f32_16x16x32_bf16 v[100:103], v[174:177], v[198:201], v[100:103]
	v_mfma_f32_16x16x32_bf16 v[96:99], v[182:185], v[198:201], v[96:99]
	v_mfma_f32_16x16x32_bf16 v[84:87], v[174:177], v[206:209], v[84:87]
	v_mfma_f32_16x16x32_bf16 v[80:83], v[182:185], v[206:209], v[80:83]
	v_mfma_f32_16x16x32_bf16 v[68:71], v[174:177], v[214:217], v[68:71]
	v_mfma_f32_16x16x32_bf16 v[64:67], v[182:185], v[214:217], v[64:67]
	s_barrier
	s_add_i32 s54, s66, s23
	v_lshl_add_u64 v[148:149], v[148:149], 0, s[6:7]
	s_mov_b32 m0, s54
	ds_read_b128 v[186:189], v156 offset:49152
	ds_read_b128 v[190:193], v156 offset:50176
	ds_read_b128 v[194:197], v156 offset:51200
	ds_read_b128 v[198:201], v156 offset:52224
	ds_read_b128 v[202:205], v156 offset:53248
	ds_read_b128 v[206:209], v156 offset:54272
	ds_read_b128 v[210:213], v156 offset:55296
	ds_read_b128 v[214:217], v156 offset:56320
	global_load_lds_dwordx4 v[148:149], off
	s_add_i32 m0, s54, 0x2000
	s_add_u32 s52, s52, 0x40080
	v_lshl_add_u64 v[148:149], v[218:219], 0, s[6:7]
	s_addc_u32 s53, s53, 0
	s_add_i32 s54, s67, s23
	global_load_lds_dwordx4 v[148:149], off
	s_mov_b32 m0, s54
	s_nop 0
	global_load_lds_dwordx4 v130, s[52:53]
	s_add_i32 m0, s54, 0x2000
	s_nop 0
	global_load_lds_dwordx4 v134, s[52:53]
	v_lshl_add_u64 v[148:149], v[220:221], 0, s[6:7]
	s_mov_b32 m0, s56
	s_nop 0
	global_load_lds_dwordx4 v[148:149], off
	v_lshl_add_u64 v[148:149], v[222:223], 0, s[6:7]
	s_mov_b32 m0, s57
	s_nop 0
	global_load_lds_dwordx4 v[148:149], off
	s_waitcnt vmcnt(8)
	s_waitcnt lgkmcnt(0)
	s_barrier
	v_mfma_f32_16x16x32_bf16 v[60:63], v[144:147], v[186:189], v[60:63]
	v_mfma_f32_16x16x32_bf16 v[56:59], v[162:165], v[186:189], v[56:59]
	v_mfma_f32_16x16x32_bf16 v[44:47], v[144:147], v[194:197], v[44:47]
	v_mfma_f32_16x16x32_bf16 v[40:43], v[162:165], v[194:197], v[40:43]
	v_mfma_f32_16x16x32_bf16 v[28:31], v[144:147], v[202:205], v[28:31]
	v_mfma_f32_16x16x32_bf16 v[24:27], v[162:165], v[202:205], v[24:27]
	v_mfma_f32_16x16x32_bf16 v[12:15], v[144:147], v[210:213], v[12:15]
	v_mfma_f32_16x16x32_bf16 v[8:11], v[162:165], v[210:213], v[8:11]
	v_mfma_f32_16x16x32_bf16 v[60:63], v[158:161], v[190:193], v[60:63]
	v_mfma_f32_16x16x32_bf16 v[56:59], v[166:169], v[190:193], v[56:59]
	v_mfma_f32_16x16x32_bf16 v[44:47], v[158:161], v[198:201], v[44:47]
	v_mfma_f32_16x16x32_bf16 v[40:43], v[166:169], v[198:201], v[40:43]
	v_mfma_f32_16x16x32_bf16 v[28:31], v[158:161], v[206:209], v[28:31]
	v_mfma_f32_16x16x32_bf16 v[24:27], v[166:169], v[206:209], v[24:27]
	v_mfma_f32_16x16x32_bf16 v[12:15], v[158:161], v[214:217], v[12:15]
	v_mfma_f32_16x16x32_bf16 v[8:11], v[166:169], v[214:217], v[8:11]
	v_mfma_f32_16x16x32_bf16 v[52:55], v[170:173], v[186:189], v[52:55]
	v_mfma_f32_16x16x32_bf16 v[48:51], v[178:181], v[186:189], v[48:51]
	v_mfma_f32_16x16x32_bf16 v[36:39], v[170:173], v[194:197], v[36:39]
	v_mfma_f32_16x16x32_bf16 v[32:35], v[178:181], v[194:197], v[32:35]
	v_mfma_f32_16x16x32_bf16 v[20:23], v[170:173], v[202:205], v[20:23]
	v_mfma_f32_16x16x32_bf16 v[16:19], v[178:181], v[202:205], v[16:19]
	v_mfma_f32_16x16x32_bf16 v[4:7], v[170:173], v[210:213], v[4:7]
	v_mfma_f32_16x16x32_bf16 v[0:3], v[178:181], v[210:213], v[0:3]
	v_mfma_f32_16x16x32_bf16 v[52:55], v[174:177], v[190:193], v[52:55]
	v_mfma_f32_16x16x32_bf16 v[48:51], v[182:185], v[190:193], v[48:51]
	v_mfma_f32_16x16x32_bf16 v[36:39], v[174:177], v[198:201], v[36:39]
	v_mfma_f32_16x16x32_bf16 v[32:35], v[182:185], v[198:201], v[32:35]
	v_mfma_f32_16x16x32_bf16 v[20:23], v[174:177], v[206:209], v[20:23]
	v_mfma_f32_16x16x32_bf16 v[16:19], v[182:185], v[206:209], v[16:19]
	v_mfma_f32_16x16x32_bf16 v[4:7], v[174:177], v[214:217], v[4:7]
	v_mfma_f32_16x16x32_bf16 v[0:3], v[182:185], v[214:217], v[0:3]
	s_barrier
	s_add_i32 s65, s65, 2
	s_add_u32 s50, s50, 0x100
	s_addc_u32 s51, s51, 0
	s_add_u32 s63, s63, 0x100
	s_addc_u32 s64, s64, 0
	s_cmp_gt_u32 s65, 13
	s_cbranch_scc0 .LBB0_2498
	s_and_b64 vcc, exec, s[8:9]
	s_cbranch_vccz .LBB0_2501
	s_barrier
